# f32->bf16 bit-trick pairs replaced by v_cvt_pk_bf16_f32 (244 sites, same RNE rounding), wide-store WAR hazard re-padded
# baseline (speedup 1.0000x reference)
.LBB0_68:
	ds_read2_b32 v[104:105], v152 offset1:8
	ds_read2_b32 v[112:113], v152 offset0:66 offset1:74
	ds_read2_b32 v[114:115], v152 offset0:33 offset1:41
	ds_read2_b32 v[116:117], v152 offset0:99 offset1:107
	ds_read2_b32 v[118:119], v152 offset0:132 offset1:140
	ds_read2_b32 v[120:121], v152 offset0:198 offset1:206
	ds_read2_b32 v[122:123], v152 offset0:165 offset1:173
	ds_read2_b32 v[124:125], v152 offset0:231 offset1:239
	s_waitcnt lgkmcnt(7)
	v_mov_b32_e32 v108, v104
	s_waitcnt lgkmcnt(5)
	v_mov_b32_e32 v110, v114
	s_waitcnt lgkmcnt(4)
	v_mov_b32_e32 v111, v116
	s_waitcnt lgkmcnt(3)
	v_mov_b32_e32 v126, v118
	s_waitcnt lgkmcnt(2)
	v_mov_b32_e32 v127, v120
	v_mov_b32_e32 v109, v112
	v_pk_mul_f32 v[110:111], v[100:101], v[110:111]
	v_pk_mul_f32 v[126:127], v[98:99], v[126:127]
	s_waitcnt lgkmcnt(1)
	v_mov_b32_e32 v128, v122
	s_waitcnt lgkmcnt(0)
	v_mov_b32_e32 v129, v124
	v_pk_mul_f32 v[108:109], v[102:103], v[108:109]
	v_pk_mul_f32 v[128:129], v[106:107], v[128:129]
	v_mov_b32_e32 v114, v111
	v_mov_b32_e32 v120, v127
	v_mov_b32_e32 v116, v110
	v_mov_b32_e32 v110, v128
	v_mov_b32_e32 v104, v129
	v_mov_b32_e32 v118, v126
	v_mov_b32_e32 v111, v120
	v_mov_b32_e32 v112, v118
	v_cvt_pk_bf16_f32 v111, v111, v104
	v_or_b32_e32 v104, s55, v1
	s_ashr_i32 s5, s55, 31
	v_cvt_pk_bf16_f32 v110, v112, v110
	v_mul_lo_u32 v112, s31, v104
	s_mul_i32 s5, s30, s5
	v_mad_u64_u32 v[126:127], s[36:37], s30, v104, 0
	v_add3_u32 v127, v127, s5, v112
	v_lshl_add_u64 v[126:127], v[126:127], 1, s[28:29]
	s_lshl_b64 s[34:35], s[34:35], 1
	v_lshl_add_u64 v[126:127], v[126:127], 0, s[34:35]
	v_mov_b32_e32 v143, v139
	v_mov_b32_e32 v112, v105
	v_mov_b32_e32 v124, v123
	v_cvt_pk_bf16_f32 v109, v109, v114
	v_cvt_pk_bf16_f32 v108, v108, v116
	v_lshl_add_u64 v[126:127], v[126:127], 0, v[142:143]
	v_pk_mul_f32 v[104:105], v[102:103], v[112:113]
	v_mov_b32_e32 v116, v115
	v_pk_mul_f32 v[112:113], v[106:107], v[124:125]
	global_store_dwordx4 v[126:127], v[108:111], off
	v_mov_b32_e32 v120, v119
	s_nop 0
	v_pk_mul_f32 v[108:109], v[100:101], v[116:117]
	v_pk_mul_f32 v[110:111], v[98:99], v[120:121]
	v_cvt_pk_bf16_f32 v108, v104, v108
	v_or_b32_e32 v104, s55, v141
	v_cvt_pk_bf16_f32 v110, v110, v112
	v_cvt_pk_bf16_f32 v109, v105, v109
	v_mul_lo_u32 v112, s31, v104
	v_mad_u64_u32 v[104:105], s[36:37], s30, v104, 0
	v_add3_u32 v105, v105, s5, v112
	v_lshl_add_u64 v[104:105], v[104:105], 1, s[28:29]
	v_lshl_add_u64 v[104:105], v[104:105], 0, s[34:35]
	v_cvt_pk_bf16_f32 v111, v111, v113
	v_lshl_add_u64 v[104:105], v[104:105], 0, v[142:143]
	ds_read2_b32 v[112:113], v152 offset0:16 offset1:24
	ds_read2_b32 v[114:115], v152 offset0:82 offset1:90
	global_store_dwordx4 v[104:105], v[108:111], off
	ds_read2_b32 v[104:105], v152 offset0:49 offset1:57
	ds_read2_b32 v[116:117], v152 offset0:115 offset1:123
	ds_read2_b32 v[118:119], v152 offset0:148 offset1:156
	ds_read2_b32 v[120:121], v152 offset0:214 offset1:222
	ds_read2_b32 v[122:123], v152 offset0:181 offset1:189
	ds_read2_b32 v[124:125], v152 offset0:247 offset1:255
	s_waitcnt lgkmcnt(7)
	v_mov_b32_e32 v108, v112
	s_waitcnt lgkmcnt(5)
	v_mov_b32_e32 v110, v104
	s_waitcnt lgkmcnt(4)
	v_mov_b32_e32 v111, v116
	s_waitcnt lgkmcnt(3)
	v_mov_b32_e32 v126, v118
	s_waitcnt lgkmcnt(2)
	v_mov_b32_e32 v127, v120
	v_mov_b32_e32 v109, v114
	v_pk_mul_f32 v[110:111], v[100:101], v[110:111]
	v_pk_mul_f32 v[126:127], v[98:99], v[126:127]
	s_waitcnt lgkmcnt(1)
	v_mov_b32_e32 v128, v122
	s_waitcnt lgkmcnt(0)
	v_mov_b32_e32 v129, v124
	v_pk_mul_f32 v[108:109], v[102:103], v[108:109]
	v_pk_mul_f32 v[128:129], v[106:107], v[128:129]
	v_bfe_u32 v112, v128, 16, 1
	v_mov_b32_e32 v114, v111
	v_bfe_u32 v118, v126, 16, 1
	v_mov_b32_e32 v120, v127
	v_mov_b32_e32 v116, v110
	v_add3_u32 v110, v128, v112, s51
	v_mov_b32_e32 v104, v129
	v_add3_u32 v118, v126, v118, s51
	v_mov_b32_e32 v111, v120
	v_lshrrev_b32_e32 v112, 16, v118
	v_cvt_pk_bf16_f32 v111, v111, v104
	v_or_b32_e32 v104, s55, v146
	v_and_or_b32 v110, v110, s52, v112
	v_mul_lo_u32 v112, s31, v104
	v_mad_u64_u32 v[126:127], s[36:37], s30, v104, 0
	v_add3_u32 v127, v127, s5, v112
	v_lshl_add_u64 v[126:127], v[126:127], 1, s[28:29]
	v_cvt_pk_bf16_f32 v108, v108, v116
	v_lshl_add_u64 v[126:127], v[126:127], 0, s[34:35]
	v_mov_b32_e32 v116, v105
	v_mov_b32_e32 v124, v123
	v_cvt_pk_bf16_f32 v109, v109, v114
	v_lshl_add_u64 v[126:127], v[126:127], 0, v[142:143]
	v_mov_b32_e32 v114, v113
	v_pk_mul_f32 v[100:101], v[100:101], v[116:117]
	v_mov_b32_e32 v120, v119
	v_pk_mul_f32 v[104:105], v[106:107], v[124:125]
	global_store_dwordx4 v[126:127], v[108:111], off
	v_pk_mul_f32 v[102:103], v[102:103], v[114:115]
	v_pk_mul_f32 v[98:99], v[98:99], v[120:121]
	v_bfe_u32 v106, v105, 16, 1
	v_bfe_u32 v107, v104, 16, 1
	v_bfe_u32 v108, v101, 16, 1
	v_bfe_u32 v109, v100, 16, 1
	v_add3_u32 v109, v100, v109, s51
	v_add3_u32 v108, v101, v108, s51
	v_add3_u32 v100, v104, v107, s51
	v_add3_u32 v101, v105, v106, s51
	v_bfe_u32 v104, v102, 16, 1
	v_bfe_u32 v106, v98, 16, 1
	v_bfe_u32 v105, v103, 16, 1
	v_bfe_u32 v107, v99, 16, 1
	v_add3_u32 v98, v98, v106, s51
	v_add3_u32 v102, v102, v104, s51
	v_add3_u32 v99, v99, v107, s51
	v_add3_u32 v103, v103, v105, s51
	v_lshrrev_b32_e32 v102, 16, v102
	v_lshrrev_b32_e32 v98, 16, v98
	v_lshrrev_b32_e32 v103, 16, v103
	v_lshrrev_b32_e32 v99, 16, v99
	v_and_or_b32 v100, v100, s52, v98
	v_and_or_b32 v98, v109, s52, v102
	v_or_b32_e32 v102, s55, v147
	v_and_or_b32 v101, v101, s52, v99
	v_and_or_b32 v99, v108, s52, v103
	v_mul_lo_u32 v104, s31, v102
	v_mad_u64_u32 v[102:103], s[30:31], s30, v102, 0
	v_add3_u32 v103, v103, s5, v104
	v_lshl_add_u64 v[102:103], v[102:103], 1, s[28:29]
	v_lshl_add_u64 v[102:103], v[102:103], 0, s[34:35]
	v_lshl_add_u64 v[102:103], v[102:103], 0, v[142:143]
	global_store_dwordx4 v[102:103], v[98:101], off
	s_waitcnt lgkmcnt(0)
	s_add_i32 s53, s53, s2
	s_cmp_lt_i32 s53, 0xe750
	s_mov_b32 s90, s76
	s_cselect_b64 s[38:39], -1, 0

.LBB0_92:
	ds_read2_b32 v[136:137], v152 offset1:8
	ds_read2_b32 v[174:175], v152 offset0:66 offset1:74
	ds_read2_b32 v[176:177], v152 offset0:33 offset1:41
	ds_read2_b32 v[178:179], v152 offset0:99 offset1:107
	ds_read2_b32 v[180:181], v152 offset0:132 offset1:140
	ds_read2_b32 v[182:183], v152 offset0:198 offset1:206
	ds_read2_b32 v[184:185], v152 offset0:165 offset1:173
	ds_read2_b32 v[186:187], v152 offset0:231 offset1:239
	s_waitcnt lgkmcnt(7)
	v_mov_b32_e32 v170, v136
	s_waitcnt lgkmcnt(5)
	v_mov_b32_e32 v172, v176
	s_waitcnt lgkmcnt(4)
	v_mov_b32_e32 v173, v178
	s_waitcnt lgkmcnt(3)
	v_mov_b32_e32 v188, v180
	s_waitcnt lgkmcnt(2)
	v_mov_b32_e32 v189, v182
	v_mov_b32_e32 v171, v174
	v_pk_mul_f32 v[172:173], v[132:133], v[172:173]
	v_pk_mul_f32 v[188:189], v[130:131], v[188:189]
	s_waitcnt lgkmcnt(1)
	v_mov_b32_e32 v190, v184
	s_waitcnt lgkmcnt(0)
	v_mov_b32_e32 v191, v186
	v_pk_mul_f32 v[170:171], v[134:135], v[170:171]
	v_pk_mul_f32 v[190:191], v[144:145], v[190:191]
	v_mov_b32_e32 v169, v173
	v_mov_b32_e32 v178, v189
	v_mov_b32_e32 v136, v191
	v_mov_b32_e32 v173, v178
	v_mov_b32_e32 v174, v172
	v_mov_b32_e32 v176, v188
	v_cvt_pk_bf16_f32 v173, v173, v136
	v_add_u32_e32 v136, s3, v1
	v_mov_b32_e32 v143, v190
	v_mov_b32_e32 v172, v176
	v_mad_u64_u32 v[188:189], s[38:39], v136, s54, 0
	v_cvt_pk_bf16_f32 v172, v172, v143
	v_ashrrev_i32_e32 v143, 31, v136
	v_mov_b32_e32 v136, v189
	v_mad_u64_u32 v[190:191], s[38:39], v143, s54, v[136:137]
	v_mov_b32_e32 v189, v190
	v_lshl_add_u64 v[188:189], v[188:189], 1, s[10:11]
	s_lshl_b64 s[38:39], s[4:5], 1
	v_cvt_pk_bf16_f32 v170, v170, v174
	v_lshl_add_u64 v[188:189], v[188:189], 0, s[38:39]
	v_mov_b32_e32 v143, v139
	v_mov_b32_e32 v174, v137
	v_mov_b32_e32 v186, v185
	v_cvt_pk_bf16_f32 v171, v171, v169
	v_lshl_add_u64 v[188:189], v[188:189], 0, v[142:143]
	v_pk_mul_f32 v[136:137], v[134:135], v[174:175]
	v_mov_b32_e32 v178, v177
	v_pk_mul_f32 v[174:175], v[144:145], v[186:187]
	global_store_dwordx4 v[188:189], v[170:173], off
	v_mov_b32_e32 v182, v181
	s_nop 0
	v_pk_mul_f32 v[170:171], v[132:133], v[178:179]
	v_pk_mul_f32 v[172:173], v[130:131], v[182:183]
	v_bfe_u32 v178, v170, 16, 1
	v_mov_b32_e32 v169, v175
	v_bfe_u32 v175, v136, 16, 1
	v_add3_u32 v170, v170, v178, s51
	v_add3_u32 v136, v136, v175, s51
	v_lshrrev_b32_e32 v136, 16, v136
	v_and_or_b32 v170, v170, s52, v136
	v_add_u32_e32 v136, s3, v141
	v_cvt_pk_bf16_f32 v173, v173, v169
	v_cvt_pk_bf16_f32 v171, v137, v171
	v_ashrrev_i32_e32 v169, 31, v136
	v_mad_u64_u32 v[136:137], s[40:41], v136, s54, 0
	v_cvt_pk_bf16_f32 v172, v172, v174
	v_mov_b32_e32 v174, v137
	v_mad_u64_u32 v[174:175], s[40:41], v169, s54, v[174:175]
	v_mov_b32_e32 v137, v174
	v_lshl_add_u64 v[136:137], v[136:137], 1, s[10:11]
	v_lshl_add_u64 v[136:137], v[136:137], 0, s[38:39]
	v_lshl_add_u64 v[136:137], v[136:137], 0, v[142:143]
	ds_read2_b32 v[174:175], v152 offset0:16 offset1:24
	ds_read2_b32 v[176:177], v152 offset0:82 offset1:90
	global_store_dwordx4 v[136:137], v[170:173], off
	ds_read2_b32 v[136:137], v152 offset0:49 offset1:57
	ds_read2_b32 v[178:179], v152 offset0:115 offset1:123
	ds_read2_b32 v[180:181], v152 offset0:148 offset1:156
	ds_read2_b32 v[182:183], v152 offset0:214 offset1:222
	ds_read2_b32 v[184:185], v152 offset0:181 offset1:189
	ds_read2_b32 v[186:187], v152 offset0:247 offset1:255
	s_waitcnt lgkmcnt(7)
	v_mov_b32_e32 v170, v174
	s_waitcnt lgkmcnt(5)
	v_mov_b32_e32 v172, v136
	s_waitcnt lgkmcnt(4)
	v_mov_b32_e32 v173, v178
	s_waitcnt lgkmcnt(3)
	v_mov_b32_e32 v188, v180
	s_waitcnt lgkmcnt(2)
	v_mov_b32_e32 v189, v182
	v_mov_b32_e32 v171, v176
	v_pk_mul_f32 v[172:173], v[132:133], v[172:173]
	v_pk_mul_f32 v[188:189], v[130:131], v[188:189]
	s_waitcnt lgkmcnt(1)
	v_mov_b32_e32 v190, v184
	s_waitcnt lgkmcnt(0)
	v_mov_b32_e32 v191, v186
	v_pk_mul_f32 v[170:171], v[134:135], v[170:171]
	v_pk_mul_f32 v[190:191], v[144:145], v[190:191]
	v_bfe_u32 v174, v173, 16, 1
	v_bfe_u32 v180, v189, 16, 1
	v_bfe_u32 v136, v191, 16, 1
	v_add3_u32 v174, v173, v174, s51
	v_bfe_u32 v173, v171, 16, 1
	v_add3_u32 v180, v189, v180, s51
	v_add3_u32 v136, v191, v136, s51
	v_add3_u32 v171, v171, v173, s51
	v_lshrrev_b32_e32 v173, 16, v180
	v_mov_b32_e32 v176, v172
	v_mov_b32_e32 v178, v188
	v_and_or_b32 v173, v136, s52, v173
	v_add_u32_e32 v136, s3, v146
	v_mov_b32_e32 v169, v190
	v_mov_b32_e32 v172, v178
	v_mad_u64_u32 v[188:189], s[40:41], v136, s54, 0
	v_cvt_pk_bf16_f32 v172, v172, v169
	v_ashrrev_i32_e32 v169, 31, v136
	v_mov_b32_e32 v136, v189
	v_mad_u64_u32 v[190:191], s[40:41], v169, s54, v[136:137]
	v_mov_b32_e32 v189, v190
	v_lshl_add_u64 v[188:189], v[188:189], 1, s[10:11]
	v_lshrrev_b32_e32 v171, 16, v171
	v_lshl_add_u64 v[188:189], v[188:189], 0, s[38:39]
	v_mov_b32_e32 v178, v137
	v_mov_b32_e32 v186, v185
	v_and_or_b32 v171, v174, s52, v171
	v_cvt_pk_bf16_f32 v170, v170, v176
	v_lshl_add_u64 v[188:189], v[188:189], 0, v[142:143]
	v_mov_b32_e32 v176, v175
	v_pk_mul_f32 v[132:133], v[132:133], v[178:179]
	v_mov_b32_e32 v182, v181
	v_pk_mul_f32 v[136:137], v[144:145], v[186:187]
	global_store_dwordx4 v[188:189], v[170:173], off
	v_pk_mul_f32 v[134:135], v[134:135], v[176:177]
	v_pk_mul_f32 v[130:131], v[130:131], v[182:183]
	v_bfe_u32 v144, v137, 16, 1
	v_bfe_u32 v145, v136, 16, 1
	v_bfe_u32 v169, v133, 16, 1
	v_bfe_u32 v170, v132, 16, 1
	v_add3_u32 v170, v132, v170, s51
	v_add3_u32 v169, v133, v169, s51
	v_add3_u32 v132, v136, v145, s51
	v_add3_u32 v133, v137, v144, s51
	v_bfe_u32 v136, v134, 16, 1
	v_bfe_u32 v144, v130, 16, 1
	v_bfe_u32 v137, v135, 16, 1
	v_bfe_u32 v145, v131, 16, 1
	v_add3_u32 v130, v130, v144, s51
	v_add3_u32 v134, v134, v136, s51
	v_add3_u32 v131, v131, v145, s51
	v_add3_u32 v135, v135, v137, s51
	v_lshrrev_b32_e32 v134, 16, v134
	v_lshrrev_b32_e32 v130, 16, v130
	v_lshrrev_b32_e32 v135, 16, v135
	v_lshrrev_b32_e32 v131, 16, v131
	v_and_or_b32 v132, v132, s52, v130
	v_and_or_b32 v130, v170, s52, v134
	v_add_u32_e32 v134, s3, v147
	v_and_or_b32 v133, v133, s52, v131
	v_and_or_b32 v131, v169, s52, v135
	v_ashrrev_i32_e32 v137, 31, v134
	v_mad_u64_u32 v[134:135], s[40:41], v134, s54, 0
	v_mov_b32_e32 v136, v135
	v_mad_u64_u32 v[136:137], s[40:41], v137, s54, v[136:137]
	v_mov_b32_e32 v135, v136
	v_lshl_add_u64 v[134:135], v[134:135], 1, s[10:11]
	v_lshl_add_u64 v[134:135], v[134:135], 0, s[38:39]
	v_lshl_add_u64 v[134:135], v[134:135], 0, v[142:143]
	global_store_dwordx4 v[134:135], v[130:133], off
	s_waitcnt lgkmcnt(0)
	s_add_i32 s53, s53, s2
	s_mov_b32 s90, s76
	s_cmp_lt_i32 s53, 0xe750
	s_mov_b64 s[38:39], 0
	s_cbranch_scc0 .LBB0_69
	s_add_i32 s3, s53, s45
	s_cmp_lt_i32 s3, 0xe750
	s_cselect_b32 s5, s3, s53
	s_cmp_lt_i32 s5, 0x8080
	s_cbranch_scc1 .LBB0_107
	s_cmpk_lt_u32 s5, 0xa080
	s_cbranch_scc1 .LBB0_108
	s_cmp_lt_u32 s5, 0x14c80
	s_cselect_b64 s[10:11], -1, 0
	s_add_i32 s3, s5, 0xfffe1580
	s_cmpk_lt_u32 s3, 0xac00
	s_cselect_b64 s[26:27], -1, 0
	s_or_b64 s[10:11], s[10:11], s[26:27]
	s_mov_b64 s[40:41], -1
	s_and_b64 vcc, exec, s[10:11]
	s_cbranch_vccnz .LBB0_104
	s_add_i32 s3, s5, 0xfffd6980
	s_cmp_lt_u32 s3, 0xffff0c00
	s_mov_b64 s[94:95], -1
	s_cbranch_scc1 .LBB0_101
	s_cmp_lt_u32 s5, 0x1ca80
	s_mov_b64 s[10:11], -1
	s_cbranch_scc1 .LBB0_99
	s_add_i32 s4, s5, 0xfffe3580
	v_readlane_b32 s56, v250, 18
	s_lshl_b32 s3, s5, 5
	s_lshr_b32 s4, s4, 1
	v_readlane_b32 s64, v250, 26
	v_readlane_b32 s65, v250, 27
	s_and_b32 s3, s3, 0xfe0
	s_and_b32 s4, s4, 0x7fffffc0
	s_mov_b64 s[10:11], 0
	s_mov_b64 s[38:39], s[64:65]
	v_readlane_b32 s57, v250, 19
	v_readlane_b32 s58, v250, 20
	v_readlane_b32 s59, v250, 21
	v_readlane_b32 s60, v250, 22
	v_readlane_b32 s61, v250, 23
	v_readlane_b32 s62, v250, 24
	v_readlane_b32 s63, v250, 25
	v_readlane_b32 s66, v250, 28
	v_readlane_b32 s67, v250, 29
	v_readlane_b32 s68, v250, 30
	v_readlane_b32 s69, v250, 31
	v_readlane_b32 s70, v250, 32
	v_readlane_b32 s71, v250, 33

.LBB0_115:
	ds_read2_b32 v[136:137], v152 offset1:8
	ds_read2_b32 v[174:175], v152 offset0:66 offset1:74
	ds_read2_b32 v[176:177], v152 offset0:33 offset1:41
	ds_read2_b32 v[178:179], v152 offset0:99 offset1:107
	ds_read2_b32 v[180:181], v152 offset0:132 offset1:140
	ds_read2_b32 v[182:183], v152 offset0:198 offset1:206
	ds_read2_b32 v[184:185], v152 offset0:165 offset1:173
	ds_read2_b32 v[186:187], v152 offset0:231 offset1:239
	s_waitcnt lgkmcnt(7)
	v_mov_b32_e32 v170, v136
	s_waitcnt lgkmcnt(5)
	v_mov_b32_e32 v172, v176
	s_waitcnt lgkmcnt(4)
	v_mov_b32_e32 v173, v178
	s_waitcnt lgkmcnt(3)
	v_mov_b32_e32 v188, v180
	s_waitcnt lgkmcnt(2)
	v_mov_b32_e32 v189, v182
	v_mov_b32_e32 v171, v174
	v_pk_mul_f32 v[172:173], v[132:133], v[172:173]
	v_pk_mul_f32 v[188:189], v[130:131], v[188:189]
	s_waitcnt lgkmcnt(1)
	v_mov_b32_e32 v190, v184
	s_waitcnt lgkmcnt(0)
	v_mov_b32_e32 v191, v186
	v_pk_mul_f32 v[170:171], v[134:135], v[170:171]
	v_pk_mul_f32 v[190:191], v[144:145], v[190:191]
	v_mov_b32_e32 v169, v173
	v_mov_b32_e32 v178, v189
	v_mov_b32_e32 v136, v191
	v_mov_b32_e32 v173, v178
	v_mov_b32_e32 v174, v172
	v_mov_b32_e32 v176, v188
	v_cvt_pk_bf16_f32 v173, v173, v136
	v_add_u32_e32 v136, s33, v1
	v_mov_b32_e32 v143, v190
	v_mov_b32_e32 v172, v176
	v_mad_u64_u32 v[188:189], s[38:39], v136, s42, 0
	v_cvt_pk_bf16_f32 v172, v172, v143
	v_ashrrev_i32_e32 v143, 31, v136
	v_mov_b32_e32 v136, v189
	v_mad_u64_u32 v[190:191], s[38:39], v143, s42, v[136:137]
	v_mov_b32_e32 v189, v190
	v_lshl_add_u64 v[188:189], v[188:189], 1, s[16:17]
	s_lshl_b64 s[38:39], s[12:13], 1
	v_cvt_pk_bf16_f32 v170, v170, v174
	v_lshl_add_u64 v[188:189], v[188:189], 0, s[38:39]
	v_mov_b32_e32 v143, v139
	v_mov_b32_e32 v174, v137
	v_mov_b32_e32 v186, v185
	v_cvt_pk_bf16_f32 v171, v171, v169
	v_lshl_add_u64 v[188:189], v[188:189], 0, v[142:143]
	v_pk_mul_f32 v[136:137], v[134:135], v[174:175]
	v_mov_b32_e32 v178, v177
	v_pk_mul_f32 v[174:175], v[144:145], v[186:187]
	global_store_dwordx4 v[188:189], v[170:173], off
	v_mov_b32_e32 v182, v181
	s_nop 0
	v_pk_mul_f32 v[170:171], v[132:133], v[178:179]
	v_pk_mul_f32 v[172:173], v[130:131], v[182:183]
	v_bfe_u32 v178, v170, 16, 1
	v_mov_b32_e32 v169, v175
	v_bfe_u32 v175, v136, 16, 1
	v_add3_u32 v170, v170, v178, s51
	v_add3_u32 v136, v136, v175, s51
	v_lshrrev_b32_e32 v136, 16, v136
	v_and_or_b32 v170, v170, s52, v136
	v_add_u32_e32 v136, s33, v141
	v_cvt_pk_bf16_f32 v173, v173, v169
	v_cvt_pk_bf16_f32 v171, v137, v171
	v_ashrrev_i32_e32 v169, 31, v136
	v_mad_u64_u32 v[136:137], s[40:41], v136, s42, 0
	v_cvt_pk_bf16_f32 v172, v172, v174
	v_mov_b32_e32 v174, v137
	v_mad_u64_u32 v[174:175], s[40:41], v169, s42, v[174:175]
	v_mov_b32_e32 v137, v174
	v_lshl_add_u64 v[136:137], v[136:137], 1, s[16:17]
	v_lshl_add_u64 v[136:137], v[136:137], 0, s[38:39]
	v_lshl_add_u64 v[136:137], v[136:137], 0, v[142:143]
	ds_read2_b32 v[174:175], v152 offset0:16 offset1:24
	ds_read2_b32 v[176:177], v152 offset0:82 offset1:90
	global_store_dwordx4 v[136:137], v[170:173], off
	ds_read2_b32 v[136:137], v152 offset0:49 offset1:57
	ds_read2_b32 v[178:179], v152 offset0:115 offset1:123
	ds_read2_b32 v[180:181], v152 offset0:148 offset1:156
	ds_read2_b32 v[182:183], v152 offset0:214 offset1:222
	ds_read2_b32 v[184:185], v152 offset0:181 offset1:189
	ds_read2_b32 v[186:187], v152 offset0:247 offset1:255
	s_waitcnt lgkmcnt(7)
	v_mov_b32_e32 v170, v174
	s_waitcnt lgkmcnt(5)
	v_mov_b32_e32 v172, v136
	s_waitcnt lgkmcnt(4)
	v_mov_b32_e32 v173, v178
	s_waitcnt lgkmcnt(3)
	v_mov_b32_e32 v188, v180
	s_waitcnt lgkmcnt(2)
	v_mov_b32_e32 v189, v182
	v_mov_b32_e32 v171, v176
	v_pk_mul_f32 v[172:173], v[132:133], v[172:173]
	v_pk_mul_f32 v[188:189], v[130:131], v[188:189]
	s_waitcnt lgkmcnt(1)
	v_mov_b32_e32 v190, v184
	s_waitcnt lgkmcnt(0)
	v_mov_b32_e32 v191, v186
	v_pk_mul_f32 v[170:171], v[134:135], v[170:171]
	v_pk_mul_f32 v[190:191], v[144:145], v[190:191]
	v_bfe_u32 v174, v173, 16, 1
	v_bfe_u32 v180, v189, 16, 1
	v_bfe_u32 v136, v191, 16, 1
	v_add3_u32 v174, v173, v174, s51
	v_bfe_u32 v173, v171, 16, 1
	v_add3_u32 v180, v189, v180, s51
	v_add3_u32 v136, v191, v136, s51
	v_add3_u32 v171, v171, v173, s51
	v_lshrrev_b32_e32 v173, 16, v180
	v_mov_b32_e32 v176, v172
	v_mov_b32_e32 v178, v188
	v_and_or_b32 v173, v136, s52, v173
	v_add_u32_e32 v136, s33, v146
	v_mov_b32_e32 v169, v190
	v_mov_b32_e32 v172, v178
	v_mad_u64_u32 v[188:189], s[40:41], v136, s42, 0
	v_cvt_pk_bf16_f32 v172, v172, v169
	v_ashrrev_i32_e32 v169, 31, v136
	v_mov_b32_e32 v136, v189
	v_mad_u64_u32 v[190:191], s[40:41], v169, s42, v[136:137]
	v_mov_b32_e32 v189, v190
	v_lshl_add_u64 v[188:189], v[188:189], 1, s[16:17]
	v_lshrrev_b32_e32 v171, 16, v171
	v_lshl_add_u64 v[188:189], v[188:189], 0, s[38:39]
	v_mov_b32_e32 v178, v137
	v_mov_b32_e32 v186, v185
	v_and_or_b32 v171, v174, s52, v171
	v_cvt_pk_bf16_f32 v170, v170, v176
	v_lshl_add_u64 v[188:189], v[188:189], 0, v[142:143]
	v_mov_b32_e32 v176, v175
	v_pk_mul_f32 v[132:133], v[132:133], v[178:179]
	v_mov_b32_e32 v182, v181
	v_pk_mul_f32 v[136:137], v[144:145], v[186:187]
	global_store_dwordx4 v[188:189], v[170:173], off
	v_pk_mul_f32 v[134:135], v[134:135], v[176:177]
	v_pk_mul_f32 v[130:131], v[130:131], v[182:183]
	v_bfe_u32 v144, v137, 16, 1
	v_bfe_u32 v145, v136, 16, 1
	v_bfe_u32 v169, v133, 16, 1
	v_bfe_u32 v170, v132, 16, 1
	v_add3_u32 v170, v132, v170, s51
	v_add3_u32 v169, v133, v169, s51
	v_add3_u32 v132, v136, v145, s51
	v_add3_u32 v133, v137, v144, s51
	v_bfe_u32 v136, v134, 16, 1
	v_bfe_u32 v144, v130, 16, 1
	v_bfe_u32 v137, v135, 16, 1
	v_bfe_u32 v145, v131, 16, 1
	v_add3_u32 v130, v130, v144, s51
	v_add3_u32 v134, v134, v136, s51
	v_add3_u32 v131, v131, v145, s51
	v_add3_u32 v135, v135, v137, s51
	v_lshrrev_b32_e32 v134, 16, v134
	v_lshrrev_b32_e32 v130, 16, v130
	v_lshrrev_b32_e32 v135, 16, v135
	v_lshrrev_b32_e32 v131, 16, v131
	v_and_or_b32 v132, v132, s52, v130
	v_and_or_b32 v130, v170, s52, v134
	v_add_u32_e32 v134, s33, v147
	v_and_or_b32 v133, v133, s52, v131
	v_and_or_b32 v131, v169, s52, v135
	v_ashrrev_i32_e32 v137, 31, v134
	v_mad_u64_u32 v[134:135], s[40:41], v134, s42, 0
	v_mov_b32_e32 v136, v135
	v_mad_u64_u32 v[136:137], s[40:41], v137, s42, v[136:137]
	v_mov_b32_e32 v135, v136
	v_lshl_add_u64 v[134:135], v[134:135], 1, s[16:17]
	v_lshl_add_u64 v[134:135], v[134:135], 0, s[38:39]
	v_lshl_add_u64 v[134:135], v[134:135], 0, v[142:143]
	global_store_dwordx4 v[134:135], v[130:133], off
	s_waitcnt lgkmcnt(0)
	s_add_i32 s53, s53, s2
	s_mov_b32 s90, s76
	s_cmp_gt_i32 s53, 0xe74f
	s_mov_b64 s[38:39], 0
	s_cbranch_scc1 .LBB0_69
	s_add_i32 s5, s53, s45
	s_cmp_lt_i32 s5, 0xe750
	s_cselect_b32 s5, s5, s53
	s_cmp_lt_i32 s5, 0x8080
	s_cbranch_scc1 .LBB0_130
	s_cmpk_lt_u32 s5, 0xa080
	s_cbranch_scc1 .LBB0_131
	s_cmp_lt_u32 s5, 0x14c80
	s_cselect_b64 s[12:13], -1, 0
	s_add_i32 s14, s5, 0xfffe1580
	s_cmpk_lt_u32 s14, 0xac00
	s_cselect_b64 s[14:15], -1, 0
	s_or_b64 s[12:13], s[12:13], s[14:15]
	s_mov_b64 s[40:41], -1
	s_and_b64 vcc, exec, s[12:13]
	s_cbranch_vccnz .LBB0_127
	s_add_i32 s12, s5, 0xfffd6980
	s_cmp_lt_u32 s12, 0xffff0c00
	s_mov_b64 s[94:95], -1
	s_cbranch_scc1 .LBB0_124
	s_cmp_lt_u32 s5, 0x1ca80
	s_mov_b64 s[14:15], -1
	s_cbranch_scc1 .LBB0_122
	s_add_i32 s12, s5, 0xfffe3580
	v_readlane_b32 s56, v250, 18
	s_lshl_b32 s13, s5, 5
	s_lshr_b32 s12, s12, 1
	v_readlane_b32 s64, v250, 26
	v_readlane_b32 s65, v250, 27
	s_and_b32 s33, s13, 0xfe0
	s_and_b32 s12, s12, 0x7fffffc0
	s_mov_b64 s[14:15], 0
	s_mov_b64 s[38:39], s[64:65]
	v_readlane_b32 s57, v250, 19
	v_readlane_b32 s58, v250, 20
	v_readlane_b32 s59, v250, 21
	v_readlane_b32 s60, v250, 22
	v_readlane_b32 s61, v250, 23
	v_readlane_b32 s62, v250, 24
	v_readlane_b32 s63, v250, 25
	v_readlane_b32 s66, v250, 28
	v_readlane_b32 s67, v250, 29
	v_readlane_b32 s68, v250, 30
	v_readlane_b32 s69, v250, 31
	v_readlane_b32 s70, v250, 32
	v_readlane_b32 s71, v250, 33

.LBB0_138:
	ds_read2_b32 v[136:137], v152 offset1:8
	ds_read2_b32 v[174:175], v152 offset0:66 offset1:74
	ds_read2_b32 v[176:177], v152 offset0:33 offset1:41
	ds_read2_b32 v[178:179], v152 offset0:99 offset1:107
	ds_read2_b32 v[180:181], v152 offset0:132 offset1:140
	ds_read2_b32 v[182:183], v152 offset0:198 offset1:206
	ds_read2_b32 v[184:185], v152 offset0:165 offset1:173
	ds_read2_b32 v[186:187], v152 offset0:231 offset1:239
	s_waitcnt lgkmcnt(7)
	v_mov_b32_e32 v170, v136
	s_waitcnt lgkmcnt(5)
	v_mov_b32_e32 v172, v176
	s_waitcnt lgkmcnt(4)
	v_mov_b32_e32 v173, v178
	s_waitcnt lgkmcnt(3)
	v_mov_b32_e32 v188, v180
	s_waitcnt lgkmcnt(2)
	v_mov_b32_e32 v189, v182
	v_mov_b32_e32 v171, v174
	v_pk_mul_f32 v[172:173], v[132:133], v[172:173]
	v_pk_mul_f32 v[188:189], v[130:131], v[188:189]
	s_waitcnt lgkmcnt(1)
	v_mov_b32_e32 v190, v184
	s_waitcnt lgkmcnt(0)
	v_mov_b32_e32 v191, v186
	v_pk_mul_f32 v[170:171], v[134:135], v[170:171]
	v_pk_mul_f32 v[190:191], v[144:145], v[190:191]
	v_mov_b32_e32 v169, v173
	v_mov_b32_e32 v178, v189
	v_mov_b32_e32 v136, v191
	v_mov_b32_e32 v173, v178
	v_mov_b32_e32 v174, v172
	v_mov_b32_e32 v176, v188
	v_cvt_pk_bf16_f32 v173, v173, v136
	v_add_u32_e32 v136, s43, v1
	v_mov_b32_e32 v143, v190
	v_mov_b32_e32 v172, v176
	v_mad_u64_u32 v[188:189], s[38:39], v136, s44, 0
	v_cvt_pk_bf16_f32 v172, v172, v143
	v_ashrrev_i32_e32 v143, 31, v136
	v_mov_b32_e32 v136, v189
	v_mad_u64_u32 v[190:191], s[38:39], v143, s44, v[136:137]
	v_mov_b32_e32 v189, v190
	v_lshl_add_u64 v[188:189], v[188:189], 1, s[22:23]
	s_lshl_b64 s[38:39], s[18:19], 1
	v_cvt_pk_bf16_f32 v170, v170, v174
	v_lshl_add_u64 v[188:189], v[188:189], 0, s[38:39]
	v_mov_b32_e32 v143, v139
	v_mov_b32_e32 v174, v137
	v_mov_b32_e32 v186, v185
	v_cvt_pk_bf16_f32 v171, v171, v169
	v_lshl_add_u64 v[188:189], v[188:189], 0, v[142:143]
	v_pk_mul_f32 v[136:137], v[134:135], v[174:175]
	v_mov_b32_e32 v178, v177
	v_pk_mul_f32 v[174:175], v[144:145], v[186:187]
	global_store_dwordx4 v[188:189], v[170:173], off
	v_mov_b32_e32 v182, v181
	s_nop 0
	v_pk_mul_f32 v[170:171], v[132:133], v[178:179]
	v_pk_mul_f32 v[172:173], v[130:131], v[182:183]
	v_bfe_u32 v178, v170, 16, 1
	v_mov_b32_e32 v169, v175
	v_bfe_u32 v175, v136, 16, 1
	v_add3_u32 v170, v170, v178, s51
	v_add3_u32 v136, v136, v175, s51
	v_lshrrev_b32_e32 v136, 16, v136
	v_and_or_b32 v170, v170, s52, v136
	v_add_u32_e32 v136, s43, v141
	v_cvt_pk_bf16_f32 v173, v173, v169
	v_cvt_pk_bf16_f32 v171, v137, v171
	v_ashrrev_i32_e32 v169, 31, v136
	v_mad_u64_u32 v[136:137], s[40:41], v136, s44, 0
	v_cvt_pk_bf16_f32 v172, v172, v174
	v_mov_b32_e32 v174, v137
	v_mad_u64_u32 v[174:175], s[40:41], v169, s44, v[174:175]
	v_mov_b32_e32 v137, v174
	v_lshl_add_u64 v[136:137], v[136:137], 1, s[22:23]
	v_lshl_add_u64 v[136:137], v[136:137], 0, s[38:39]
	v_lshl_add_u64 v[136:137], v[136:137], 0, v[142:143]
	ds_read2_b32 v[174:175], v152 offset0:16 offset1:24
	ds_read2_b32 v[176:177], v152 offset0:82 offset1:90
	global_store_dwordx4 v[136:137], v[170:173], off
	ds_read2_b32 v[136:137], v152 offset0:49 offset1:57
	ds_read2_b32 v[178:179], v152 offset0:115 offset1:123
	ds_read2_b32 v[180:181], v152 offset0:148 offset1:156
	ds_read2_b32 v[182:183], v152 offset0:214 offset1:222
	ds_read2_b32 v[184:185], v152 offset0:181 offset1:189
	ds_read2_b32 v[186:187], v152 offset0:247 offset1:255
	s_waitcnt lgkmcnt(7)
	v_mov_b32_e32 v170, v174
	s_waitcnt lgkmcnt(5)
	v_mov_b32_e32 v172, v136
	s_waitcnt lgkmcnt(4)
	v_mov_b32_e32 v173, v178
	s_waitcnt lgkmcnt(3)
	v_mov_b32_e32 v188, v180
	s_waitcnt lgkmcnt(2)
	v_mov_b32_e32 v189, v182
	v_mov_b32_e32 v171, v176
	v_pk_mul_f32 v[172:173], v[132:133], v[172:173]
	v_pk_mul_f32 v[188:189], v[130:131], v[188:189]
	s_waitcnt lgkmcnt(1)
	v_mov_b32_e32 v190, v184
	s_waitcnt lgkmcnt(0)
	v_mov_b32_e32 v191, v186
	v_pk_mul_f32 v[170:171], v[134:135], v[170:171]
	v_pk_mul_f32 v[190:191], v[144:145], v[190:191]
	v_bfe_u32 v174, v173, 16, 1
	v_bfe_u32 v180, v189, 16, 1
	v_bfe_u32 v136, v191, 16, 1
	v_add3_u32 v174, v173, v174, s51
	v_bfe_u32 v173, v171, 16, 1
	v_add3_u32 v180, v189, v180, s51
	v_add3_u32 v136, v191, v136, s51
	v_add3_u32 v171, v171, v173, s51
	v_lshrrev_b32_e32 v173, 16, v180
	v_mov_b32_e32 v176, v172
	v_mov_b32_e32 v178, v188
	v_and_or_b32 v173, v136, s52, v173
	v_add_u32_e32 v136, s43, v146
	v_mov_b32_e32 v169, v190
	v_mov_b32_e32 v172, v178
	v_mad_u64_u32 v[188:189], s[40:41], v136, s44, 0
	v_cvt_pk_bf16_f32 v172, v172, v169
	v_ashrrev_i32_e32 v169, 31, v136
	v_mov_b32_e32 v136, v189
	v_mad_u64_u32 v[190:191], s[40:41], v169, s44, v[136:137]
	v_mov_b32_e32 v189, v190
	v_lshl_add_u64 v[188:189], v[188:189], 1, s[22:23]
	v_lshrrev_b32_e32 v171, 16, v171
	v_lshl_add_u64 v[188:189], v[188:189], 0, s[38:39]
	v_mov_b32_e32 v178, v137
	v_mov_b32_e32 v186, v185
	v_and_or_b32 v171, v174, s52, v171
	v_cvt_pk_bf16_f32 v170, v170, v176
	v_lshl_add_u64 v[188:189], v[188:189], 0, v[142:143]
	v_mov_b32_e32 v176, v175
	v_pk_mul_f32 v[132:133], v[132:133], v[178:179]
	v_mov_b32_e32 v182, v181
	v_pk_mul_f32 v[136:137], v[144:145], v[186:187]
	global_store_dwordx4 v[188:189], v[170:173], off
	v_pk_mul_f32 v[134:135], v[134:135], v[176:177]
	v_pk_mul_f32 v[130:131], v[130:131], v[182:183]
	v_bfe_u32 v144, v137, 16, 1
	v_bfe_u32 v145, v136, 16, 1
	v_bfe_u32 v169, v133, 16, 1
	v_bfe_u32 v170, v132, 16, 1
	v_add3_u32 v170, v132, v170, s51
	v_add3_u32 v169, v133, v169, s51
	v_add3_u32 v132, v136, v145, s51
	v_add3_u32 v133, v137, v144, s51
	v_bfe_u32 v136, v134, 16, 1
	v_bfe_u32 v144, v130, 16, 1
	v_bfe_u32 v137, v135, 16, 1
	v_bfe_u32 v145, v131, 16, 1
	v_add3_u32 v130, v130, v144, s51
	v_add3_u32 v134, v134, v136, s51
	v_add3_u32 v131, v131, v145, s51
	v_add3_u32 v135, v135, v137, s51
	v_lshrrev_b32_e32 v134, 16, v134
	v_lshrrev_b32_e32 v130, 16, v130
	v_lshrrev_b32_e32 v135, 16, v135
	v_lshrrev_b32_e32 v131, 16, v131
	v_and_or_b32 v132, v132, s52, v130
	v_and_or_b32 v130, v170, s52, v134
	v_add_u32_e32 v134, s43, v147
	v_and_or_b32 v133, v133, s52, v131
	v_and_or_b32 v131, v169, s52, v135
	v_ashrrev_i32_e32 v137, 31, v134
	v_mad_u64_u32 v[134:135], s[40:41], v134, s44, 0
	v_mov_b32_e32 v136, v135
	v_mad_u64_u32 v[136:137], s[40:41], v137, s44, v[136:137]
	v_mov_b32_e32 v135, v136
	v_lshl_add_u64 v[134:135], v[134:135], 1, s[22:23]
	v_lshl_add_u64 v[134:135], v[134:135], 0, s[38:39]
	v_lshl_add_u64 v[134:135], v[134:135], 0, v[142:143]
	global_store_dwordx4 v[134:135], v[130:133], off
	s_waitcnt lgkmcnt(0)
	s_add_i32 s53, s53, s2
	s_mov_b32 s90, s76
	s_cmp_gt_i32 s53, 0xe74f
	s_mov_b64 s[38:39], 0
	s_cbranch_scc1 .LBB0_69
	s_add_i32 s5, s53, s45
	s_cmp_lt_i32 s5, 0xe750
	s_cselect_b32 s5, s5, s53
	s_cmp_lt_i32 s5, 0x8080
	s_cbranch_scc1 .LBB0_153
	s_cmpk_lt_u32 s5, 0xa080
	s_cbranch_scc1 .LBB0_154
	s_cmp_lt_u32 s5, 0x14c80
	s_cselect_b64 s[18:19], -1, 0
	s_add_i32 s13, s5, 0xfffe1580
	s_cmpk_lt_u32 s13, 0xac00
	s_cselect_b64 s[20:21], -1, 0
	s_or_b64 s[18:19], s[18:19], s[20:21]
	s_mov_b64 s[40:41], -1
	s_and_b64 vcc, exec, s[18:19]
	s_cbranch_vccnz .LBB0_150
	s_add_i32 s13, s5, 0xfffd6980
	s_cmp_lt_u32 s13, 0xffff0c00
	s_mov_b64 s[94:95], -1
	s_cbranch_scc1 .LBB0_147
	s_cmp_lt_u32 s5, 0x1ca80
	s_mov_b64 s[20:21], -1
	s_cbranch_scc1 .LBB0_145
	s_add_i32 s13, s5, 0xfffe3580
	v_readlane_b32 s56, v250, 18
	s_lshl_b32 s18, s5, 5
	s_lshr_b32 s13, s13, 1
	v_readlane_b32 s64, v250, 26
	v_readlane_b32 s65, v250, 27
	s_and_b32 s43, s18, 0xfe0
	s_and_b32 s18, s13, 0x7fffffc0
	s_mov_b64 s[20:21], 0
	s_mov_b64 s[38:39], s[64:65]
	v_readlane_b32 s57, v250, 19
	v_readlane_b32 s58, v250, 20
	v_readlane_b32 s59, v250, 21
	v_readlane_b32 s60, v250, 22
	v_readlane_b32 s61, v250, 23
	v_readlane_b32 s62, v250, 24
	v_readlane_b32 s63, v250, 25
	v_readlane_b32 s66, v250, 28
	v_readlane_b32 s67, v250, 29
	v_readlane_b32 s68, v250, 30
	v_readlane_b32 s69, v250, 31
	v_readlane_b32 s70, v250, 32
	v_readlane_b32 s71, v250, 33

.LBB0_178:
	v_lshl_add_u64 v[66:67], s[4:5], 0, v[130:131]
	global_load_dwordx4 v[126:129], v130, s[4:5]
	global_load_dwordx4 v[122:125], v130, s[4:5] offset:1024
	global_load_dwordx4 v[106:109], v130, s[4:5] offset:3072
	global_load_dwordx4 v[118:121], v130, s[4:5] offset:2048
	v_add_co_u32_e32 v68, vcc, s3, v66
	s_waitcnt vmcnt(3)
	v_pk_mul_f32 v[142:143], v[128:129], v[128:129]
	v_addc_co_u32_e32 v69, vcc, 0, v67, vcc
	global_load_dwordx4 v[114:117], v[68:69], off offset:-4096
	v_add_co_u32_e32 v70, vcc, s18, v66
	v_pk_mul_f32 v[144:145], v[126:127], v[126:127]
	s_nop 0
	v_addc_co_u32_e32 v71, vcc, 0, v67, vcc
	global_load_dwordx4 v[98:101], v[70:71], off offset:2048
	global_load_dwordx4 v[110:113], v[70:71], off offset:1024
	global_load_dwordx4 v[102:105], v[70:71], off offset:3072
	global_load_dwordx4 v[86:89], v[68:69], off offset:1024
	global_load_dwordx4 v[94:97], v[68:69], off
	global_load_dwordx4 v[90:93], v[68:69], off offset:2048
	v_add_co_u32_e32 v66, vcc, s19, v66
	s_waitcnt vmcnt(9)
	v_pk_mul_f32 v[146:147], v[124:125], v[124:125]
	v_addc_co_u32_e32 v67, vcc, 0, v67, vcc
	global_load_dwordx4 v[82:85], v[68:69], off offset:3072
	global_load_dwordx4 v[74:77], v[66:67], off
	global_load_dwordx4 v[78:81], v[66:67], off offset:1024
	global_load_dwordx4 v[70:73], v[66:67], off offset:2048
	s_nop 0
	global_load_dwordx4 v[66:69], v[66:67], off offset:3072
	v_pk_mul_f32 v[148:149], v[122:123], v[122:123]
	v_pk_mov_b32 v[152:153], v[144:145], v[142:143] op_sel:[1,0]
	v_mov_b32_e32 v145, v143
	v_pk_mov_b32 v[142:143], v[148:149], v[146:147] op_sel:[1,0]
	v_mov_b32_e32 v149, v147
	s_waitcnt vmcnt(12)
	v_mul_f32_e32 v134, v119, v119
	v_mul_f32_e32 v150, v121, v121
	v_pk_add_f32 v[144:145], v[152:153], v[144:145]
	v_pk_add_f32 v[142:143], v[142:143], v[148:149]
	v_mul_f32_e32 v161, v106, v106
	v_mul_f32_e32 v163, v107, v107
	v_mul_f32_e32 v154, v108, v108
	v_mul_f32_e32 v155, v109, v109
	v_pk_fma_f32 v[146:147], v[118:119], v[118:119], v[134:135] op_sel_hi:[1,1,0]
	v_pk_fma_f32 v[150:151], v[120:121], v[120:121], v[150:151] op_sel_hi:[1,1,0]
	v_pk_add_f32 v[144:145], v[144:145], v[144:145] op_sel:[0,1] op_sel_hi:[1,0]
	v_pk_add_f32 v[142:143], v[142:143], v[142:143] op_sel:[0,1] op_sel_hi:[1,0]
	v_mov_b32_e32 v147, v154
	v_mov_b32_e32 v151, v155
	v_mov_b32_e32 v145, v161
	v_mov_b32_e32 v143, v163
	v_pk_add_f32 v[146:147], v[146:147], v[150:151]
	v_pk_add_f32 v[142:143], v[144:145], v[142:143]
	s_waitcnt vmcnt(11)
	v_pk_mul_f32 v[148:149], v[116:117], v[116:117]
	v_pk_mul_f32 v[152:153], v[114:115], v[114:115]
	s_waitcnt vmcnt(9)
	v_mul_f32_e32 v134, v111, v111
	v_pk_mov_b32 v[150:151], v[152:153], v[148:149] op_sel:[1,0]
	v_mov_b32_e32 v153, v149
	v_mul_f32_e32 v154, v113, v113
	v_pk_add_f32 v[150:151], v[150:151], v[152:153]
	v_pk_add_f32 v[142:143], v[142:143], v[146:147]
	v_mul_f32_e32 v166, v98, v98
	v_mul_f32_e32 v167, v99, v99
	v_mul_f32_e32 v168, v100, v100
	v_mul_f32_e32 v169, v101, v101
	v_pk_fma_f32 v[148:149], v[110:111], v[110:111], v[134:135] op_sel_hi:[1,1,0]
	v_pk_fma_f32 v[154:155], v[112:113], v[112:113], v[154:155] op_sel_hi:[1,1,0]
	v_pk_add_f32 v[144:145], v[150:151], v[150:151] op_sel:[0,1] op_sel_hi:[1,0]
	v_pk_add_f32 v[142:143], v[142:143], v[142:143] op_sel:[0,1] op_sel_hi:[1,0]
	s_waitcnt vmcnt(8)
	v_pk_mul_f32 v[156:157], v[104:105], v[104:105]
	v_pk_mul_f32 v[158:159], v[102:103], v[102:103]
	v_mov_b32_e32 v149, v168
	v_mov_b32_e32 v155, v169
	v_mov_b32_e32 v145, v167
	v_mov_b32_e32 v143, v166
	v_pk_mov_b32 v[164:165], v[158:159], v[156:157] op_sel:[1,0]
	v_mov_b32_e32 v159, v157
	v_pk_add_f32 v[148:149], v[148:149], v[154:155]
	v_pk_add_f32 v[142:143], v[142:143], v[144:145]
	s_waitcnt vmcnt(6)
	v_mul_f32_e32 v160, v95, v95
	v_pk_add_f32 v[152:153], v[164:165], v[158:159]
	v_pk_add_f32 v[142:143], v[142:143], v[148:149]
	v_mul_f32_e32 v134, v97, v97
	v_mul_f32_e32 v170, v86, v86
	v_mul_f32_e32 v171, v87, v87
	v_mul_f32_e32 v172, v88, v88
	v_mul_f32_e32 v173, v89, v89
	v_pk_fma_f32 v[156:157], v[94:95], v[94:95], v[160:161] op_sel_hi:[1,1,0]
	v_pk_add_f32 v[150:151], v[152:153], v[152:153] op_sel:[0,1] op_sel_hi:[1,0]
	v_pk_add_f32 v[142:143], v[142:143], v[142:143] op_sel:[0,1] op_sel_hi:[1,0]
	v_pk_fma_f32 v[144:145], v[96:97], v[96:97], v[134:135] op_sel_hi:[1,1,0]
	v_mov_b32_e32 v151, v171
	v_mov_b32_e32 v143, v170
	v_mov_b32_e32 v157, v172
	v_mov_b32_e32 v145, v173
	v_pk_add_f32 v[142:143], v[142:143], v[150:151]
	v_pk_add_f32 v[144:145], v[156:157], v[144:145]
	s_waitcnt vmcnt(5)
	v_pk_mul_f32 v[146:147], v[90:91], v[90:91]
	v_pk_add_f32 v[142:143], v[142:143], v[144:145]
	v_pk_mul_f32 v[144:145], v[92:93], v[92:93]
	s_waitcnt vmcnt(3)
	v_mul_f32_e32 v134, v74, v74
	v_pk_mov_b32 v[148:149], v[146:147], v[144:145] op_sel:[1,0]
	v_mov_b32_e32 v147, v145
	v_pk_add_f32 v[144:145], v[148:149], v[146:147]
	v_mul_f32_e32 v146, v75, v75
	v_pk_add_f32 v[142:143], v[142:143], v[142:143] op_sel:[0,1] op_sel_hi:[1,0]
	v_pk_add_f32 v[144:145], v[144:145], v[144:145] op_sel:[0,1] op_sel_hi:[1,0]
	v_mov_b32_e32 v143, v134
	v_mov_b32_e32 v145, v146
	v_mul_f32_e32 v134, v83, v83
	v_mul_f32_e32 v147, v76, v76
	v_pk_add_f32 v[142:143], v[142:143], v[144:145]
	v_pk_fma_f32 v[144:145], v[82:83], v[82:83], v[134:135] op_sel_hi:[1,1,0]
	v_mul_f32_e32 v134, v85, v85
	v_mul_f32_e32 v148, v77, v77
	v_mov_b32_e32 v145, v147
	v_pk_fma_f32 v[146:147], v[84:85], v[84:85], v[134:135] op_sel_hi:[1,1,0]
	s_waitcnt vmcnt(0)
	v_mul_f32_e32 v134, v66, v66
	v_mov_b32_e32 v147, v148
	v_pk_add_f32 v[144:145], v[144:145], v[146:147]
	v_pk_mul_f32 v[146:147], v[78:79], v[78:79]
	v_pk_add_f32 v[142:143], v[142:143], v[144:145]
	v_pk_mul_f32 v[144:145], v[80:81], v[80:81]
	v_pk_add_f32 v[142:143], v[142:143], v[142:143] op_sel:[0,1] op_sel_hi:[1,0]
	v_pk_mov_b32 v[148:149], v[146:147], v[144:145] op_sel:[1,0]
	v_mov_b32_e32 v147, v145
	v_pk_add_f32 v[144:145], v[148:149], v[146:147]
	v_mul_f32_e32 v146, v67, v67
	v_pk_add_f32 v[144:145], v[144:145], v[144:145] op_sel:[0,1] op_sel_hi:[1,0]
	v_mov_b32_e32 v143, v134
	v_mov_b32_e32 v145, v146
	v_mul_f32_e32 v134, v71, v71
	v_mul_f32_e32 v147, v68, v68
	v_pk_add_f32 v[142:143], v[142:143], v[144:145]
	v_pk_fma_f32 v[144:145], v[70:71], v[70:71], v[134:135] op_sel_hi:[1,1,0]
	v_mul_f32_e32 v134, v73, v73
	v_mul_f32_e32 v148, v69, v69
	v_mov_b32_e32 v145, v147
	v_pk_fma_f32 v[146:147], v[72:73], v[72:73], v[134:135] op_sel_hi:[1,1,0]
	s_nop 0
	v_mov_b32_e32 v147, v148
	v_pk_add_f32 v[144:145], v[144:145], v[146:147]
	s_nop 0
	v_pk_add_f32 v[142:143], v[142:143], v[144:145]
	s_nop 0
	v_add_f32_e32 v134, v142, v143
	ds_bpermute_b32 v142, v1, v134
	s_waitcnt lgkmcnt(0)
	v_add_f32_e32 v134, v134, v142
	ds_bpermute_b32 v142, v135, v134
	s_waitcnt lgkmcnt(0)
	v_add_f32_e32 v134, v134, v142
	ds_bpermute_b32 v142, v136, v134
	s_waitcnt lgkmcnt(0)
	v_add_f32_e32 v134, v134, v142
	ds_bpermute_b32 v142, v137, v134
	s_waitcnt lgkmcnt(0)
	v_add_f32_e32 v134, v134, v142
	ds_bpermute_b32 v142, v138, v134
	s_waitcnt lgkmcnt(0)
	v_add_f32_e32 v134, v134, v142
	ds_bpermute_b32 v142, v139, v134
	s_waitcnt lgkmcnt(0)
	v_add_f32_e32 v134, v134, v142
	v_fmamk_f32 v134, v134, 0x39800000, v140
	v_mul_f32_e32 v142, 0x4f800000, v134
	v_cmp_gt_f32_e32 vcc, s20, v134
	s_nop 1
	v_cndmask_b32_e32 v134, v134, v142, vcc
	v_sqrt_f32_e32 v142, v134
	s_nop 0
	v_add_u32_e32 v143, -1, v142
	v_fma_f32 v144, -v143, v142, v134
	v_cmp_ge_f32_e64 s[4:5], 0, v144
	v_add_u32_e32 v144, 1, v142
	s_nop 0
	v_cndmask_b32_e64 v143, v142, v143, s[4:5]
	v_fma_f32 v142, -v144, v142, v134
	v_cmp_lt_f32_e64 s[4:5], 0, v142
	s_nop 1
	v_cndmask_b32_e64 v142, v143, v144, s[4:5]
	v_mul_f32_e32 v143, 0x37800000, v142
	v_cndmask_b32_e32 v142, v142, v143, vcc
	v_cmp_class_f32_e32 vcc, v134, v141
	s_nop 1
	v_cndmask_b32_e32 v134, v142, v134, vcc
	v_div_scale_f32 v142, s[4:5], v134, v134, 1.0
	v_rcp_f32_e32 v143, v142
	s_lshl_b64 s[4:5], s[16:17], 13
	s_add_u32 s14, s14, s92
	s_addc_u32 s15, s15, s93
	v_fma_f32 v144, -v142, v143, 1.0
	v_fmac_f32_e32 v143, v144, v143
	v_div_scale_f32 v144, vcc, 1.0, v134, 1.0
	v_mul_f32_e32 v145, v144, v143
	v_fma_f32 v146, -v142, v145, v144
	v_fmac_f32_e32 v145, v146, v143
	v_fma_f32 v142, -v142, v145, v144
	v_div_fmas_f32 v142, v142, v143, v145
	v_div_fixup_f32 v134, v142, v134, 1.0
	v_pk_mul_f32 v[126:127], v[126:127], v[134:135] op_sel_hi:[1,0]
	v_pk_mul_f32 v[128:129], v[128:129], v[134:135] op_sel_hi:[1,0]
	v_pk_mul_f32 v[126:127], v[6:7], v[126:127]
	v_pk_mul_f32 v[128:129], v[8:9], v[128:129]
	v_bfe_u32 v144, v126, 16, 1
	v_add3_u32 v126, v126, v144, s21
	v_bfe_u32 v144, v127, 16, 1
	v_lshrrev_b32_e32 v126, 16, v126
	v_add3_u32 v127, v127, v144, s21
	v_and_or_b32 v126, v127, s22, v126
	v_bfe_u32 v127, v128, 16, 1
	v_add3_u32 v127, v128, v127, s21
	v_bfe_u32 v128, v129, 16, 1
	v_lshrrev_b32_e32 v127, 16, v127
	v_add3_u32 v128, v129, v128, s21
	v_pk_mul_f32 v[122:123], v[122:123], v[134:135] op_sel_hi:[1,0]
	v_lshl_add_u64 v[142:143], v[132:133], 0, s[4:5]
	v_and_or_b32 v127, v128, s22, v127
	v_pk_mul_f32 v[122:123], v[10:11], v[122:123]
	global_store_dwordx2 v[142:143], v[126:127], off
	v_bfe_u32 v126, v122, 16, 1
	v_pk_mul_f32 v[124:125], v[124:125], v[134:135] op_sel_hi:[1,0]
	v_add3_u32 v122, v122, v126, s21
	v_bfe_u32 v126, v123, 16, 1
	v_pk_mul_f32 v[124:125], v[12:13], v[124:125]
	v_lshrrev_b32_e32 v122, 16, v122
	v_add3_u32 v123, v123, v126, s21
	v_and_or_b32 v122, v123, s22, v122
	v_bfe_u32 v123, v124, 16, 1
	v_add3_u32 v123, v124, v123, s21
	v_bfe_u32 v124, v125, 16, 1
	v_lshrrev_b32_e32 v123, 16, v123
	v_add3_u32 v124, v125, v124, s21
	v_pk_mul_f32 v[118:119], v[118:119], v[134:135] op_sel_hi:[1,0]
	v_and_or_b32 v123, v124, s22, v123
	v_pk_mul_f32 v[118:119], v[2:3], v[118:119]
	global_store_dwordx2 v[142:143], v[122:123], off offset:512
	v_bfe_u32 v122, v118, 16, 1
	v_pk_mul_f32 v[120:121], v[120:121], v[134:135] op_sel_hi:[1,0]
	v_add3_u32 v118, v118, v122, s21
	v_bfe_u32 v122, v119, 16, 1
	v_pk_mul_f32 v[120:121], v[4:5], v[120:121]
	v_lshrrev_b32_e32 v118, 16, v118
	v_add3_u32 v119, v119, v122, s21
	v_and_or_b32 v118, v119, s22, v118
	v_bfe_u32 v119, v120, 16, 1
	v_add3_u32 v119, v120, v119, s21
	v_bfe_u32 v120, v121, 16, 1
	v_lshrrev_b32_e32 v119, 16, v119
	v_add3_u32 v120, v121, v120, s21
	v_pk_mul_f32 v[106:107], v[106:107], v[134:135] op_sel_hi:[1,0]
	v_and_or_b32 v119, v120, s22, v119
	v_pk_mul_f32 v[106:107], v[14:15], v[106:107]
	global_store_dwordx2 v[142:143], v[118:119], off offset:1024
	v_bfe_u32 v118, v106, 16, 1
	v_pk_mul_f32 v[108:109], v[108:109], v[134:135] op_sel_hi:[1,0]
	v_add3_u32 v106, v106, v118, s21
	v_bfe_u32 v118, v107, 16, 1
	v_pk_mul_f32 v[108:109], v[16:17], v[108:109]
	v_lshrrev_b32_e32 v106, 16, v106
	v_add3_u32 v107, v107, v118, s21
	v_and_or_b32 v106, v107, s22, v106
	v_mov_b32_e32 v107, v108
	v_mov_b32_e32 v108, v109
	v_cvt_pk_bf16_f32 v107, v107, v108
	global_store_dwordx2 v[142:143], v[106:107], off offset:1536
	v_pk_mul_f32 v[106:107], v[114:115], v[134:135] op_sel_hi:[1,0]
	v_pk_mul_f32 v[108:109], v[116:117], v[134:135] op_sel_hi:[1,0]
	v_pk_mul_f32 v[106:107], v[22:23], v[106:107]
	v_pk_mul_f32 v[108:109], v[24:25], v[108:109]
	v_bfe_u32 v114, v106, 16, 1
	v_add3_u32 v106, v106, v114, s21
	v_bfe_u32 v114, v107, 16, 1
	v_lshrrev_b32_e32 v106, 16, v106
	v_add3_u32 v107, v107, v114, s21
	v_and_or_b32 v106, v107, s22, v106
	v_mov_b32_e32 v107, v108
	v_mov_b32_e32 v108, v109
	v_cvt_pk_bf16_f32 v107, v107, v108
	global_store_dwordx2 v[142:143], v[106:107], off offset:2048
	v_pk_mul_f32 v[106:107], v[110:111], v[134:135] op_sel_hi:[1,0]
	v_pk_mul_f32 v[108:109], v[112:113], v[134:135] op_sel_hi:[1,0]
	v_pk_mul_f32 v[106:107], v[26:27], v[106:107]
	v_pk_mul_f32 v[108:109], v[28:29], v[108:109]
	v_bfe_u32 v110, v106, 16, 1
	v_add3_u32 v106, v106, v110, s21
	v_bfe_u32 v110, v107, 16, 1
	v_lshrrev_b32_e32 v106, 16, v106
	v_add3_u32 v107, v107, v110, s21
	v_and_or_b32 v106, v107, s22, v106
	v_bfe_u32 v107, v108, 16, 1
	v_add3_u32 v107, v108, v107, s21
	v_bfe_u32 v108, v109, 16, 1
	v_lshrrev_b32_e32 v107, 16, v107
	v_add3_u32 v108, v109, v108, s21
	v_pk_mul_f32 v[98:99], v[98:99], v[134:135] op_sel_hi:[1,0]
	v_and_or_b32 v107, v108, s22, v107
	v_pk_mul_f32 v[98:99], v[18:19], v[98:99]
	global_store_dwordx2 v[142:143], v[106:107], off offset:2560
	v_bfe_u32 v106, v98, 16, 1
	v_pk_mul_f32 v[100:101], v[100:101], v[134:135] op_sel_hi:[1,0]
	v_add3_u32 v98, v98, v106, s21
	v_bfe_u32 v106, v99, 16, 1
	v_pk_mul_f32 v[100:101], v[20:21], v[100:101]
	v_lshrrev_b32_e32 v98, 16, v98
	v_add3_u32 v99, v99, v106, s21
	v_and_or_b32 v98, v99, s22, v98
	v_mov_b32_e32 v99, v100
	v_mov_b32_e32 v100, v101
	v_cvt_pk_bf16_f32 v99, v99, v100
	global_store_dwordx2 v[142:143], v[98:99], off offset:3072
	v_pk_mul_f32 v[98:99], v[102:103], v[134:135] op_sel_hi:[1,0]
	v_pk_mul_f32 v[100:101], v[104:105], v[134:135] op_sel_hi:[1,0]
	v_pk_mul_f32 v[98:99], v[30:31], v[98:99]
	v_pk_mul_f32 v[100:101], v[32:33], v[100:101]
	v_bfe_u32 v102, v98, 16, 1
	v_add3_u32 v98, v98, v102, s21
	v_bfe_u32 v102, v99, 16, 1
	v_lshrrev_b32_e32 v98, 16, v98
	v_add3_u32 v99, v99, v102, s21
	v_and_or_b32 v98, v99, s22, v98
	v_bfe_u32 v99, v100, 16, 1
	v_add3_u32 v99, v100, v99, s21
	v_bfe_u32 v100, v101, 16, 1
	v_lshrrev_b32_e32 v99, 16, v99
	v_add3_u32 v100, v101, v100, s21
	v_pk_mul_f32 v[94:95], v[94:95], v[134:135] op_sel_hi:[1,0]
	v_and_or_b32 v99, v100, s22, v99
	v_pk_mul_f32 v[94:95], v[38:39], v[94:95]
	global_store_dwordx2 v[142:143], v[98:99], off offset:3584
	v_bfe_u32 v98, v94, 16, 1
	v_pk_mul_f32 v[96:97], v[96:97], v[134:135] op_sel_hi:[1,0]
	v_add3_u32 v94, v94, v98, s21
	v_bfe_u32 v98, v95, 16, 1
	v_pk_mul_f32 v[96:97], v[40:41], v[96:97]
	v_lshrrev_b32_e32 v94, 16, v94
	v_add3_u32 v95, v95, v98, s21
	v_and_or_b32 v94, v95, s22, v94
	v_mov_b32_e32 v95, v96
	v_mov_b32_e32 v96, v97
	v_cvt_pk_bf16_f32 v95, v95, v96
	v_add_co_u32_e32 v96, vcc, s18, v142
	v_pk_mul_f32 v[86:87], v[86:87], v[134:135] op_sel_hi:[1,0]
	s_nop 0
	v_addc_co_u32_e32 v97, vcc, 0, v143, vcc
	v_pk_mul_f32 v[86:87], v[42:43], v[86:87]
	global_store_dwordx2 v[96:97], v[94:95], off
	v_bfe_u32 v94, v86, 16, 1
	v_pk_mul_f32 v[88:89], v[88:89], v[134:135] op_sel_hi:[1,0]
	v_add3_u32 v86, v86, v94, s21
	v_bfe_u32 v94, v87, 16, 1
	v_pk_mul_f32 v[88:89], v[44:45], v[88:89]
	v_lshrrev_b32_e32 v86, 16, v86
	v_add3_u32 v87, v87, v94, s21
	v_and_or_b32 v86, v87, s22, v86
	v_mov_b32_e32 v87, v88
	v_mov_b32_e32 v88, v89
	v_cvt_pk_bf16_f32 v87, v87, v88
	global_store_dwordx2 v[96:97], v[86:87], off offset:512
	v_pk_mul_f32 v[86:87], v[90:91], v[134:135] op_sel_hi:[1,0]
	v_pk_mul_f32 v[88:89], v[92:93], v[134:135] op_sel_hi:[1,0]
	v_pk_mul_f32 v[86:87], v[34:35], v[86:87]
	v_pk_mul_f32 v[88:89], v[36:37], v[88:89]
	v_bfe_u32 v90, v86, 16, 1
	v_add3_u32 v86, v86, v90, s21
	v_bfe_u32 v90, v87, 16, 1
	v_lshrrev_b32_e32 v86, 16, v86
	v_add3_u32 v87, v87, v90, s21
	v_and_or_b32 v86, v87, s22, v86
	v_bfe_u32 v87, v88, 16, 1
	v_add3_u32 v87, v88, v87, s21
	v_bfe_u32 v88, v89, 16, 1
	v_lshrrev_b32_e32 v87, 16, v87
	v_add3_u32 v88, v89, v88, s21
	v_pk_mul_f32 v[82:83], v[82:83], v[134:135] op_sel_hi:[1,0]
	v_and_or_b32 v87, v88, s22, v87
	v_pk_mul_f32 v[82:83], v[46:47], v[82:83]
	global_store_dwordx2 v[96:97], v[86:87], off offset:1024
	v_bfe_u32 v86, v82, 16, 1
	v_pk_mul_f32 v[84:85], v[84:85], v[134:135] op_sel_hi:[1,0]
	v_add3_u32 v82, v82, v86, s21
	v_bfe_u32 v86, v83, 16, 1
	v_pk_mul_f32 v[84:85], v[48:49], v[84:85]
	v_lshrrev_b32_e32 v82, 16, v82
	v_add3_u32 v83, v83, v86, s21
	v_and_or_b32 v82, v83, s22, v82
	v_bfe_u32 v83, v84, 16, 1
	v_add3_u32 v83, v84, v83, s21
	v_bfe_u32 v84, v85, 16, 1
	v_lshrrev_b32_e32 v83, 16, v83
	v_add3_u32 v84, v85, v84, s21
	v_pk_mul_f32 v[74:75], v[74:75], v[134:135] op_sel_hi:[1,0]
	v_and_or_b32 v83, v84, s22, v83
	v_pk_mul_f32 v[74:75], v[54:55], v[74:75]
	global_store_dwordx2 v[96:97], v[82:83], off offset:1536
	v_bfe_u32 v82, v74, 16, 1
	v_pk_mul_f32 v[76:77], v[76:77], v[134:135] op_sel_hi:[1,0]
	v_add3_u32 v74, v74, v82, s21
	v_bfe_u32 v82, v75, 16, 1
	v_pk_mul_f32 v[76:77], v[56:57], v[76:77]
	v_lshrrev_b32_e32 v74, 16, v74
	v_add3_u32 v75, v75, v82, s21
	v_and_or_b32 v74, v75, s22, v74
	v_mov_b32_e32 v75, v76
	v_mov_b32_e32 v76, v77
	v_cvt_pk_bf16_f32 v75, v75, v76
	global_store_dwordx2 v[96:97], v[74:75], off offset:2048
	v_pk_mul_f32 v[74:75], v[78:79], v[134:135] op_sel_hi:[1,0]
	v_pk_mul_f32 v[76:77], v[80:81], v[134:135] op_sel_hi:[1,0]
	v_pk_mul_f32 v[74:75], v[58:59], v[74:75]
	v_pk_mul_f32 v[76:77], v[60:61], v[76:77]
	v_bfe_u32 v78, v74, 16, 1
	v_add3_u32 v74, v74, v78, s21
	v_bfe_u32 v78, v75, 16, 1
	v_lshrrev_b32_e32 v74, 16, v74
	v_add3_u32 v75, v75, v78, s21
	v_and_or_b32 v74, v75, s22, v74
	v_bfe_u32 v75, v76, 16, 1
	v_add3_u32 v75, v76, v75, s21
	v_bfe_u32 v76, v77, 16, 1
	v_lshrrev_b32_e32 v75, 16, v75
	v_add3_u32 v76, v77, v76, s21
	v_pk_mul_f32 v[70:71], v[70:71], v[134:135] op_sel_hi:[1,0]
	v_and_or_b32 v75, v76, s22, v75
	v_pk_mul_f32 v[70:71], v[50:51], v[70:71]
	global_store_dwordx2 v[96:97], v[74:75], off offset:2560
	v_bfe_u32 v74, v70, 16, 1
	v_pk_mul_f32 v[72:73], v[72:73], v[134:135] op_sel_hi:[1,0]
	v_add3_u32 v70, v70, v74, s21
	v_bfe_u32 v74, v71, 16, 1
	v_pk_mul_f32 v[72:73], v[52:53], v[72:73]
	v_lshrrev_b32_e32 v70, 16, v70
	v_add3_u32 v71, v71, v74, s21
	v_and_or_b32 v70, v71, s22, v70
	v_bfe_u32 v71, v72, 16, 1
	v_add3_u32 v71, v72, v71, s21
	v_bfe_u32 v72, v73, 16, 1
	v_lshrrev_b32_e32 v71, 16, v71
	v_add3_u32 v72, v73, v72, s21
	v_pk_mul_f32 v[66:67], v[66:67], v[134:135] op_sel_hi:[1,0]
	v_and_or_b32 v71, v72, s22, v71
	v_pk_mul_f32 v[66:67], v[62:63], v[66:67]
	global_store_dwordx2 v[96:97], v[70:71], off offset:3072
	v_bfe_u32 v70, v66, 16, 1
	v_pk_mul_f32 v[68:69], v[68:69], v[134:135] op_sel_hi:[1,0]
	v_add3_u32 v66, v66, v70, s21
	v_bfe_u32 v70, v67, 16, 1
	v_pk_mul_f32 v[68:69], v[64:65], v[68:69]
	v_lshrrev_b32_e32 v66, 16, v66
	v_add3_u32 v67, v67, v70, s21
	v_and_or_b32 v66, v67, s22, v66
	v_bfe_u32 v67, v68, 16, 1
	v_add3_u32 v67, v68, v67, s21
	v_bfe_u32 v68, v69, 16, 1
	s_add_u32 s10, s10, s12
	v_lshrrev_b32_e32 v67, 16, v67
	v_add3_u32 v68, v69, v68, s21
	s_addc_u32 s11, s11, s13
	v_and_or_b32 v67, v68, s22, v67
	s_cmpk_gt_i32 s14, 0x20ff
	global_store_dwordx2 v[96:97], v[66:67], off offset:3584
	s_cbranch_scc1 .LBB0_181

.LBB0_356:
	ds_read2_b32 v[104:105], v152 offset1:8
	ds_read2_b32 v[112:113], v152 offset0:66 offset1:74
	ds_read2_b32 v[114:115], v152 offset0:33 offset1:41
	ds_read2_b32 v[116:117], v152 offset0:99 offset1:107
	ds_read2_b32 v[118:119], v152 offset0:132 offset1:140
	ds_read2_b32 v[120:121], v152 offset0:198 offset1:206
	ds_read2_b32 v[122:123], v152 offset0:165 offset1:173
	ds_read2_b32 v[124:125], v152 offset0:231 offset1:239
	s_waitcnt lgkmcnt(7)
	v_mov_b32_e32 v108, v104
	s_waitcnt lgkmcnt(5)
	v_mov_b32_e32 v110, v114
	s_waitcnt lgkmcnt(4)
	v_mov_b32_e32 v111, v116
	s_waitcnt lgkmcnt(3)
	v_mov_b32_e32 v126, v118
	s_waitcnt lgkmcnt(2)
	v_mov_b32_e32 v127, v120
	v_mov_b32_e32 v109, v112
	v_pk_mul_f32 v[110:111], v[100:101], v[110:111]
	v_pk_mul_f32 v[126:127], v[98:99], v[126:127]
	s_waitcnt lgkmcnt(1)
	v_mov_b32_e32 v128, v122
	s_waitcnt lgkmcnt(0)
	v_mov_b32_e32 v129, v124
	v_pk_mul_f32 v[108:109], v[102:103], v[108:109]
	v_pk_mul_f32 v[128:129], v[106:107], v[128:129]
	v_mov_b32_e32 v114, v111
	v_mov_b32_e32 v120, v127
	v_mov_b32_e32 v116, v110
	v_mov_b32_e32 v110, v128
	v_mov_b32_e32 v104, v129
	v_mov_b32_e32 v118, v126
	v_mov_b32_e32 v111, v120
	v_mov_b32_e32 v112, v118
	v_cvt_pk_bf16_f32 v111, v111, v104
	v_or_b32_e32 v104, s54, v1
	s_ashr_i32 s7, s54, 31
	v_cvt_pk_bf16_f32 v110, v112, v110
	v_mul_lo_u32 v112, s35, v104
	s_mul_i32 s7, s34, s7
	v_mad_u64_u32 v[126:127], s[8:9], s34, v104, 0
	v_add3_u32 v127, v127, s7, v112
	v_lshl_add_u64 v[126:127], v[126:127], 1, s[28:29]
	s_lshl_b64 s[8:9], s[36:37], 1
	v_lshl_add_u64 v[126:127], v[126:127], 0, s[8:9]
	v_mov_b32_e32 v143, v139
	v_mov_b32_e32 v112, v105
	v_mov_b32_e32 v124, v123
	v_cvt_pk_bf16_f32 v109, v109, v114
	v_cvt_pk_bf16_f32 v108, v108, v116
	v_lshl_add_u64 v[126:127], v[126:127], 0, v[142:143]
	v_pk_mul_f32 v[104:105], v[102:103], v[112:113]
	v_mov_b32_e32 v116, v115
	v_pk_mul_f32 v[112:113], v[106:107], v[124:125]
	global_store_dwordx4 v[126:127], v[108:111], off
	v_mov_b32_e32 v120, v119
	s_nop 0
	v_pk_mul_f32 v[108:109], v[100:101], v[116:117]
	v_pk_mul_f32 v[110:111], v[98:99], v[120:121]
	v_cvt_pk_bf16_f32 v108, v104, v108
	v_or_b32_e32 v104, s54, v141
	v_cvt_pk_bf16_f32 v110, v110, v112
	v_cvt_pk_bf16_f32 v109, v105, v109
	v_mul_lo_u32 v112, s35, v104
	v_mad_u64_u32 v[104:105], s[24:25], s34, v104, 0
	v_add3_u32 v105, v105, s7, v112
	v_lshl_add_u64 v[104:105], v[104:105], 1, s[28:29]
	v_lshl_add_u64 v[104:105], v[104:105], 0, s[8:9]
	v_cvt_pk_bf16_f32 v111, v111, v113
	v_lshl_add_u64 v[104:105], v[104:105], 0, v[142:143]
	ds_read2_b32 v[112:113], v152 offset0:16 offset1:24
	ds_read2_b32 v[114:115], v152 offset0:82 offset1:90
	global_store_dwordx4 v[104:105], v[108:111], off
	ds_read2_b32 v[104:105], v152 offset0:49 offset1:57
	ds_read2_b32 v[116:117], v152 offset0:115 offset1:123
	ds_read2_b32 v[118:119], v152 offset0:148 offset1:156
	ds_read2_b32 v[120:121], v152 offset0:214 offset1:222
	ds_read2_b32 v[122:123], v152 offset0:181 offset1:189
	ds_read2_b32 v[124:125], v152 offset0:247 offset1:255
	s_waitcnt lgkmcnt(7)
	v_mov_b32_e32 v108, v112
	s_waitcnt lgkmcnt(5)
	v_mov_b32_e32 v110, v104
	s_waitcnt lgkmcnt(4)
	v_mov_b32_e32 v111, v116
	s_waitcnt lgkmcnt(3)
	v_mov_b32_e32 v126, v118
	s_waitcnt lgkmcnt(2)
	v_mov_b32_e32 v127, v120
	v_mov_b32_e32 v109, v114
	v_pk_mul_f32 v[110:111], v[100:101], v[110:111]
	v_pk_mul_f32 v[126:127], v[98:99], v[126:127]
	s_waitcnt lgkmcnt(1)
	v_mov_b32_e32 v128, v122
	s_waitcnt lgkmcnt(0)
	v_mov_b32_e32 v129, v124
	v_pk_mul_f32 v[108:109], v[102:103], v[108:109]
	v_pk_mul_f32 v[128:129], v[106:107], v[128:129]
	v_bfe_u32 v112, v128, 16, 1
	v_mov_b32_e32 v114, v111
	v_bfe_u32 v118, v126, 16, 1
	v_mov_b32_e32 v120, v127
	v_mov_b32_e32 v116, v110
	v_add3_u32 v110, v128, v112, s52
	v_mov_b32_e32 v104, v129
	v_add3_u32 v118, v126, v118, s52
	v_mov_b32_e32 v111, v120
	v_lshrrev_b32_e32 v112, 16, v118
	v_cvt_pk_bf16_f32 v111, v111, v104
	v_or_b32_e32 v104, s54, v146
	v_and_or_b32 v110, v110, s53, v112
	v_mul_lo_u32 v112, s35, v104
	v_mad_u64_u32 v[126:127], s[24:25], s34, v104, 0
	v_add3_u32 v127, v127, s7, v112
	v_lshl_add_u64 v[126:127], v[126:127], 1, s[28:29]
	v_cvt_pk_bf16_f32 v108, v108, v116
	v_lshl_add_u64 v[126:127], v[126:127], 0, s[8:9]
	v_mov_b32_e32 v116, v105
	v_mov_b32_e32 v124, v123
	v_cvt_pk_bf16_f32 v109, v109, v114
	v_lshl_add_u64 v[126:127], v[126:127], 0, v[142:143]
	v_mov_b32_e32 v114, v113
	v_pk_mul_f32 v[100:101], v[100:101], v[116:117]
	v_mov_b32_e32 v120, v119
	v_pk_mul_f32 v[104:105], v[106:107], v[124:125]
	global_store_dwordx4 v[126:127], v[108:111], off
	v_pk_mul_f32 v[102:103], v[102:103], v[114:115]
	v_pk_mul_f32 v[98:99], v[98:99], v[120:121]
	v_bfe_u32 v106, v105, 16, 1
	v_bfe_u32 v107, v104, 16, 1
	v_bfe_u32 v108, v101, 16, 1
	v_bfe_u32 v109, v100, 16, 1
	v_add3_u32 v109, v100, v109, s52
	v_add3_u32 v108, v101, v108, s52
	v_add3_u32 v100, v104, v107, s52
	v_add3_u32 v101, v105, v106, s52
	v_bfe_u32 v104, v102, 16, 1
	v_bfe_u32 v106, v98, 16, 1
	v_bfe_u32 v105, v103, 16, 1
	v_bfe_u32 v107, v99, 16, 1
	v_add3_u32 v98, v98, v106, s52
	v_add3_u32 v102, v102, v104, s52
	v_add3_u32 v99, v99, v107, s52
	v_add3_u32 v103, v103, v105, s52
	v_lshrrev_b32_e32 v102, 16, v102
	v_lshrrev_b32_e32 v98, 16, v98
	v_lshrrev_b32_e32 v103, 16, v103
	v_lshrrev_b32_e32 v99, 16, v99
	v_and_or_b32 v100, v100, s53, v98
	v_and_or_b32 v98, v109, s53, v102
	v_or_b32_e32 v102, s54, v147
	v_and_or_b32 v101, v101, s53, v99
	v_and_or_b32 v99, v108, s53, v103
	v_mul_lo_u32 v104, s35, v102
	v_mad_u64_u32 v[102:103], s[24:25], s34, v102, 0
	v_add3_u32 v103, v103, s7, v104
	v_lshl_add_u64 v[102:103], v[102:103], 1, s[28:29]
	v_lshl_add_u64 v[102:103], v[102:103], 0, s[8:9]
	v_lshl_add_u64 v[102:103], v[102:103], 0, v[142:143]
	global_store_dwordx4 v[102:103], v[98:101], off
	s_waitcnt lgkmcnt(0)
	s_add_i32 s3, s3, s40
	s_cmp_lt_i32 s3, 0x154a0
	s_mov_b32 s92, s2
	s_cselect_b64 s[8:9], -1, 0

.LBB0_380:
	ds_read2_b32 v[136:137], v152 offset1:8
	ds_read2_b32 v[174:175], v152 offset0:66 offset1:74
	ds_read2_b32 v[176:177], v152 offset0:33 offset1:41
	ds_read2_b32 v[178:179], v152 offset0:99 offset1:107
	ds_read2_b32 v[180:181], v152 offset0:132 offset1:140
	ds_read2_b32 v[182:183], v152 offset0:198 offset1:206
	ds_read2_b32 v[184:185], v152 offset0:165 offset1:173
	ds_read2_b32 v[186:187], v152 offset0:231 offset1:239
	s_waitcnt lgkmcnt(7)
	v_mov_b32_e32 v170, v136
	s_waitcnt lgkmcnt(5)
	v_mov_b32_e32 v172, v176
	s_waitcnt lgkmcnt(4)
	v_mov_b32_e32 v173, v178
	s_waitcnt lgkmcnt(3)
	v_mov_b32_e32 v188, v180
	s_waitcnt lgkmcnt(2)
	v_mov_b32_e32 v189, v182
	v_mov_b32_e32 v171, v174
	v_pk_mul_f32 v[172:173], v[132:133], v[172:173]
	v_pk_mul_f32 v[188:189], v[130:131], v[188:189]
	s_waitcnt lgkmcnt(1)
	v_mov_b32_e32 v190, v184
	s_waitcnt lgkmcnt(0)
	v_mov_b32_e32 v191, v186
	v_pk_mul_f32 v[170:171], v[134:135], v[170:171]
	v_pk_mul_f32 v[190:191], v[144:145], v[190:191]
	v_mov_b32_e32 v169, v173
	v_mov_b32_e32 v178, v189
	v_mov_b32_e32 v136, v191
	v_mov_b32_e32 v173, v178
	v_mov_b32_e32 v174, v172
	v_mov_b32_e32 v176, v188
	v_cvt_pk_bf16_f32 v173, v173, v136
	v_add_u32_e32 v136, s33, v1
	v_mov_b32_e32 v143, v190
	v_mov_b32_e32 v172, v176
	v_mad_u64_u32 v[188:189], s[8:9], v136, s41, 0
	v_cvt_pk_bf16_f32 v172, v172, v143
	v_ashrrev_i32_e32 v143, 31, v136
	v_mov_b32_e32 v136, v189
	v_mad_u64_u32 v[190:191], s[8:9], v143, s41, v[136:137]
	v_mov_b32_e32 v189, v190
	v_lshl_add_u64 v[188:189], v[188:189], 1, s[10:11]
	s_lshl_b64 s[8:9], s[6:7], 1
	v_cvt_pk_bf16_f32 v170, v170, v174
	v_lshl_add_u64 v[188:189], v[188:189], 0, s[8:9]
	v_mov_b32_e32 v143, v139
	v_mov_b32_e32 v174, v137
	v_mov_b32_e32 v186, v185
	v_cvt_pk_bf16_f32 v171, v171, v169
	v_lshl_add_u64 v[188:189], v[188:189], 0, v[142:143]
	v_pk_mul_f32 v[136:137], v[134:135], v[174:175]
	v_mov_b32_e32 v178, v177
	v_pk_mul_f32 v[174:175], v[144:145], v[186:187]
	global_store_dwordx4 v[188:189], v[170:173], off
	v_mov_b32_e32 v182, v181
	s_nop 0
	v_pk_mul_f32 v[170:171], v[132:133], v[178:179]
	v_pk_mul_f32 v[172:173], v[130:131], v[182:183]
	v_bfe_u32 v178, v170, 16, 1
	v_mov_b32_e32 v169, v175
	v_bfe_u32 v175, v136, 16, 1
	v_add3_u32 v170, v170, v178, s52
	v_add3_u32 v136, v136, v175, s52
	v_lshrrev_b32_e32 v136, 16, v136
	v_and_or_b32 v170, v170, s53, v136
	v_add_u32_e32 v136, s33, v141
	v_cvt_pk_bf16_f32 v173, v173, v169
	v_cvt_pk_bf16_f32 v171, v137, v171
	v_ashrrev_i32_e32 v169, 31, v136
	v_mad_u64_u32 v[136:137], s[24:25], v136, s41, 0
	v_cvt_pk_bf16_f32 v172, v172, v174
	v_mov_b32_e32 v174, v137
	v_mad_u64_u32 v[174:175], s[24:25], v169, s41, v[174:175]
	v_mov_b32_e32 v137, v174
	v_lshl_add_u64 v[136:137], v[136:137], 1, s[10:11]
	v_lshl_add_u64 v[136:137], v[136:137], 0, s[8:9]
	v_lshl_add_u64 v[136:137], v[136:137], 0, v[142:143]
	ds_read2_b32 v[174:175], v152 offset0:16 offset1:24
	ds_read2_b32 v[176:177], v152 offset0:82 offset1:90
	global_store_dwordx4 v[136:137], v[170:173], off
	ds_read2_b32 v[136:137], v152 offset0:49 offset1:57
	ds_read2_b32 v[178:179], v152 offset0:115 offset1:123
	ds_read2_b32 v[180:181], v152 offset0:148 offset1:156
	ds_read2_b32 v[182:183], v152 offset0:214 offset1:222
	ds_read2_b32 v[184:185], v152 offset0:181 offset1:189
	ds_read2_b32 v[186:187], v152 offset0:247 offset1:255
	s_waitcnt lgkmcnt(7)
	v_mov_b32_e32 v170, v174
	s_waitcnt lgkmcnt(5)
	v_mov_b32_e32 v172, v136
	s_waitcnt lgkmcnt(4)
	v_mov_b32_e32 v173, v178
	s_waitcnt lgkmcnt(3)
	v_mov_b32_e32 v188, v180
	s_waitcnt lgkmcnt(2)
	v_mov_b32_e32 v189, v182
	v_mov_b32_e32 v171, v176
	v_pk_mul_f32 v[172:173], v[132:133], v[172:173]
	v_pk_mul_f32 v[188:189], v[130:131], v[188:189]
	s_waitcnt lgkmcnt(1)
	v_mov_b32_e32 v190, v184
	s_waitcnt lgkmcnt(0)
	v_mov_b32_e32 v191, v186
	v_pk_mul_f32 v[170:171], v[134:135], v[170:171]
	v_pk_mul_f32 v[190:191], v[144:145], v[190:191]
	v_bfe_u32 v174, v173, 16, 1
	v_bfe_u32 v180, v189, 16, 1
	v_bfe_u32 v136, v191, 16, 1
	v_add3_u32 v174, v173, v174, s52
	v_bfe_u32 v173, v171, 16, 1
	v_add3_u32 v180, v189, v180, s52
	v_add3_u32 v136, v191, v136, s52
	v_add3_u32 v171, v171, v173, s52
	v_lshrrev_b32_e32 v173, 16, v180
	v_mov_b32_e32 v176, v172
	v_mov_b32_e32 v178, v188
	v_and_or_b32 v173, v136, s53, v173
	v_add_u32_e32 v136, s33, v146
	v_mov_b32_e32 v169, v190
	v_mov_b32_e32 v172, v178
	v_mad_u64_u32 v[188:189], s[24:25], v136, s41, 0
	v_cvt_pk_bf16_f32 v172, v172, v169
	v_ashrrev_i32_e32 v169, 31, v136
	v_mov_b32_e32 v136, v189
	v_mad_u64_u32 v[190:191], s[24:25], v169, s41, v[136:137]
	v_mov_b32_e32 v189, v190
	v_lshl_add_u64 v[188:189], v[188:189], 1, s[10:11]
	v_lshrrev_b32_e32 v171, 16, v171
	v_lshl_add_u64 v[188:189], v[188:189], 0, s[8:9]
	v_mov_b32_e32 v178, v137
	v_mov_b32_e32 v186, v185
	v_and_or_b32 v171, v174, s53, v171
	v_cvt_pk_bf16_f32 v170, v170, v176
	v_lshl_add_u64 v[188:189], v[188:189], 0, v[142:143]
	v_mov_b32_e32 v176, v175
	v_pk_mul_f32 v[132:133], v[132:133], v[178:179]
	v_mov_b32_e32 v182, v181
	v_pk_mul_f32 v[136:137], v[144:145], v[186:187]
	global_store_dwordx4 v[188:189], v[170:173], off
	v_pk_mul_f32 v[134:135], v[134:135], v[176:177]
	v_pk_mul_f32 v[130:131], v[130:131], v[182:183]
	v_bfe_u32 v144, v137, 16, 1
	v_bfe_u32 v145, v136, 16, 1
	v_bfe_u32 v169, v133, 16, 1
	v_bfe_u32 v170, v132, 16, 1
	v_add3_u32 v170, v132, v170, s52
	v_add3_u32 v169, v133, v169, s52
	v_add3_u32 v132, v136, v145, s52
	v_add3_u32 v133, v137, v144, s52
	v_bfe_u32 v136, v134, 16, 1
	v_bfe_u32 v144, v130, 16, 1
	v_bfe_u32 v137, v135, 16, 1
	v_bfe_u32 v145, v131, 16, 1
	v_add3_u32 v130, v130, v144, s52
	v_add3_u32 v134, v134, v136, s52
	v_add3_u32 v131, v131, v145, s52
	v_add3_u32 v135, v135, v137, s52
	v_lshrrev_b32_e32 v134, 16, v134
	v_lshrrev_b32_e32 v130, 16, v130
	v_lshrrev_b32_e32 v135, 16, v135
	v_lshrrev_b32_e32 v131, 16, v131
	v_and_or_b32 v132, v132, s53, v130
	v_and_or_b32 v130, v170, s53, v134
	v_add_u32_e32 v134, s33, v147
	v_and_or_b32 v133, v133, s53, v131
	v_and_or_b32 v131, v169, s53, v135
	v_ashrrev_i32_e32 v137, 31, v134
	v_mad_u64_u32 v[134:135], s[24:25], v134, s41, 0
	v_mov_b32_e32 v136, v135
	v_mad_u64_u32 v[136:137], s[24:25], v137, s41, v[136:137]
	v_mov_b32_e32 v135, v136
	v_lshl_add_u64 v[134:135], v[134:135], 1, s[10:11]
	v_lshl_add_u64 v[134:135], v[134:135], 0, s[8:9]
	v_lshl_add_u64 v[134:135], v[134:135], 0, v[142:143]
	global_store_dwordx4 v[134:135], v[130:133], off
	s_waitcnt lgkmcnt(0)
	s_add_i32 s3, s3, s40
	s_mov_b32 s92, s2
	s_cmp_lt_i32 s3, 0x154a0
	s_mov_b64 s[8:9], 0
	s_cbranch_scc0 .LBB0_357
	s_add_i32 s6, s3, s46
	s_cmp_lt_i32 s6, 0x154a0
	s_cselect_b32 s7, s6, s3
	s_cmp_lt_i32 s7, 0x8080
	s_cbranch_scc1 .LBB0_395
	s_cmpk_lt_u32 s7, 0xa080
	s_cbranch_scc1 .LBB0_396
	s_cmp_lt_u32 s7, 0x14c80
	s_cselect_b64 s[8:9], -1, 0
	s_add_i32 s6, s7, 0xfffe1580
	s_cmpk_lt_u32 s6, 0xac00
	s_cselect_b64 s[10:11], -1, 0
	s_or_b64 s[8:9], s[8:9], s[10:11]
	s_mov_b64 s[30:31], -1
	s_and_b64 vcc, exec, s[8:9]
	s_cbranch_vccnz .LBB0_392
	s_add_i32 s6, s7, 0xfffd6980
	s_cmp_lt_u32 s6, 0xffff0c00
	s_cbranch_scc1 .LBB0_389
	s_cmp_lt_u32 s7, 0x1ca80
	s_mov_b64 s[8:9], -1
	s_cbranch_scc1 .LBB0_387
	s_add_i32 s6, s7, 0xfffe3580
	v_readlane_b32 s56, v250, 18
	s_lshl_b32 s8, s7, 5
	s_lshr_b32 s6, s6, 1
	v_readlane_b32 s64, v250, 26
	v_readlane_b32 s65, v250, 27
	s_and_b32 s33, s8, 0xfe0
	s_and_b32 s6, s6, 0x7fffffc0
	s_mov_b64 s[8:9], 0
	s_mov_b64 s[92:93], s[64:65]
	v_readlane_b32 s57, v250, 19
	v_readlane_b32 s58, v250, 20
	v_readlane_b32 s59, v250, 21
	v_readlane_b32 s60, v250, 22
	v_readlane_b32 s61, v250, 23
	v_readlane_b32 s62, v250, 24
	v_readlane_b32 s63, v250, 25
	v_readlane_b32 s66, v250, 28
	v_readlane_b32 s67, v250, 29
	v_readlane_b32 s68, v250, 30
	v_readlane_b32 s69, v250, 31
	v_readlane_b32 s70, v250, 32
	v_readlane_b32 s71, v250, 33

.LBB0_403:
	ds_read2_b32 v[136:137], v152 offset1:8
	ds_read2_b32 v[174:175], v152 offset0:66 offset1:74
	ds_read2_b32 v[176:177], v152 offset0:33 offset1:41
	ds_read2_b32 v[178:179], v152 offset0:99 offset1:107
	ds_read2_b32 v[180:181], v152 offset0:132 offset1:140
	ds_read2_b32 v[182:183], v152 offset0:198 offset1:206
	ds_read2_b32 v[184:185], v152 offset0:165 offset1:173
	ds_read2_b32 v[186:187], v152 offset0:231 offset1:239
	s_waitcnt lgkmcnt(7)
	v_mov_b32_e32 v170, v136
	s_waitcnt lgkmcnt(5)
	v_mov_b32_e32 v172, v176
	s_waitcnt lgkmcnt(4)
	v_mov_b32_e32 v173, v178
	s_waitcnt lgkmcnt(3)
	v_mov_b32_e32 v188, v180
	s_waitcnt lgkmcnt(2)
	v_mov_b32_e32 v189, v182
	v_mov_b32_e32 v171, v174
	v_pk_mul_f32 v[172:173], v[132:133], v[172:173]
	v_pk_mul_f32 v[188:189], v[130:131], v[188:189]
	s_waitcnt lgkmcnt(1)
	v_mov_b32_e32 v190, v184
	s_waitcnt lgkmcnt(0)
	v_mov_b32_e32 v191, v186
	v_pk_mul_f32 v[170:171], v[134:135], v[170:171]
	v_pk_mul_f32 v[190:191], v[144:145], v[190:191]
	v_mov_b32_e32 v169, v173
	v_mov_b32_e32 v178, v189
	v_mov_b32_e32 v136, v191
	v_mov_b32_e32 v173, v178
	v_mov_b32_e32 v174, v172
	v_mov_b32_e32 v176, v188
	v_cvt_pk_bf16_f32 v173, v173, v136
	v_add_u32_e32 v136, s42, v1
	v_mov_b32_e32 v143, v190
	v_mov_b32_e32 v172, v176
	v_mad_u64_u32 v[188:189], s[8:9], v136, s43, 0
	v_cvt_pk_bf16_f32 v172, v172, v143
	v_ashrrev_i32_e32 v143, 31, v136
	v_mov_b32_e32 v136, v189
	v_mad_u64_u32 v[190:191], s[8:9], v143, s43, v[136:137]
	v_mov_b32_e32 v189, v190
	v_lshl_add_u64 v[188:189], v[188:189], 1, s[16:17]
	s_lshl_b64 s[8:9], s[12:13], 1
	v_cvt_pk_bf16_f32 v170, v170, v174
	v_lshl_add_u64 v[188:189], v[188:189], 0, s[8:9]
	v_mov_b32_e32 v143, v139
	v_mov_b32_e32 v174, v137
	v_mov_b32_e32 v186, v185
	v_cvt_pk_bf16_f32 v171, v171, v169
	v_lshl_add_u64 v[188:189], v[188:189], 0, v[142:143]
	v_pk_mul_f32 v[136:137], v[134:135], v[174:175]
	v_mov_b32_e32 v178, v177
	v_pk_mul_f32 v[174:175], v[144:145], v[186:187]
	global_store_dwordx4 v[188:189], v[170:173], off
	v_mov_b32_e32 v182, v181
	s_nop 0
	v_pk_mul_f32 v[170:171], v[132:133], v[178:179]
	v_pk_mul_f32 v[172:173], v[130:131], v[182:183]
	v_bfe_u32 v178, v170, 16, 1
	v_mov_b32_e32 v169, v175
	v_bfe_u32 v175, v136, 16, 1
	v_add3_u32 v170, v170, v178, s52
	v_add3_u32 v136, v136, v175, s52
	v_lshrrev_b32_e32 v136, 16, v136
	v_and_or_b32 v170, v170, s53, v136
	v_add_u32_e32 v136, s42, v141
	v_cvt_pk_bf16_f32 v173, v173, v169
	v_cvt_pk_bf16_f32 v171, v137, v171
	v_ashrrev_i32_e32 v169, 31, v136
	v_mad_u64_u32 v[136:137], s[24:25], v136, s43, 0
	v_cvt_pk_bf16_f32 v172, v172, v174
	v_mov_b32_e32 v174, v137
	v_mad_u64_u32 v[174:175], s[24:25], v169, s43, v[174:175]
	v_mov_b32_e32 v137, v174
	v_lshl_add_u64 v[136:137], v[136:137], 1, s[16:17]
	v_lshl_add_u64 v[136:137], v[136:137], 0, s[8:9]
	v_lshl_add_u64 v[136:137], v[136:137], 0, v[142:143]
	ds_read2_b32 v[174:175], v152 offset0:16 offset1:24
	ds_read2_b32 v[176:177], v152 offset0:82 offset1:90
	global_store_dwordx4 v[136:137], v[170:173], off
	ds_read2_b32 v[136:137], v152 offset0:49 offset1:57
	ds_read2_b32 v[178:179], v152 offset0:115 offset1:123
	ds_read2_b32 v[180:181], v152 offset0:148 offset1:156
	ds_read2_b32 v[182:183], v152 offset0:214 offset1:222
	ds_read2_b32 v[184:185], v152 offset0:181 offset1:189
	ds_read2_b32 v[186:187], v152 offset0:247 offset1:255
	s_waitcnt lgkmcnt(7)
	v_mov_b32_e32 v170, v174
	s_waitcnt lgkmcnt(5)
	v_mov_b32_e32 v172, v136
	s_waitcnt lgkmcnt(4)
	v_mov_b32_e32 v173, v178
	s_waitcnt lgkmcnt(3)
	v_mov_b32_e32 v188, v180
	s_waitcnt lgkmcnt(2)
	v_mov_b32_e32 v189, v182
	v_mov_b32_e32 v171, v176
	v_pk_mul_f32 v[172:173], v[132:133], v[172:173]
	v_pk_mul_f32 v[188:189], v[130:131], v[188:189]
	s_waitcnt lgkmcnt(1)
	v_mov_b32_e32 v190, v184
	s_waitcnt lgkmcnt(0)
	v_mov_b32_e32 v191, v186
	v_pk_mul_f32 v[170:171], v[134:135], v[170:171]
	v_pk_mul_f32 v[190:191], v[144:145], v[190:191]
	v_bfe_u32 v174, v173, 16, 1
	v_bfe_u32 v180, v189, 16, 1
	v_bfe_u32 v136, v191, 16, 1
	v_add3_u32 v174, v173, v174, s52
	v_bfe_u32 v173, v171, 16, 1
	v_add3_u32 v180, v189, v180, s52
	v_add3_u32 v136, v191, v136, s52
	v_add3_u32 v171, v171, v173, s52
	v_lshrrev_b32_e32 v173, 16, v180
	v_mov_b32_e32 v176, v172
	v_mov_b32_e32 v178, v188
	v_and_or_b32 v173, v136, s53, v173
	v_add_u32_e32 v136, s42, v146
	v_mov_b32_e32 v169, v190
	v_mov_b32_e32 v172, v178
	v_mad_u64_u32 v[188:189], s[24:25], v136, s43, 0
	v_cvt_pk_bf16_f32 v172, v172, v169
	v_ashrrev_i32_e32 v169, 31, v136
	v_mov_b32_e32 v136, v189
	v_mad_u64_u32 v[190:191], s[24:25], v169, s43, v[136:137]
	v_mov_b32_e32 v189, v190
	v_lshl_add_u64 v[188:189], v[188:189], 1, s[16:17]
	v_lshrrev_b32_e32 v171, 16, v171
	v_lshl_add_u64 v[188:189], v[188:189], 0, s[8:9]
	v_mov_b32_e32 v178, v137
	v_mov_b32_e32 v186, v185
	v_and_or_b32 v171, v174, s53, v171
	v_cvt_pk_bf16_f32 v170, v170, v176
	v_lshl_add_u64 v[188:189], v[188:189], 0, v[142:143]
	v_mov_b32_e32 v176, v175
	v_pk_mul_f32 v[132:133], v[132:133], v[178:179]
	v_mov_b32_e32 v182, v181
	v_pk_mul_f32 v[136:137], v[144:145], v[186:187]
	global_store_dwordx4 v[188:189], v[170:173], off
	v_pk_mul_f32 v[134:135], v[134:135], v[176:177]
	v_pk_mul_f32 v[130:131], v[130:131], v[182:183]
	v_bfe_u32 v144, v137, 16, 1
	v_bfe_u32 v145, v136, 16, 1
	v_bfe_u32 v169, v133, 16, 1
	v_bfe_u32 v170, v132, 16, 1
	v_add3_u32 v170, v132, v170, s52
	v_add3_u32 v169, v133, v169, s52
	v_add3_u32 v132, v136, v145, s52
	v_add3_u32 v133, v137, v144, s52
	v_bfe_u32 v136, v134, 16, 1
	v_bfe_u32 v144, v130, 16, 1
	v_bfe_u32 v137, v135, 16, 1
	v_bfe_u32 v145, v131, 16, 1
	v_add3_u32 v130, v130, v144, s52
	v_add3_u32 v134, v134, v136, s52
	v_add3_u32 v131, v131, v145, s52
	v_add3_u32 v135, v135, v137, s52
	v_lshrrev_b32_e32 v134, 16, v134
	v_lshrrev_b32_e32 v130, 16, v130
	v_lshrrev_b32_e32 v135, 16, v135
	v_lshrrev_b32_e32 v131, 16, v131
	v_and_or_b32 v132, v132, s53, v130
	v_and_or_b32 v130, v170, s53, v134
	v_add_u32_e32 v134, s42, v147
	v_and_or_b32 v133, v133, s53, v131
	v_and_or_b32 v131, v169, s53, v135
	v_ashrrev_i32_e32 v137, 31, v134
	v_mad_u64_u32 v[134:135], s[24:25], v134, s43, 0
	v_mov_b32_e32 v136, v135
	v_mad_u64_u32 v[136:137], s[24:25], v137, s43, v[136:137]
	v_mov_b32_e32 v135, v136
	v_lshl_add_u64 v[134:135], v[134:135], 1, s[16:17]
	v_lshl_add_u64 v[134:135], v[134:135], 0, s[8:9]
	v_lshl_add_u64 v[134:135], v[134:135], 0, v[142:143]
	global_store_dwordx4 v[134:135], v[130:133], off
	s_waitcnt lgkmcnt(0)
	s_add_i32 s3, s3, s40
	s_mov_b32 s92, s2
	s_cmp_gt_i32 s3, 0x1549f
	s_mov_b64 s[8:9], 0
	s_cbranch_scc1 .LBB0_357
	s_add_i32 s7, s3, s46
	s_cmp_lt_i32 s7, 0x154a0
	s_cselect_b32 s7, s7, s3
	s_cmp_lt_i32 s7, 0x8080
	s_cbranch_scc1 .LBB0_418
	s_cmpk_lt_u32 s7, 0xa080
	s_cbranch_scc1 .LBB0_419
	s_cmp_lt_u32 s7, 0x14c80
	s_cselect_b64 s[8:9], -1, 0
	s_add_i32 s12, s7, 0xfffe1580
	s_cmpk_lt_u32 s12, 0xac00
	s_cselect_b64 s[12:13], -1, 0
	s_or_b64 s[8:9], s[8:9], s[12:13]
	s_mov_b64 s[30:31], -1
	s_and_b64 vcc, exec, s[8:9]
	s_cbranch_vccnz .LBB0_415
	s_add_i32 s8, s7, 0xfffd6980
	s_cmp_lt_u32 s8, 0xffff0c00
	s_cbranch_scc1 .LBB0_412
	s_cmp_lt_u32 s7, 0x1ca80
	s_mov_b64 s[8:9], -1
	s_cbranch_scc1 .LBB0_410
	s_add_i32 s8, s7, 0xfffe3580
	v_readlane_b32 s56, v250, 18
	s_lshl_b32 s9, s7, 5
	s_lshr_b32 s8, s8, 1
	v_readlane_b32 s64, v250, 26
	v_readlane_b32 s65, v250, 27
	s_and_b32 s42, s9, 0xfe0
	s_and_b32 s12, s8, 0x7fffffc0
	s_mov_b64 s[8:9], 0
	s_mov_b64 s[92:93], s[64:65]
	v_readlane_b32 s57, v250, 19
	v_readlane_b32 s58, v250, 20
	v_readlane_b32 s59, v250, 21
	v_readlane_b32 s60, v250, 22
	v_readlane_b32 s61, v250, 23
	v_readlane_b32 s62, v250, 24
	v_readlane_b32 s63, v250, 25
	v_readlane_b32 s66, v250, 28
	v_readlane_b32 s67, v250, 29
	v_readlane_b32 s68, v250, 30
	v_readlane_b32 s69, v250, 31
	v_readlane_b32 s70, v250, 32
	v_readlane_b32 s71, v250, 33

.LBB0_426:
	ds_read2_b32 v[136:137], v152 offset1:8
	ds_read2_b32 v[174:175], v152 offset0:66 offset1:74
	ds_read2_b32 v[176:177], v152 offset0:33 offset1:41
	ds_read2_b32 v[178:179], v152 offset0:99 offset1:107
	ds_read2_b32 v[180:181], v152 offset0:132 offset1:140
	ds_read2_b32 v[182:183], v152 offset0:198 offset1:206
	ds_read2_b32 v[184:185], v152 offset0:165 offset1:173
	ds_read2_b32 v[186:187], v152 offset0:231 offset1:239
	s_waitcnt lgkmcnt(7)
	v_mov_b32_e32 v170, v136
	s_waitcnt lgkmcnt(5)
	v_mov_b32_e32 v172, v176
	s_waitcnt lgkmcnt(4)
	v_mov_b32_e32 v173, v178
	s_waitcnt lgkmcnt(3)
	v_mov_b32_e32 v188, v180
	s_waitcnt lgkmcnt(2)
	v_mov_b32_e32 v189, v182
	v_mov_b32_e32 v171, v174
	v_pk_mul_f32 v[172:173], v[132:133], v[172:173]
	v_pk_mul_f32 v[188:189], v[130:131], v[188:189]
	s_waitcnt lgkmcnt(1)
	v_mov_b32_e32 v190, v184
	s_waitcnt lgkmcnt(0)
	v_mov_b32_e32 v191, v186
	v_pk_mul_f32 v[170:171], v[134:135], v[170:171]
	v_pk_mul_f32 v[190:191], v[144:145], v[190:191]
	v_mov_b32_e32 v169, v173
	v_mov_b32_e32 v178, v189
	v_mov_b32_e32 v136, v191
	v_mov_b32_e32 v173, v178
	v_mov_b32_e32 v174, v172
	v_mov_b32_e32 v176, v188
	v_cvt_pk_bf16_f32 v173, v173, v136
	v_add_u32_e32 v136, s44, v1
	v_mov_b32_e32 v143, v190
	v_mov_b32_e32 v172, v176
	v_mad_u64_u32 v[188:189], s[8:9], v136, s45, 0
	v_cvt_pk_bf16_f32 v172, v172, v143
	v_ashrrev_i32_e32 v143, 31, v136
	v_mov_b32_e32 v136, v189
	v_mad_u64_u32 v[190:191], s[8:9], v143, s45, v[136:137]
	v_mov_b32_e32 v189, v190
	v_lshl_add_u64 v[188:189], v[188:189], 1, s[22:23]
	s_lshl_b64 s[8:9], s[18:19], 1
	v_cvt_pk_bf16_f32 v170, v170, v174
	v_lshl_add_u64 v[188:189], v[188:189], 0, s[8:9]
	v_mov_b32_e32 v143, v139
	v_mov_b32_e32 v174, v137
	v_mov_b32_e32 v186, v185
	v_cvt_pk_bf16_f32 v171, v171, v169
	v_lshl_add_u64 v[188:189], v[188:189], 0, v[142:143]
	v_pk_mul_f32 v[136:137], v[134:135], v[174:175]
	v_mov_b32_e32 v178, v177
	v_pk_mul_f32 v[174:175], v[144:145], v[186:187]
	global_store_dwordx4 v[188:189], v[170:173], off
	v_mov_b32_e32 v182, v181
	s_nop 0
	v_pk_mul_f32 v[170:171], v[132:133], v[178:179]
	v_pk_mul_f32 v[172:173], v[130:131], v[182:183]
	v_bfe_u32 v178, v170, 16, 1
	v_mov_b32_e32 v169, v175
	v_bfe_u32 v175, v136, 16, 1
	v_add3_u32 v170, v170, v178, s52
	v_add3_u32 v136, v136, v175, s52
	v_lshrrev_b32_e32 v136, 16, v136
	v_and_or_b32 v170, v170, s53, v136
	v_add_u32_e32 v136, s44, v141
	v_cvt_pk_bf16_f32 v173, v173, v169
	v_cvt_pk_bf16_f32 v171, v137, v171
	v_ashrrev_i32_e32 v169, 31, v136
	v_mad_u64_u32 v[136:137], s[24:25], v136, s45, 0
	v_cvt_pk_bf16_f32 v172, v172, v174
	v_mov_b32_e32 v174, v137
	v_mad_u64_u32 v[174:175], s[24:25], v169, s45, v[174:175]
	v_mov_b32_e32 v137, v174
	v_lshl_add_u64 v[136:137], v[136:137], 1, s[22:23]
	v_lshl_add_u64 v[136:137], v[136:137], 0, s[8:9]
	v_lshl_add_u64 v[136:137], v[136:137], 0, v[142:143]
	ds_read2_b32 v[174:175], v152 offset0:16 offset1:24
	ds_read2_b32 v[176:177], v152 offset0:82 offset1:90
	global_store_dwordx4 v[136:137], v[170:173], off
	ds_read2_b32 v[136:137], v152 offset0:49 offset1:57
	ds_read2_b32 v[178:179], v152 offset0:115 offset1:123
	ds_read2_b32 v[180:181], v152 offset0:148 offset1:156
	ds_read2_b32 v[182:183], v152 offset0:214 offset1:222
	ds_read2_b32 v[184:185], v152 offset0:181 offset1:189
	ds_read2_b32 v[186:187], v152 offset0:247 offset1:255
	s_waitcnt lgkmcnt(7)
	v_mov_b32_e32 v170, v174
	s_waitcnt lgkmcnt(5)
	v_mov_b32_e32 v172, v136
	s_waitcnt lgkmcnt(4)
	v_mov_b32_e32 v173, v178
	s_waitcnt lgkmcnt(3)
	v_mov_b32_e32 v188, v180
	s_waitcnt lgkmcnt(2)
	v_mov_b32_e32 v189, v182
	v_mov_b32_e32 v171, v176
	v_pk_mul_f32 v[172:173], v[132:133], v[172:173]
	v_pk_mul_f32 v[188:189], v[130:131], v[188:189]
	s_waitcnt lgkmcnt(1)
	v_mov_b32_e32 v190, v184
	s_waitcnt lgkmcnt(0)
	v_mov_b32_e32 v191, v186
	v_pk_mul_f32 v[170:171], v[134:135], v[170:171]
	v_pk_mul_f32 v[190:191], v[144:145], v[190:191]
	v_bfe_u32 v174, v173, 16, 1
	v_bfe_u32 v180, v189, 16, 1
	v_bfe_u32 v136, v191, 16, 1
	v_add3_u32 v174, v173, v174, s52
	v_bfe_u32 v173, v171, 16, 1
	v_add3_u32 v180, v189, v180, s52
	v_add3_u32 v136, v191, v136, s52
	v_add3_u32 v171, v171, v173, s52
	v_lshrrev_b32_e32 v173, 16, v180
	v_mov_b32_e32 v176, v172
	v_mov_b32_e32 v178, v188
	v_and_or_b32 v173, v136, s53, v173
	v_add_u32_e32 v136, s44, v146
	v_mov_b32_e32 v169, v190
	v_mov_b32_e32 v172, v178
	v_mad_u64_u32 v[188:189], s[24:25], v136, s45, 0
	v_cvt_pk_bf16_f32 v172, v172, v169
	v_ashrrev_i32_e32 v169, 31, v136
	v_mov_b32_e32 v136, v189
	v_mad_u64_u32 v[190:191], s[24:25], v169, s45, v[136:137]
	v_mov_b32_e32 v189, v190
	v_lshl_add_u64 v[188:189], v[188:189], 1, s[22:23]
	v_lshrrev_b32_e32 v171, 16, v171
	v_lshl_add_u64 v[188:189], v[188:189], 0, s[8:9]
	v_mov_b32_e32 v178, v137
	v_mov_b32_e32 v186, v185
	v_and_or_b32 v171, v174, s53, v171
	v_cvt_pk_bf16_f32 v170, v170, v176
	v_lshl_add_u64 v[188:189], v[188:189], 0, v[142:143]
	v_mov_b32_e32 v176, v175
	v_pk_mul_f32 v[132:133], v[132:133], v[178:179]
	v_mov_b32_e32 v182, v181
	v_pk_mul_f32 v[136:137], v[144:145], v[186:187]
	global_store_dwordx4 v[188:189], v[170:173], off
	v_pk_mul_f32 v[134:135], v[134:135], v[176:177]
	v_pk_mul_f32 v[130:131], v[130:131], v[182:183]
	v_bfe_u32 v144, v137, 16, 1
	v_bfe_u32 v145, v136, 16, 1
	v_bfe_u32 v169, v133, 16, 1
	v_bfe_u32 v170, v132, 16, 1
	v_add3_u32 v170, v132, v170, s52
	v_add3_u32 v169, v133, v169, s52
	v_add3_u32 v132, v136, v145, s52
	v_add3_u32 v133, v137, v144, s52
	v_bfe_u32 v136, v134, 16, 1
	v_bfe_u32 v144, v130, 16, 1
	v_bfe_u32 v137, v135, 16, 1
	v_bfe_u32 v145, v131, 16, 1
	v_add3_u32 v130, v130, v144, s52
	v_add3_u32 v134, v134, v136, s52
	v_add3_u32 v131, v131, v145, s52
	v_add3_u32 v135, v135, v137, s52
	v_lshrrev_b32_e32 v134, 16, v134
	v_lshrrev_b32_e32 v130, 16, v130
	v_lshrrev_b32_e32 v135, 16, v135
	v_lshrrev_b32_e32 v131, 16, v131
	v_and_or_b32 v132, v132, s53, v130
	v_and_or_b32 v130, v170, s53, v134
	v_add_u32_e32 v134, s44, v147
	v_and_or_b32 v133, v133, s53, v131
	v_and_or_b32 v131, v169, s53, v135
	v_ashrrev_i32_e32 v137, 31, v134
	v_mad_u64_u32 v[134:135], s[24:25], v134, s45, 0
	v_mov_b32_e32 v136, v135
	v_mad_u64_u32 v[136:137], s[24:25], v137, s45, v[136:137]
	v_mov_b32_e32 v135, v136
	v_lshl_add_u64 v[134:135], v[134:135], 1, s[22:23]
	v_lshl_add_u64 v[134:135], v[134:135], 0, s[8:9]
	v_lshl_add_u64 v[134:135], v[134:135], 0, v[142:143]
	global_store_dwordx4 v[134:135], v[130:133], off
	s_waitcnt lgkmcnt(0)
	s_add_i32 s3, s3, s40
	s_mov_b32 s92, s2
	s_cmp_gt_i32 s3, 0x1549f
	s_mov_b64 s[8:9], 0
	s_cbranch_scc1 .LBB0_357
	s_add_i32 s7, s3, s46
	s_cmp_lt_i32 s7, 0x154a0
	s_cselect_b32 s7, s7, s3
	s_cmp_lt_i32 s7, 0x8080
	s_cbranch_scc1 .LBB0_441
	s_cmpk_lt_u32 s7, 0xa080
	s_cbranch_scc1 .LBB0_442
	s_cmp_lt_u32 s7, 0x14c80
	s_cselect_b64 s[8:9], -1, 0
	s_add_i32 s13, s7, 0xfffe1580
	s_cmpk_lt_u32 s13, 0xac00
	s_cselect_b64 s[18:19], -1, 0
	s_or_b64 s[8:9], s[8:9], s[18:19]
	s_mov_b64 s[30:31], -1
	s_and_b64 vcc, exec, s[8:9]
	s_cbranch_vccnz .LBB0_438
	s_add_i32 s8, s7, 0xfffd6980
	s_cmp_lt_u32 s8, 0xffff0c00
	s_cbranch_scc1 .LBB0_435
	s_cmp_lt_u32 s7, 0x1ca80
	s_mov_b64 s[8:9], -1
	s_cbranch_scc1 .LBB0_433
	s_add_i32 s8, s7, 0xfffe3580
	v_readlane_b32 s56, v250, 18
	s_lshl_b32 s9, s7, 5
	s_lshr_b32 s8, s8, 1
	v_readlane_b32 s64, v250, 26
	v_readlane_b32 s65, v250, 27
	s_and_b32 s44, s9, 0xfe0
	s_and_b32 s18, s8, 0x7fffffc0
	s_mov_b64 s[8:9], 0
	s_mov_b64 s[92:93], s[64:65]
	v_readlane_b32 s57, v250, 19
	v_readlane_b32 s58, v250, 20
	v_readlane_b32 s59, v250, 21
	v_readlane_b32 s60, v250, 22
	v_readlane_b32 s61, v250, 23
	v_readlane_b32 s62, v250, 24
	v_readlane_b32 s63, v250, 25
	v_readlane_b32 s66, v250, 28
	v_readlane_b32 s67, v250, 29
	v_readlane_b32 s68, v250, 30
	v_readlane_b32 s69, v250, 31
	v_readlane_b32 s70, v250, 32
	v_readlane_b32 s71, v250, 33

.LBB0_1096:
	global_load_dwordx4 v[78:81], v[82:83], off offset:-3072
	global_load_dwordx4 v[74:77], v[82:83], off offset:-2048
	global_load_dwordx4 v[70:73], v[82:83], off offset:-1024
	global_load_dwordx4 v[66:69], v[82:83], off
	v_add_co_u32_e32 v88, vcc, 0xfffff000, v82
	v_add_co_u32_e64 v84, s[6:7], s14, v82
	s_nop 0
	v_addc_co_u32_e32 v89, vcc, -1, v83, vcc
	global_load_dwordx4 v[98:101], v[88:89], off offset:-3072
	global_load_dwordx4 v[102:105], v[88:89], off offset:-2048
	global_load_dwordx4 v[106:109], v[88:89], off offset:-1024
	global_load_dwordx4 v[110:113], v[82:83], off offset:-4096
	v_addc_co_u32_e64 v85, s[6:7], -1, v83, s[6:7]
	v_add_co_u32_e64 v86, s[6:7], s15, v82
	s_add_i32 s16, s16, s92
	s_nop 0
	v_addc_co_u32_e64 v87, s[6:7], -1, v83, s[6:7]
	s_cmpk_gt_i32 s16, 0x1fff
	v_lshl_add_u64 v[82:83], v[82:83], 0, s[8:9]
	s_waitcnt vmcnt(7)
	v_lshlrev_b32_e32 v89, 16, v80
	v_lshlrev_b32_e32 v88, 16, v78
	v_and_b32_e32 v115, 0xffff0000, v80
	v_and_b32_e32 v114, 0xffff0000, v78
	v_lshlrev_b32_e32 v117, 16, v81
	v_lshlrev_b32_e32 v116, 16, v79
	v_and_b32_e32 v81, 0xffff0000, v81
	v_and_b32_e32 v80, 0xffff0000, v79
	s_waitcnt vmcnt(6)
	v_lshlrev_b32_e32 v79, 16, v75
	v_lshlrev_b32_e32 v78, 16, v74
	v_and_b32_e32 v75, 0xffff0000, v75
	v_and_b32_e32 v74, 0xffff0000, v74
	v_lshlrev_b32_e32 v119, 16, v77
	v_lshlrev_b32_e32 v118, 16, v76
	v_and_b32_e32 v77, 0xffff0000, v77
	v_and_b32_e32 v76, 0xffff0000, v76
	s_waitcnt vmcnt(5)
	v_lshlrev_b32_e32 v120, 16, v70
	v_and_b32_e32 v121, 0xffff0000, v70
	v_lshlrev_b32_e32 v70, 16, v71
	v_and_b32_e32 v71, 0xffff0000, v71
	v_lshlrev_b32_e32 v122, 16, v72
	v_and_b32_e32 v123, 0xffff0000, v72
	v_lshlrev_b32_e32 v72, 16, v73
	v_and_b32_e32 v73, 0xffff0000, v73
	s_waitcnt vmcnt(4)
	v_lshlrev_b32_e32 v126, 16, v68
	v_and_b32_e32 v127, 0xffff0000, v68
	v_lshlrev_b32_e32 v68, 16, v69
	v_and_b32_e32 v69, 0xffff0000, v69
	v_pk_mul_f32 v[128:129], v[114:115], v[114:115]
	v_pk_mul_f32 v[130:131], v[80:81], v[80:81]
	v_pk_mul_f32 v[132:133], v[74:75], v[74:75]
	v_pk_mul_f32 v[134:135], v[76:77], v[76:77]
	v_mul_f32_e32 v136, v121, v121
	v_mul_f32_e32 v138, v71, v71
	v_mul_f32_e32 v140, v123, v123
	v_mul_f32_e32 v142, v73, v73
	s_waitcnt vmcnt(3)
	v_lshlrev_b32_e32 v153, 16, v99
	v_lshlrev_b32_e32 v152, 16, v98
	v_and_b32_e32 v99, 0xffff0000, v99
	v_and_b32_e32 v98, 0xffff0000, v98
	v_lshlrev_b32_e32 v155, 16, v101
	v_lshlrev_b32_e32 v154, 16, v100
	v_and_b32_e32 v101, 0xffff0000, v101
	v_and_b32_e32 v100, 0xffff0000, v100
	s_waitcnt vmcnt(2)
	v_lshlrev_b32_e32 v157, 16, v103
	v_lshlrev_b32_e32 v156, 16, v102
	v_and_b32_e32 v103, 0xffff0000, v103
	v_and_b32_e32 v102, 0xffff0000, v102
	v_lshlrev_b32_e32 v159, 16, v105
	v_lshlrev_b32_e32 v158, 16, v104
	v_and_b32_e32 v105, 0xffff0000, v105
	v_and_b32_e32 v104, 0xffff0000, v104
	v_lshlrev_b32_e32 v124, 16, v66
	v_and_b32_e32 v125, 0xffff0000, v66
	v_mul_f32_e32 v180, v126, v126
	v_mul_f32_e32 v181, v127, v127
	v_mul_f32_e32 v182, v68, v68
	v_mul_f32_e32 v183, v69, v69
	v_mov_b32_e32 v144, v88
	v_mov_b32_e32 v145, v114
	v_mov_b32_e32 v146, v116
	v_mov_b32_e32 v147, v80
	v_mov_b32_e32 v114, v89
	v_mov_b32_e32 v80, v117
	v_mov_b32_e32 v148, v78
	v_mov_b32_e32 v149, v74
	v_mov_b32_e32 v74, v79
	v_mov_b32_e32 v150, v118
	v_mov_b32_e32 v151, v76
	v_mov_b32_e32 v76, v119
	s_waitcnt vmcnt(1)
	v_lshlrev_b32_e32 v160, 16, v106
	v_and_b32_e32 v161, 0xffff0000, v106
	v_lshlrev_b32_e32 v106, 16, v107
	v_and_b32_e32 v107, 0xffff0000, v107
	v_lshlrev_b32_e32 v168, 16, v108
	v_and_b32_e32 v169, 0xffff0000, v108
	v_lshlrev_b32_e32 v108, 16, v109
	v_and_b32_e32 v109, 0xffff0000, v109
	v_pk_fma_f32 v[88:89], v[88:89], v[88:89], v[128:129]
	v_pk_fma_f32 v[116:117], v[116:117], v[116:117], v[130:131]
	v_pk_fma_f32 v[78:79], v[78:79], v[78:79], v[132:133]
	v_pk_fma_f32 v[118:119], v[118:119], v[118:119], v[134:135]
	v_pk_fma_f32 v[128:129], v[120:121], v[120:121], v[136:137] op_sel_hi:[1,1,0]
	v_pk_fma_f32 v[130:131], v[70:71], v[70:71], v[138:139] op_sel_hi:[1,1,0]
	v_pk_fma_f32 v[132:133], v[122:123], v[122:123], v[140:141] op_sel_hi:[1,1,0]
	v_pk_fma_f32 v[134:135], v[72:73], v[72:73], v[142:143] op_sel_hi:[1,1,0]
	v_pk_mul_f32 v[136:137], v[98:99], v[98:99]
	v_pk_mul_f32 v[138:139], v[100:101], v[100:101]
	v_pk_mul_f32 v[140:141], v[102:103], v[102:103]
	v_pk_mul_f32 v[142:143], v[104:105], v[104:105]
	v_lshlrev_b32_e32 v66, 16, v67
	v_and_b32_e32 v67, 0xffff0000, v67
	v_mul_f32_e32 v177, v124, v124
	v_mul_f32_e32 v179, v125, v125
	s_waitcnt vmcnt(0)
	v_lshlrev_b32_e32 v170, 16, v110
	v_and_b32_e32 v171, 0xffff0000, v110
	v_lshlrev_b32_e32 v110, 16, v111
	v_and_b32_e32 v111, 0xffff0000, v111
	v_lshlrev_b32_e32 v172, 16, v112
	v_and_b32_e32 v173, 0xffff0000, v112
	v_lshlrev_b32_e32 v112, 16, v113
	v_and_b32_e32 v113, 0xffff0000, v113
	v_mul_f32_e32 v166, v161, v161
	v_mul_f32_e32 v174, v107, v107
	v_mul_f32_e32 v176, v169, v169
	v_mul_f32_e32 v178, v109, v109
	v_mov_b32_e32 v129, v180
	v_mov_b32_e32 v131, v181
	v_mov_b32_e32 v133, v182
	v_mov_b32_e32 v135, v183
	v_pk_fma_f32 v[136:137], v[152:153], v[152:153], v[136:137]
	v_pk_fma_f32 v[138:139], v[154:155], v[154:155], v[138:139]
	v_pk_fma_f32 v[140:141], v[156:157], v[156:157], v[140:141]
	v_pk_fma_f32 v[142:143], v[158:159], v[158:159], v[142:143]
	v_mul_f32_e32 v186, v66, v66
	v_mul_f32_e32 v187, v67, v67
	v_mul_f32_e32 v188, v170, v170
	v_mul_f32_e32 v189, v171, v171
	v_mul_f32_e32 v190, v110, v110
	v_mul_f32_e32 v191, v111, v111
	v_mul_f32_e32 v192, v172, v172
	v_mul_f32_e32 v193, v173, v173
	v_mul_f32_e32 v194, v112, v112
	v_mul_f32_e32 v195, v113, v113
	v_pk_add_f32 v[88:89], v[88:89], v[116:117]
	v_pk_add_f32 v[78:79], v[78:79], v[78:79] op_sel:[0,1] op_sel_hi:[1,0]
	v_pk_add_f32 v[116:117], v[118:119], v[118:119] op_sel:[0,1] op_sel_hi:[1,0]
	v_mov_b32_e32 v118, v152
	v_mov_b32_e32 v119, v98
	v_mov_b32_e32 v98, v153
	v_mov_b32_e32 v180, v154
	v_mov_b32_e32 v181, v100
	v_mov_b32_e32 v100, v155
	v_mov_b32_e32 v182, v156
	v_mov_b32_e32 v183, v102
	v_mov_b32_e32 v102, v157
	v_mov_b32_e32 v184, v158
	v_mov_b32_e32 v185, v104
	v_mov_b32_e32 v104, v159
	v_pk_fma_f32 v[152:153], v[160:161], v[160:161], v[166:167] op_sel_hi:[1,1,0]
	v_pk_fma_f32 v[154:155], v[106:107], v[106:107], v[174:175] op_sel_hi:[1,1,0]
	v_pk_fma_f32 v[156:157], v[168:169], v[168:169], v[176:177] op_sel_hi:[1,1,0]
	v_pk_fma_f32 v[158:159], v[108:109], v[108:109], v[178:179] op_sel_hi:[1,1,0]
	v_pk_add_f32 v[128:129], v[128:129], v[130:131]
	v_pk_add_f32 v[130:131], v[132:133], v[134:135]
	v_pk_add_f32 v[132:133], v[136:137], v[136:137] op_sel:[0,1] op_sel_hi:[1,0]
	v_pk_add_f32 v[134:135], v[138:139], v[138:139] op_sel:[0,1] op_sel_hi:[1,0]
	v_pk_add_f32 v[136:137], v[140:141], v[140:141] op_sel:[0,1] op_sel_hi:[1,0]
	v_pk_add_f32 v[138:139], v[142:143], v[142:143] op_sel:[0,1] op_sel_hi:[1,0]
	v_mov_b32_e32 v79, v186
	v_mov_b32_e32 v117, v187
	v_mov_b32_e32 v153, v192
	v_mov_b32_e32 v155, v193
	v_mov_b32_e32 v157, v194
	v_mov_b32_e32 v159, v195
	v_mov_b32_e32 v133, v188
	v_mov_b32_e32 v135, v189
	v_mov_b32_e32 v137, v190
	v_mov_b32_e32 v139, v191
	v_pk_add_f32 v[78:79], v[78:79], v[116:117]
	v_pk_add_f32 v[116:117], v[128:129], v[130:131]
	v_pk_add_f32 v[128:129], v[152:153], v[154:155]
	v_pk_add_f32 v[130:131], v[156:157], v[158:159]
	v_pk_add_f32 v[132:133], v[132:133], v[134:135]
	v_pk_add_f32 v[134:135], v[136:137], v[138:139]
	v_pk_add_f32 v[128:129], v[128:129], v[130:131]
	v_pk_add_f32 v[130:131], v[132:133], v[134:135]
	v_pk_add_f32 v[88:89], v[88:89], v[88:89] op_sel:[0,1] op_sel_hi:[1,0]
	v_pk_add_f32 v[128:129], v[130:131], v[128:129]
	v_mov_b32_e32 v89, v179
	v_pk_add_f32 v[128:129], v[128:129], v[128:129] op_sel:[0,1] op_sel_hi:[1,0]
	s_nop 0
	v_mov_b32_e32 v129, v177
	v_pk_add_f32 v[88:89], v[128:129], v[88:89]
	s_nop 0
	v_pk_add_f32 v[78:79], v[88:89], v[78:79]
	s_nop 0
	v_pk_add_f32 v[78:79], v[78:79], v[116:117]
	s_nop 0
	v_add_f32_e32 v78, v78, v79
	ds_bpermute_b32 v79, v90, v78
	s_waitcnt lgkmcnt(0)
	v_add_f32_e32 v78, v78, v79
	ds_bpermute_b32 v79, v91, v78
	s_waitcnt lgkmcnt(0)
	v_add_f32_e32 v78, v78, v79
	ds_bpermute_b32 v79, v92, v78
	s_waitcnt lgkmcnt(0)
	v_add_f32_e32 v78, v78, v79
	ds_bpermute_b32 v79, v93, v78
	s_waitcnt lgkmcnt(0)
	v_add_f32_e32 v78, v78, v79
	ds_bpermute_b32 v79, v94, v78
	s_waitcnt lgkmcnt(0)
	v_add_f32_e32 v78, v78, v79
	ds_bpermute_b32 v79, v95, v78
	s_waitcnt lgkmcnt(0)
	v_add_f32_e32 v78, v78, v79
	v_fmamk_f32 v78, v78, 0x39800000, v96
	v_mul_f32_e32 v79, 0x4f800000, v78
	v_cmp_gt_f32_e32 vcc, s12, v78
	s_nop 1
	v_cndmask_b32_e32 v78, v78, v79, vcc
	v_sqrt_f32_e32 v79, v78
	s_nop 0
	v_add_u32_e32 v88, -1, v79
	v_add_u32_e32 v89, 1, v79
	v_fma_f32 v116, -v88, v79, v78
	v_fma_f32 v117, -v89, v79, v78
	v_cmp_ge_f32_e64 s[6:7], 0, v116
	s_nop 1
	v_cndmask_b32_e64 v79, v79, v88, s[6:7]
	v_cmp_lt_f32_e64 s[6:7], 0, v117
	s_nop 1
	v_cndmask_b32_e64 v79, v79, v89, s[6:7]
	v_mul_f32_e32 v88, 0x37800000, v79
	v_cndmask_b32_e32 v79, v79, v88, vcc
	v_cmp_class_f32_e32 vcc, v78, v97
	s_nop 1
	v_cndmask_b32_e32 v78, v79, v78, vcc
	v_div_scale_f32 v79, s[6:7], v78, v78, 1.0
	v_rcp_f32_e32 v89, v79
	v_div_scale_f32 v88, vcc, 1.0, v78, 1.0
	v_fma_f32 v116, -v79, v89, 1.0
	v_fmac_f32_e32 v89, v116, v89
	v_mul_f32_e32 v116, v88, v89
	v_fma_f32 v117, -v79, v116, v88
	v_fmac_f32_e32 v116, v117, v89
	v_fma_f32 v79, -v79, v116, v88
	v_div_fmas_f32 v79, v79, v89, v116
	v_div_fixup_f32 v78, v79, v78, 1.0
	v_pk_mul_f32 v[88:89], v[78:79], v[118:119] op_sel_hi:[0,1]
	v_pk_mul_f32 v[98:99], v[78:79], v[98:99] op_sel_hi:[0,1]
	v_pk_mul_f32 v[116:117], v[78:79], v[180:181] op_sel_hi:[0,1]
	v_pk_mul_f32 v[100:101], v[78:79], v[100:101] op_sel_hi:[0,1]
	v_pk_mul_f32 v[118:119], v[78:79], v[182:183] op_sel_hi:[0,1]
	v_pk_mul_f32 v[102:103], v[78:79], v[102:103] op_sel_hi:[0,1]
	v_pk_mul_f32 v[128:129], v[78:79], v[184:185] op_sel_hi:[0,1]
	v_pk_mul_f32 v[104:105], v[78:79], v[104:105] op_sel_hi:[0,1]
	v_pk_mul_f32 v[130:131], v[78:79], v[160:161] op_sel_hi:[0,1]
	v_pk_mul_f32 v[106:107], v[78:79], v[106:107] op_sel_hi:[0,1]
	v_pk_mul_f32 v[132:133], v[78:79], v[168:169] op_sel_hi:[0,1]
	v_pk_mul_f32 v[108:109], v[78:79], v[108:109] op_sel_hi:[0,1]
	v_pk_mul_f32 v[134:135], v[78:79], v[170:171] op_sel_hi:[0,1]
	v_pk_mul_f32 v[110:111], v[78:79], v[110:111] op_sel_hi:[0,1]
	v_pk_mul_f32 v[136:137], v[78:79], v[172:173] op_sel_hi:[0,1]
	v_pk_mul_f32 v[112:113], v[78:79], v[112:113] op_sel_hi:[0,1]
	v_pk_mul_f32 v[138:139], v[78:79], v[144:145] op_sel_hi:[0,1]
	v_pk_mul_f32 v[140:141], v[78:79], v[146:147] op_sel_hi:[0,1]
	v_pk_mul_f32 v[114:115], v[78:79], v[114:115] op_sel_hi:[0,1]
	v_pk_mul_f32 v[80:81], v[78:79], v[80:81] op_sel_hi:[0,1]
	v_pk_mul_f32 v[142:143], v[78:79], v[148:149] op_sel_hi:[0,1]
	v_pk_mul_f32 v[74:75], v[78:79], v[74:75] op_sel_hi:[0,1]
	v_pk_mul_f32 v[144:145], v[78:79], v[150:151] op_sel_hi:[0,1]
	v_pk_mul_f32 v[76:77], v[78:79], v[76:77] op_sel_hi:[0,1]
	v_pk_mul_f32 v[120:121], v[78:79], v[120:121] op_sel_hi:[0,1]
	v_pk_mul_f32 v[70:71], v[78:79], v[70:71] op_sel_hi:[0,1]
	v_pk_mul_f32 v[122:123], v[78:79], v[122:123] op_sel_hi:[0,1]
	v_pk_mul_f32 v[72:73], v[78:79], v[72:73] op_sel_hi:[0,1]
	v_pk_mul_f32 v[124:125], v[78:79], v[124:125] op_sel_hi:[0,1]
	v_pk_mul_f32 v[66:67], v[78:79], v[66:67] op_sel_hi:[0,1]
	v_pk_mul_f32 v[126:127], v[78:79], v[126:127] op_sel_hi:[0,1]
	v_pk_mul_f32 v[68:69], v[78:79], v[68:69] op_sel_hi:[0,1]
	v_pk_mul_f32 v[78:79], v[8:9], v[98:99]
	v_pk_mul_f32 v[88:89], v[6:7], v[88:89]
	v_pk_mul_f32 v[98:99], v[12:13], v[100:101]
	v_pk_mul_f32 v[100:101], v[10:11], v[116:117]
	v_pk_mul_f32 v[102:103], v[4:5], v[102:103]
	v_pk_mul_f32 v[116:117], v[2:3], v[118:119]
	v_pk_mul_f32 v[104:105], v[16:17], v[104:105]
	v_pk_mul_f32 v[118:119], v[14:15], v[128:129]
	v_pk_mul_f32 v[106:107], v[24:25], v[106:107]
	v_pk_mul_f32 v[128:129], v[22:23], v[130:131]
	v_pk_mul_f32 v[108:109], v[28:29], v[108:109]
	v_pk_mul_f32 v[130:131], v[26:27], v[132:133]
	v_pk_mul_f32 v[110:111], v[20:21], v[110:111]
	v_pk_mul_f32 v[132:133], v[18:19], v[134:135]
	v_pk_mul_f32 v[112:113], v[32:33], v[112:113]
	v_pk_mul_f32 v[134:135], v[30:31], v[136:137]
	v_pk_mul_f32 v[136:137], v[40:41], v[140:141]
	v_pk_mul_f32 v[138:139], v[38:39], v[138:139]
	v_pk_mul_f32 v[80:81], v[44:45], v[80:81]
	v_pk_mul_f32 v[114:115], v[42:43], v[114:115]
	v_pk_mul_f32 v[74:75], v[36:37], v[74:75]
	v_pk_mul_f32 v[140:141], v[34:35], v[142:143]
	v_pk_mul_f32 v[76:77], v[48:49], v[76:77]
	v_pk_mul_f32 v[142:143], v[46:47], v[144:145]
	v_pk_mul_f32 v[70:71], v[56:57], v[70:71]
	v_pk_mul_f32 v[120:121], v[54:55], v[120:121]
	v_pk_mul_f32 v[72:73], v[60:61], v[72:73]
	v_pk_mul_f32 v[122:123], v[58:59], v[122:123]
	v_pk_mul_f32 v[66:67], v[52:53], v[66:67]
	v_pk_mul_f32 v[124:125], v[50:51], v[124:125]
	v_pk_mul_f32 v[68:69], v[64:65], v[68:69]
	v_pk_mul_f32 v[126:127], v[62:63], v[126:127]
	v_bfe_u32 v144, v88, 16, 1
	v_bfe_u32 v148, v100, 16, 1
	v_bfe_u32 v145, v89, 16, 1
	v_bfe_u32 v149, v101, 16, 1
	v_bfe_u32 v152, v116, 16, 1
	v_bfe_u32 v156, v118, 16, 1
	v_bfe_u32 v158, v104, 16, 1
	v_bfe_u32 v160, v128, 16, 1
	v_bfe_u32 v166, v106, 16, 1
	v_bfe_u32 v169, v130, 16, 1
	v_bfe_u32 v171, v108, 16, 1
	v_bfe_u32 v173, v132, 16, 1
	v_bfe_u32 v176, v110, 16, 1
	v_bfe_u32 v178, v134, 16, 1
	v_bfe_u32 v180, v112, 16, 1
	v_bfe_u32 v182, v138, 16, 1
	v_bfe_u32 v184, v136, 16, 1
	v_bfe_u32 v186, v114, 16, 1
	v_bfe_u32 v188, v80, 16, 1
	v_bfe_u32 v189, v81, 16, 1
	v_bfe_u32 v190, v140, 16, 1
	v_bfe_u32 v191, v141, 16, 1
	v_bfe_u32 v192, v74, 16, 1
	v_bfe_u32 v193, v75, 16, 1
	v_bfe_u32 v194, v142, 16, 1
	v_bfe_u32 v195, v143, 16, 1
	v_bfe_u32 v196, v76, 16, 1
	v_bfe_u32 v197, v77, 16, 1
	v_bfe_u32 v202, v120, 16, 1
	v_bfe_u32 v203, v121, 16, 1
	v_bfe_u32 v204, v70, 16, 1
	v_bfe_u32 v205, v71, 16, 1
	v_bfe_u32 v206, v122, 16, 1
	v_bfe_u32 v207, v123, 16, 1
	v_bfe_u32 v208, v72, 16, 1
	v_bfe_u32 v209, v73, 16, 1
	v_bfe_u32 v210, v124, 16, 1
	v_bfe_u32 v211, v125, 16, 1
	v_bfe_u32 v212, v66, 16, 1
	v_bfe_u32 v213, v67, 16, 1
	v_bfe_u32 v214, v126, 16, 1
	v_bfe_u32 v215, v127, 16, 1
	v_bfe_u32 v216, v68, 16, 1
	v_bfe_u32 v217, v69, 16, 1
	v_add3_u32 v88, v88, v144, s13
	v_add3_u32 v100, v100, v148, s13
	v_bfe_u32 v153, v117, 16, 1
	v_bfe_u32 v157, v119, 16, 1
	v_bfe_u32 v159, v105, 16, 1
	v_bfe_u32 v161, v129, 16, 1
	v_bfe_u32 v168, v107, 16, 1
	v_bfe_u32 v170, v131, 16, 1
	v_bfe_u32 v172, v109, 16, 1
	v_bfe_u32 v174, v133, 16, 1
	v_bfe_u32 v177, v111, 16, 1
	v_bfe_u32 v179, v135, 16, 1
	v_bfe_u32 v181, v113, 16, 1
	v_bfe_u32 v183, v139, 16, 1
	v_bfe_u32 v185, v137, 16, 1
	v_bfe_u32 v187, v115, 16, 1
	v_add3_u32 v89, v89, v145, s13
	v_add3_u32 v101, v101, v149, s13
	v_add3_u32 v116, v116, v152, s13
	v_add3_u32 v118, v118, v156, s13
	v_add3_u32 v104, v104, v158, s13
	v_add3_u32 v128, v128, v160, s13
	v_add3_u32 v106, v106, v166, s13
	v_add3_u32 v130, v130, v169, s13
	v_add3_u32 v108, v108, v171, s13
	v_add3_u32 v132, v132, v173, s13
	v_add3_u32 v110, v110, v176, s13
	v_add3_u32 v134, v134, v178, s13
	v_add3_u32 v112, v112, v180, s13
	v_add3_u32 v138, v138, v182, s13
	v_add3_u32 v136, v136, v184, s13
	v_add3_u32 v114, v114, v186, s13
	v_add3_u32 v80, v80, v188, s13
	v_add3_u32 v144, v81, v189, s13
	v_add3_u32 v81, v140, v190, s13
	v_add3_u32 v140, v141, v191, s13
	v_add3_u32 v74, v74, v192, s13
	v_add3_u32 v141, v75, v193, s13
	v_add3_u32 v75, v142, v194, s13
	v_add3_u32 v142, v143, v195, s13
	v_add3_u32 v76, v76, v196, s13
	v_add3_u32 v143, v77, v197, s13
	v_add3_u32 v77, v120, v202, s13
	v_add3_u32 v120, v121, v203, s13
	v_add3_u32 v70, v70, v204, s13
	v_add3_u32 v121, v71, v205, s13
	v_add3_u32 v71, v122, v206, s13
	v_add3_u32 v122, v123, v207, s13
	v_add3_u32 v72, v72, v208, s13
	v_add3_u32 v123, v73, v209, s13
	v_add3_u32 v73, v124, v210, s13
	v_add3_u32 v124, v125, v211, s13
	v_add3_u32 v66, v66, v212, s13
	v_add3_u32 v125, v67, v213, s13
	v_add3_u32 v67, v126, v214, s13
	v_add3_u32 v126, v127, v215, s13
	v_add3_u32 v68, v68, v216, s13
	v_add3_u32 v127, v69, v217, s13
	v_lshrrev_b32_e32 v69, 16, v88
	v_lshrrev_b32_e32 v88, 16, v100
	v_add3_u32 v117, v117, v153, s13
	v_add3_u32 v119, v119, v157, s13
	v_add3_u32 v105, v105, v159, s13
	v_add3_u32 v129, v129, v161, s13
	v_add3_u32 v107, v107, v168, s13
	v_add3_u32 v131, v131, v170, s13
	v_add3_u32 v109, v109, v172, s13
	v_add3_u32 v133, v133, v174, s13
	v_add3_u32 v111, v111, v177, s13
	v_add3_u32 v135, v135, v179, s13
	v_add3_u32 v113, v113, v181, s13
	v_add3_u32 v139, v139, v183, s13
	v_add3_u32 v137, v137, v185, s13
	v_add3_u32 v115, v115, v187, s13
	v_lshrrev_b32_e32 v100, 16, v116
	v_lshrrev_b32_e32 v116, 16, v118
	v_lshrrev_b32_e32 v104, 16, v104
	v_lshrrev_b32_e32 v118, 16, v128
	v_lshrrev_b32_e32 v106, 16, v106
	v_lshrrev_b32_e32 v128, 16, v130
	v_lshrrev_b32_e32 v108, 16, v108
	v_lshrrev_b32_e32 v130, 16, v132
	v_lshrrev_b32_e32 v110, 16, v110
	v_lshrrev_b32_e32 v132, 16, v134
	v_lshrrev_b32_e32 v112, 16, v112
	v_lshrrev_b32_e32 v134, 16, v138
	v_lshrrev_b32_e32 v136, 16, v136
	v_lshrrev_b32_e32 v114, 16, v114
	v_lshrrev_b32_e32 v138, 16, v80
	v_lshrrev_b32_e32 v145, 16, v81
	v_lshrrev_b32_e32 v146, 16, v74
	v_lshrrev_b32_e32 v147, 16, v75
	v_lshrrev_b32_e32 v148, 16, v76
	v_lshrrev_b32_e32 v149, 16, v77
	v_lshrrev_b32_e32 v150, 16, v70
	v_lshrrev_b32_e32 v151, 16, v71
	v_lshrrev_b32_e32 v152, 16, v72
	v_lshrrev_b32_e32 v153, 16, v73
	v_lshrrev_b32_e32 v154, 16, v66
	v_lshrrev_b32_e32 v155, 16, v67
	v_lshrrev_b32_e32 v156, 16, v68
	v_and_or_b32 v66, v89, s3, v69
	v_cvt_pk_bf16_f32 v67, v78, v79
	v_and_or_b32 v68, v101, s3, v88
	v_cvt_pk_bf16_f32 v69, v98, v99
	v_and_or_b32 v70, v117, s3, v100
	v_cvt_pk_bf16_f32 v71, v102, v103
	v_and_or_b32 v72, v119, s3, v116
	v_and_or_b32 v73, v105, s3, v104
	v_and_or_b32 v74, v129, s3, v118
	v_and_or_b32 v75, v107, s3, v106
	v_and_or_b32 v76, v131, s3, v128
	v_and_or_b32 v77, v109, s3, v108
	v_and_or_b32 v78, v133, s3, v130
	v_and_or_b32 v79, v111, s3, v110
	v_and_or_b32 v80, v135, s3, v132
	v_and_or_b32 v81, v113, s3, v112
	v_and_or_b32 v98, v139, s3, v134
	v_and_or_b32 v99, v137, s3, v136
	v_and_or_b32 v100, v115, s3, v114
	v_and_or_b32 v101, v144, s3, v138
	v_and_or_b32 v102, v140, s3, v145
	v_and_or_b32 v103, v141, s3, v146
	v_and_or_b32 v104, v142, s3, v147
	v_and_or_b32 v105, v143, s3, v148
	v_and_or_b32 v106, v120, s3, v149
	v_and_or_b32 v107, v121, s3, v150
	v_and_or_b32 v108, v122, s3, v151
	v_and_or_b32 v109, v123, s3, v152
	v_and_or_b32 v110, v124, s3, v153
	v_and_or_b32 v111, v125, s3, v154
	v_and_or_b32 v112, v126, s3, v155
	v_and_or_b32 v113, v127, s3, v156
	global_store_dwordx4 v[84:85], v[66:69], off offset:-3072
	global_store_dwordx4 v[84:85], v[70:73], off offset:-2048
	global_store_dwordx4 v[84:85], v[74:77], off offset:-1024
	global_store_dwordx4 v[86:87], v[78:81], off offset:-4096
	global_store_dwordx4 v[86:87], v[98:101], off offset:-3072
	global_store_dwordx4 v[86:87], v[102:105], off offset:-2048
	global_store_dwordx4 v[86:87], v[106:109], off offset:-1024
	global_store_dwordx4 v[86:87], v[110:113], off
	s_cbranch_scc0 .LBB0_1096

.LBB0_1099:
	s_waitcnt lgkmcnt(1)
	v_add_f32_e32 v22, v22, v23
	v_add_f32_e32 v23, v24, v25
	s_waitcnt lgkmcnt(0)
	v_add_f32_e32 v18, v18, v19
	v_add_f32_e32 v19, v20, v21
	v_add_f32_e32 v22, v22, v23
	v_add_f32_e32 v18, v18, v19
	v_add_f32_e32 v18, v22, v18
	v_fmamk_f32 v18, v18, 0x39800000, v26
	v_mul_f32_e32 v19, 0x4f800000, v18
	v_cmp_gt_f32_e32 vcc, s35, v18
	s_add_i32 s37, s37, s86
	v_lshl_add_u64 v[30:31], v[30:31], 0, s[12:13]
	v_cndmask_b32_e32 v18, v18, v19, vcc
	v_sqrt_f32_e32 v19, v18
	s_cmpk_lt_i32 s37, 0x100
	v_lshl_add_u64 v[34:35], v[34:35], 0, s[14:15]
	v_add_u32_e32 v20, -1, v19
	v_fma_f32 v21, -v20, v19, v18
	v_cmp_ge_f32_e64 s[8:9], 0, v21
	v_add_u32_e32 v21, 1, v19
	s_nop 0
	v_cndmask_b32_e64 v20, v19, v20, s[8:9]
	v_fma_f32 v19, -v21, v19, v18
	v_cmp_lt_f32_e64 s[8:9], 0, v19
	s_nop 1
	v_cndmask_b32_e64 v19, v20, v21, s[8:9]
	v_mul_f32_e32 v20, 0x37800000, v19
	v_cndmask_b32_e32 v19, v19, v20, vcc
	v_cmp_class_f32_e32 vcc, v18, v64
	s_nop 1
	v_cndmask_b32_e32 v18, v19, v18, vcc
	v_div_scale_f32 v19, s[8:9], v18, v18, 1.0
	v_rcp_f32_e32 v20, v19
	s_nop 0
	v_fma_f32 v21, -v19, v20, 1.0
	v_fmac_f32_e32 v20, v21, v20
	v_div_scale_f32 v21, vcc, 1.0, v18, 1.0
	v_mul_f32_e32 v22, v21, v20
	v_fma_f32 v23, -v19, v22, v21
	v_fmac_f32_e32 v22, v23, v20
	v_fma_f32 v19, -v19, v22, v21
	v_div_fmas_f32 v19, v19, v20, v22
	v_div_fixup_f32 v18, v19, v18, 1.0
	v_pk_mul_f32 v[6:7], v[6:7], v[18:19] op_sel_hi:[1,0]
	v_pk_mul_f32 v[2:3], v[2:3], v[18:19] op_sel_hi:[1,0]
	s_waitcnt vmcnt(0)
	v_pk_mul_f32 v[6:7], v[6:7], v[14:15]
	v_pk_mul_f32 v[2:3], v[2:3], v[10:11]
	v_bfe_u32 v10, v6, 16, 1
	v_pk_mul_f32 v[8:9], v[8:9], v[18:19] op_sel_hi:[1,0]
	v_add3_u32 v6, v6, v10, s36
	v_bfe_u32 v10, v7, 16, 1
	v_pk_mul_f32 v[8:9], v[8:9], v[16:17]
	v_lshrrev_b32_e32 v6, 16, v6
	v_add3_u32 v7, v7, v10, s36
	v_and_or_b32 v6, v7, s3, v6
	v_mov_b32_e32 v7, v8
	v_mov_b32_e32 v8, v9
	v_cvt_pk_bf16_f32 v7, v7, v8
	v_bfe_u32 v8, v2, 16, 1
	v_pk_mul_f32 v[4:5], v[4:5], v[18:19] op_sel_hi:[1,0]
	v_add3_u32 v2, v2, v8, s36
	v_bfe_u32 v8, v3, 16, 1
	v_pk_mul_f32 v[4:5], v[4:5], v[12:13]
	v_lshrrev_b32_e32 v2, 16, v2
	v_add3_u32 v3, v3, v8, s36
	v_and_or_b32 v2, v3, s3, v2
	v_mov_b32_e32 v3, v4
	v_mov_b32_e32 v4, v5
	v_cvt_pk_bf16_f32 v3, v3, v4
	v_lshl_add_u64 v[4:5], s[80:81], 0, v[32:33]
	v_add_co_u32_e32 v4, vcc, 0x2ef00000, v4
	v_lshl_add_u64 v[32:33], v[32:33], 0, s[12:13]
	s_nop 0
	v_addc_co_u32_e32 v5, vcc, 0, v5, vcc
	global_store_dwordx2 v[4:5], v[6:7], off
	global_store_dwordx2 v[4:5], v[2:3], off offset:512
	s_cbranch_scc0 .LBB0_1106

.LBB0_1261:
	ds_read2_b32 v[104:105], v153 offset1:8
	ds_read2_b32 v[112:113], v153 offset0:66 offset1:74
	ds_read2_b32 v[114:115], v153 offset0:33 offset1:41
	ds_read2_b32 v[116:117], v153 offset0:99 offset1:107
	ds_read2_b32 v[118:119], v153 offset0:132 offset1:140
	ds_read2_b32 v[120:121], v153 offset0:198 offset1:206
	ds_read2_b32 v[122:123], v153 offset0:165 offset1:173
	ds_read2_b32 v[124:125], v153 offset0:231 offset1:239
	s_waitcnt lgkmcnt(7)
	v_mov_b32_e32 v108, v104
	s_waitcnt lgkmcnt(5)
	v_mov_b32_e32 v110, v114
	s_waitcnt lgkmcnt(4)
	v_mov_b32_e32 v111, v116
	s_waitcnt lgkmcnt(3)
	v_mov_b32_e32 v126, v118
	s_waitcnt lgkmcnt(2)
	v_mov_b32_e32 v127, v120
	v_mov_b32_e32 v109, v112
	v_pk_mul_f32 v[110:111], v[100:101], v[110:111]
	v_pk_mul_f32 v[126:127], v[98:99], v[126:127]
	s_waitcnt lgkmcnt(1)
	v_mov_b32_e32 v128, v122
	s_waitcnt lgkmcnt(0)
	v_mov_b32_e32 v129, v124
	v_pk_mul_f32 v[108:109], v[102:103], v[108:109]
	v_pk_mul_f32 v[128:129], v[106:107], v[128:129]
	v_mov_b32_e32 v114, v111
	v_mov_b32_e32 v120, v127
	v_mov_b32_e32 v116, v110
	v_mov_b32_e32 v110, v128
	v_mov_b32_e32 v104, v129
	v_mov_b32_e32 v118, v126
	v_mov_b32_e32 v111, v120
	v_mov_b32_e32 v112, v118
	v_cvt_pk_bf16_f32 v111, v111, v104
	v_or_b32_e32 v104, s94, v141
	s_ashr_i32 s9, s94, 31
	v_cvt_pk_bf16_f32 v110, v112, v110
	v_mul_lo_u32 v112, s35, v104
	s_mul_i32 s9, s34, s9
	v_mad_u64_u32 v[126:127], s[38:39], s34, v104, 0
	v_add3_u32 v127, v127, s9, v112
	v_lshl_add_u64 v[126:127], v[126:127], 1, s[92:93]
	s_lshl_b64 s[36:37], s[36:37], 1
	v_lshl_add_u64 v[126:127], v[126:127], 0, s[36:37]
	v_mov_b32_e32 v143, v139
	v_mov_b32_e32 v112, v105
	v_mov_b32_e32 v124, v123
	v_cvt_pk_bf16_f32 v109, v109, v114
	v_cvt_pk_bf16_f32 v108, v108, v116
	v_lshl_add_u64 v[126:127], v[126:127], 0, v[142:143]
	v_pk_mul_f32 v[104:105], v[102:103], v[112:113]
	v_mov_b32_e32 v116, v115
	v_pk_mul_f32 v[112:113], v[106:107], v[124:125]
	global_store_dwordx4 v[126:127], v[108:111], off
	v_mov_b32_e32 v120, v119
	s_nop 0
	v_pk_mul_f32 v[108:109], v[100:101], v[116:117]
	v_pk_mul_f32 v[110:111], v[98:99], v[120:121]
	v_cvt_pk_bf16_f32 v108, v104, v108
	v_or_b32_e32 v104, s94, v146
	v_cvt_pk_bf16_f32 v110, v110, v112
	v_cvt_pk_bf16_f32 v109, v105, v109
	v_mul_lo_u32 v112, s35, v104
	v_mad_u64_u32 v[104:105], s[38:39], s34, v104, 0
	v_add3_u32 v105, v105, s9, v112
	v_lshl_add_u64 v[104:105], v[104:105], 1, s[92:93]
	v_lshl_add_u64 v[104:105], v[104:105], 0, s[36:37]
	v_cvt_pk_bf16_f32 v111, v111, v113
	v_lshl_add_u64 v[104:105], v[104:105], 0, v[142:143]
	ds_read2_b32 v[112:113], v153 offset0:16 offset1:24
	ds_read2_b32 v[114:115], v153 offset0:82 offset1:90
	global_store_dwordx4 v[104:105], v[108:111], off
	ds_read2_b32 v[104:105], v153 offset0:49 offset1:57
	ds_read2_b32 v[116:117], v153 offset0:115 offset1:123
	ds_read2_b32 v[118:119], v153 offset0:148 offset1:156
	ds_read2_b32 v[120:121], v153 offset0:214 offset1:222
	ds_read2_b32 v[122:123], v153 offset0:181 offset1:189
	ds_read2_b32 v[124:125], v153 offset0:247 offset1:255
	s_waitcnt lgkmcnt(7)
	v_mov_b32_e32 v108, v112
	s_waitcnt lgkmcnt(5)
	v_mov_b32_e32 v110, v104
	s_waitcnt lgkmcnt(4)
	v_mov_b32_e32 v111, v116
	s_waitcnt lgkmcnt(3)
	v_mov_b32_e32 v126, v118
	s_waitcnt lgkmcnt(2)
	v_mov_b32_e32 v127, v120
	v_mov_b32_e32 v109, v114
	v_pk_mul_f32 v[110:111], v[100:101], v[110:111]
	v_pk_mul_f32 v[126:127], v[98:99], v[126:127]
	s_waitcnt lgkmcnt(1)
	v_mov_b32_e32 v128, v122
	s_waitcnt lgkmcnt(0)
	v_mov_b32_e32 v129, v124
	v_pk_mul_f32 v[108:109], v[102:103], v[108:109]
	v_pk_mul_f32 v[128:129], v[106:107], v[128:129]
	v_bfe_u32 v112, v128, 16, 1
	v_mov_b32_e32 v114, v111
	v_bfe_u32 v118, v126, 16, 1
	v_mov_b32_e32 v120, v127
	v_mov_b32_e32 v116, v110
	v_add3_u32 v110, v128, v112, s54
	v_mov_b32_e32 v104, v129
	v_add3_u32 v118, v126, v118, s54
	v_mov_b32_e32 v111, v120
	v_lshrrev_b32_e32 v112, 16, v118
	v_cvt_pk_bf16_f32 v111, v111, v104
	v_or_b32_e32 v104, s94, v147
	v_and_or_b32 v110, v110, s55, v112
	v_mul_lo_u32 v112, s35, v104
	v_mad_u64_u32 v[126:127], s[38:39], s34, v104, 0
	v_add3_u32 v127, v127, s9, v112
	v_lshl_add_u64 v[126:127], v[126:127], 1, s[92:93]
	v_cvt_pk_bf16_f32 v108, v108, v116
	v_lshl_add_u64 v[126:127], v[126:127], 0, s[36:37]
	v_mov_b32_e32 v116, v105
	v_mov_b32_e32 v124, v123
	v_cvt_pk_bf16_f32 v109, v109, v114
	v_lshl_add_u64 v[126:127], v[126:127], 0, v[142:143]
	v_mov_b32_e32 v114, v113
	v_pk_mul_f32 v[100:101], v[100:101], v[116:117]
	v_mov_b32_e32 v120, v119
	v_pk_mul_f32 v[104:105], v[106:107], v[124:125]
	global_store_dwordx4 v[126:127], v[108:111], off
	v_pk_mul_f32 v[102:103], v[102:103], v[114:115]
	v_pk_mul_f32 v[98:99], v[98:99], v[120:121]
	v_bfe_u32 v106, v105, 16, 1
	v_bfe_u32 v107, v104, 16, 1
	v_bfe_u32 v108, v101, 16, 1
	v_bfe_u32 v109, v100, 16, 1
	v_add3_u32 v109, v100, v109, s54
	v_add3_u32 v108, v101, v108, s54
	v_add3_u32 v100, v104, v107, s54
	v_add3_u32 v101, v105, v106, s54
	v_bfe_u32 v104, v102, 16, 1
	v_bfe_u32 v106, v98, 16, 1
	v_bfe_u32 v105, v103, 16, 1
	v_bfe_u32 v107, v99, 16, 1
	v_add3_u32 v98, v98, v106, s54
	v_add3_u32 v102, v102, v104, s54
	v_add3_u32 v99, v99, v107, s54
	v_add3_u32 v103, v103, v105, s54
	v_lshrrev_b32_e32 v102, 16, v102
	v_lshrrev_b32_e32 v98, 16, v98
	v_lshrrev_b32_e32 v103, 16, v103
	v_lshrrev_b32_e32 v99, 16, v99
	v_and_or_b32 v100, v100, s55, v98
	v_and_or_b32 v98, v109, s55, v102
	v_or_b32_e32 v102, s94, v148
	v_and_or_b32 v101, v101, s55, v99
	v_and_or_b32 v99, v108, s55, v103
	v_mul_lo_u32 v104, s35, v102
	v_mad_u64_u32 v[102:103], s[34:35], s34, v102, 0
	v_add3_u32 v103, v103, s9, v104
	v_lshl_add_u64 v[102:103], v[102:103], 1, s[92:93]
	v_lshl_add_u64 v[102:103], v[102:103], 0, s[36:37]
	v_lshl_add_u64 v[102:103], v[102:103], 0, v[142:143]
	global_store_dwordx4 v[102:103], v[98:101], off
	s_waitcnt lgkmcnt(0)
	s_add_i32 s3, s3, s43
	s_cmp_lt_i32 s3, 0x1f580
	s_cselect_b64 s[60:61], -1, 0

.LBB0_1285:
	ds_read2_b32 v[136:137], v153 offset1:8
	ds_read2_b32 v[180:181], v153 offset0:66 offset1:74
	ds_read2_b32 v[182:183], v153 offset0:33 offset1:41
	ds_read2_b32 v[184:185], v153 offset0:99 offset1:107
	ds_read2_b32 v[186:187], v153 offset0:132 offset1:140
	ds_read2_b32 v[188:189], v153 offset0:198 offset1:206
	ds_read2_b32 v[190:191], v153 offset0:165 offset1:173
	ds_read2_b32 v[192:193], v153 offset0:231 offset1:239
	s_waitcnt lgkmcnt(7)
	v_mov_b32_e32 v176, v136
	s_waitcnt lgkmcnt(5)
	v_mov_b32_e32 v178, v182
	s_waitcnt lgkmcnt(4)
	v_mov_b32_e32 v179, v184
	s_waitcnt lgkmcnt(3)
	v_mov_b32_e32 v194, v186
	s_waitcnt lgkmcnt(2)
	v_mov_b32_e32 v195, v188
	v_mov_b32_e32 v177, v180
	v_pk_mul_f32 v[178:179], v[132:133], v[178:179]
	v_pk_mul_f32 v[194:195], v[130:131], v[194:195]
	s_waitcnt lgkmcnt(1)
	v_mov_b32_e32 v196, v190
	s_waitcnt lgkmcnt(0)
	v_mov_b32_e32 v197, v192
	v_pk_mul_f32 v[176:177], v[134:135], v[176:177]
	v_pk_mul_f32 v[196:197], v[144:145], v[196:197]
	v_mov_b32_e32 v174, v179
	v_mov_b32_e32 v184, v195
	v_mov_b32_e32 v136, v197
	v_mov_b32_e32 v179, v184
	v_mov_b32_e32 v180, v178
	v_mov_b32_e32 v182, v194
	v_cvt_pk_bf16_f32 v179, v179, v136
	v_add_u32_e32 v136, s33, v141
	v_mov_b32_e32 v143, v196
	v_mov_b32_e32 v178, v182
	v_mad_u64_u32 v[194:195], s[40:41], v136, s42, 0
	v_cvt_pk_bf16_f32 v178, v178, v143
	v_ashrrev_i32_e32 v143, 31, v136
	v_mov_b32_e32 v136, v195
	v_mad_u64_u32 v[196:197], s[40:41], v143, s42, v[136:137]
	v_mov_b32_e32 v195, v196
	v_lshl_add_u64 v[194:195], v[194:195], 1, s[12:13]
	s_lshl_b64 s[60:61], s[8:9], 1
	v_cvt_pk_bf16_f32 v176, v176, v180
	v_lshl_add_u64 v[194:195], v[194:195], 0, s[60:61]
	v_mov_b32_e32 v143, v139
	v_mov_b32_e32 v180, v137
	v_mov_b32_e32 v192, v191
	v_cvt_pk_bf16_f32 v177, v177, v174
	v_lshl_add_u64 v[194:195], v[194:195], 0, v[142:143]
	v_pk_mul_f32 v[136:137], v[134:135], v[180:181]
	v_mov_b32_e32 v184, v183
	v_pk_mul_f32 v[180:181], v[144:145], v[192:193]
	global_store_dwordx4 v[194:195], v[176:179], off
	v_mov_b32_e32 v188, v187
	s_nop 0
	v_pk_mul_f32 v[176:177], v[132:133], v[184:185]
	v_pk_mul_f32 v[178:179], v[130:131], v[188:189]
	v_mov_b32_e32 v174, v181
	v_cvt_pk_bf16_f32 v176, v136, v176
	v_add_u32_e32 v136, s33, v146
	v_cvt_pk_bf16_f32 v178, v178, v180
	v_cvt_pk_bf16_f32 v177, v137, v177
	v_ashrrev_i32_e32 v180, 31, v136
	v_mad_u64_u32 v[136:137], s[40:41], v136, s42, 0
	v_cvt_pk_bf16_f32 v179, v179, v174
	v_mov_b32_e32 v174, v137
	v_mad_u64_u32 v[180:181], s[40:41], v180, s42, v[174:175]
	v_mov_b32_e32 v137, v180
	v_lshl_add_u64 v[136:137], v[136:137], 1, s[12:13]
	v_lshl_add_u64 v[136:137], v[136:137], 0, s[60:61]
	v_lshl_add_u64 v[136:137], v[136:137], 0, v[142:143]
	ds_read2_b32 v[180:181], v153 offset0:16 offset1:24
	ds_read2_b32 v[182:183], v153 offset0:82 offset1:90
	global_store_dwordx4 v[136:137], v[176:179], off
	ds_read2_b32 v[136:137], v153 offset0:49 offset1:57
	ds_read2_b32 v[184:185], v153 offset0:115 offset1:123
	ds_read2_b32 v[186:187], v153 offset0:148 offset1:156
	ds_read2_b32 v[188:189], v153 offset0:214 offset1:222
	ds_read2_b32 v[190:191], v153 offset0:181 offset1:189
	ds_read2_b32 v[192:193], v153 offset0:247 offset1:255
	s_waitcnt lgkmcnt(7)
	v_mov_b32_e32 v176, v180
	s_waitcnt lgkmcnt(5)
	v_mov_b32_e32 v178, v136
	s_waitcnt lgkmcnt(4)
	v_mov_b32_e32 v179, v184
	s_waitcnt lgkmcnt(3)
	v_mov_b32_e32 v194, v186
	s_waitcnt lgkmcnt(2)
	v_mov_b32_e32 v195, v188
	v_mov_b32_e32 v177, v182
	v_pk_mul_f32 v[178:179], v[132:133], v[178:179]
	v_pk_mul_f32 v[194:195], v[130:131], v[194:195]
	s_waitcnt lgkmcnt(1)
	v_mov_b32_e32 v196, v190
	s_waitcnt lgkmcnt(0)
	v_mov_b32_e32 v197, v192
	v_pk_mul_f32 v[176:177], v[134:135], v[176:177]
	v_pk_mul_f32 v[196:197], v[144:145], v[196:197]
	v_bfe_u32 v180, v179, 16, 1
	v_bfe_u32 v186, v195, 16, 1
	v_bfe_u32 v136, v197, 16, 1
	v_add3_u32 v180, v179, v180, s54
	v_bfe_u32 v179, v177, 16, 1
	v_add3_u32 v186, v195, v186, s54
	v_add3_u32 v136, v197, v136, s54
	v_add3_u32 v177, v177, v179, s54
	v_lshrrev_b32_e32 v179, 16, v186
	v_mov_b32_e32 v182, v178
	v_mov_b32_e32 v184, v194
	v_and_or_b32 v179, v136, s55, v179
	v_add_u32_e32 v136, s33, v147
	v_mov_b32_e32 v174, v196
	v_mov_b32_e32 v178, v184
	v_mad_u64_u32 v[194:195], s[40:41], v136, s42, 0
	v_cvt_pk_bf16_f32 v178, v178, v174
	v_ashrrev_i32_e32 v174, 31, v136
	v_mov_b32_e32 v136, v195
	v_mad_u64_u32 v[196:197], s[40:41], v174, s42, v[136:137]
	v_mov_b32_e32 v195, v196
	v_lshl_add_u64 v[194:195], v[194:195], 1, s[12:13]
	v_lshrrev_b32_e32 v177, 16, v177
	v_lshl_add_u64 v[194:195], v[194:195], 0, s[60:61]
	v_mov_b32_e32 v184, v137
	v_mov_b32_e32 v192, v191
	v_and_or_b32 v177, v180, s55, v177
	v_cvt_pk_bf16_f32 v176, v176, v182
	v_lshl_add_u64 v[194:195], v[194:195], 0, v[142:143]
	v_mov_b32_e32 v182, v181
	v_pk_mul_f32 v[132:133], v[132:133], v[184:185]
	v_mov_b32_e32 v188, v187
	v_pk_mul_f32 v[136:137], v[144:145], v[192:193]
	global_store_dwordx4 v[194:195], v[176:179], off
	v_pk_mul_f32 v[134:135], v[134:135], v[182:183]
	v_pk_mul_f32 v[130:131], v[130:131], v[188:189]
	v_bfe_u32 v144, v137, 16, 1
	v_bfe_u32 v145, v136, 16, 1
	v_bfe_u32 v174, v133, 16, 1
	v_bfe_u32 v176, v132, 16, 1
	v_add3_u32 v176, v132, v176, s54
	v_add3_u32 v174, v133, v174, s54
	v_add3_u32 v132, v136, v145, s54
	v_add3_u32 v133, v137, v144, s54
	v_bfe_u32 v136, v134, 16, 1
	v_bfe_u32 v144, v130, 16, 1
	v_bfe_u32 v137, v135, 16, 1
	v_bfe_u32 v145, v131, 16, 1
	v_add3_u32 v130, v130, v144, s54
	v_add3_u32 v134, v134, v136, s54
	v_add3_u32 v131, v131, v145, s54
	v_add3_u32 v135, v135, v137, s54
	v_lshrrev_b32_e32 v134, 16, v134
	v_lshrrev_b32_e32 v130, 16, v130
	v_lshrrev_b32_e32 v135, 16, v135
	v_lshrrev_b32_e32 v131, 16, v131
	v_and_or_b32 v132, v132, s55, v130
	v_and_or_b32 v130, v176, s55, v134
	v_add_u32_e32 v134, s33, v148
	v_and_or_b32 v133, v133, s55, v131
	v_and_or_b32 v131, v174, s55, v135
	v_ashrrev_i32_e32 v137, 31, v134
	v_mad_u64_u32 v[134:135], s[40:41], v134, s42, 0
	v_mov_b32_e32 v136, v135
	v_mad_u64_u32 v[136:137], s[40:41], v137, s42, v[136:137]
	v_mov_b32_e32 v135, v136
	v_lshl_add_u64 v[134:135], v[134:135], 1, s[12:13]
	v_lshl_add_u64 v[134:135], v[134:135], 0, s[60:61]
	v_lshl_add_u64 v[134:135], v[134:135], 0, v[142:143]
	global_store_dwordx4 v[134:135], v[130:133], off
	s_waitcnt lgkmcnt(0)
	s_add_i32 s3, s3, s43
	s_cmp_lt_i32 s3, 0x1f580
	s_mov_b64 s[60:61], 0
	s_cbranch_scc0 .LBB0_1262
	s_add_i32 s8, s3, s48
	s_cmp_lt_i32 s8, 0x1f580
	s_cselect_b32 s9, s8, s3
	s_cmp_lt_i32 s9, 0x8080
	s_cbranch_scc1 .LBB0_1300
	s_cmpk_lt_u32 s9, 0xa080
	s_cbranch_scc1 .LBB0_1301
	s_cmp_lt_u32 s9, 0x14c80
	s_cselect_b64 s[10:11], -1, 0
	s_add_i32 s8, s9, 0xfffe1580
	s_cmpk_lt_u32 s8, 0xac00
	s_cselect_b64 s[12:13], -1, 0
	s_or_b64 s[10:11], s[10:11], s[12:13]
	s_mov_b64 s[40:41], -1
	s_and_b64 vcc, exec, s[10:11]
	s_cbranch_vccnz .LBB0_1297
	s_add_i32 s8, s9, 0xfffd6980
	s_cmp_lt_u32 s8, 0xffff0c00
	s_mov_b64 s[72:73], -1
	s_cbranch_scc1 .LBB0_1294
	s_cmp_lt_u32 s9, 0x1ca80
	s_mov_b64 s[10:11], -1
	s_cbranch_scc1 .LBB0_1292
	s_add_i32 s8, s9, 0xfffe3580
	v_readlane_b32 s16, v250, 18
	s_lshl_b32 s10, s9, 5
	s_lshr_b32 s8, s8, 1
	v_readlane_b32 s24, v250, 26
	v_readlane_b32 s25, v250, 27
	s_and_b32 s33, s10, 0xfe0
	s_and_b32 s8, s8, 0x7fffffc0
	s_mov_b64 s[10:11], 0
	s_mov_b64 s[60:61], s[24:25]
	v_readlane_b32 s17, v250, 19
	v_readlane_b32 s18, v250, 20
	v_readlane_b32 s19, v250, 21
	v_readlane_b32 s20, v250, 22
	v_readlane_b32 s21, v250, 23
	v_readlane_b32 s22, v250, 24
	v_readlane_b32 s23, v250, 25
	v_readlane_b32 s26, v250, 28
	v_readlane_b32 s27, v250, 29
	v_readlane_b32 s28, v250, 30
	v_readlane_b32 s29, v250, 31
	v_readlane_b32 s30, v250, 32
	v_readlane_b32 s31, v250, 33

.LBB0_1308:
	ds_read2_b32 v[136:137], v153 offset1:8
	ds_read2_b32 v[180:181], v153 offset0:66 offset1:74
	ds_read2_b32 v[182:183], v153 offset0:33 offset1:41
	ds_read2_b32 v[184:185], v153 offset0:99 offset1:107
	ds_read2_b32 v[186:187], v153 offset0:132 offset1:140
	ds_read2_b32 v[188:189], v153 offset0:198 offset1:206
	ds_read2_b32 v[190:191], v153 offset0:165 offset1:173
	ds_read2_b32 v[192:193], v153 offset0:231 offset1:239
	s_waitcnt lgkmcnt(7)
	v_mov_b32_e32 v176, v136
	s_waitcnt lgkmcnt(5)
	v_mov_b32_e32 v178, v182
	s_waitcnt lgkmcnt(4)
	v_mov_b32_e32 v179, v184
	s_waitcnt lgkmcnt(3)
	v_mov_b32_e32 v194, v186
	s_waitcnt lgkmcnt(2)
	v_mov_b32_e32 v195, v188
	v_mov_b32_e32 v177, v180
	v_pk_mul_f32 v[178:179], v[132:133], v[178:179]
	v_pk_mul_f32 v[194:195], v[130:131], v[194:195]
	s_waitcnt lgkmcnt(1)
	v_mov_b32_e32 v196, v190
	s_waitcnt lgkmcnt(0)
	v_mov_b32_e32 v197, v192
	v_pk_mul_f32 v[176:177], v[134:135], v[176:177]
	v_pk_mul_f32 v[196:197], v[144:145], v[196:197]
	v_mov_b32_e32 v174, v179
	v_mov_b32_e32 v184, v195
	v_mov_b32_e32 v136, v197
	v_mov_b32_e32 v179, v184
	v_mov_b32_e32 v180, v178
	v_mov_b32_e32 v182, v194
	v_cvt_pk_bf16_f32 v179, v179, v136
	v_add_u32_e32 v136, s44, v141
	v_mov_b32_e32 v143, v196
	v_mov_b32_e32 v178, v182
	v_mad_u64_u32 v[194:195], s[40:41], v136, s45, 0
	v_cvt_pk_bf16_f32 v178, v178, v143
	v_ashrrev_i32_e32 v143, 31, v136
	v_mov_b32_e32 v136, v195
	v_mad_u64_u32 v[196:197], s[40:41], v143, s45, v[136:137]
	v_mov_b32_e32 v195, v196
	v_lshl_add_u64 v[194:195], v[194:195], 1, s[0:1]
	s_lshl_b64 s[60:61], s[14:15], 1
	v_cvt_pk_bf16_f32 v176, v176, v180
	v_lshl_add_u64 v[194:195], v[194:195], 0, s[60:61]
	v_mov_b32_e32 v143, v139
	v_mov_b32_e32 v180, v137
	v_mov_b32_e32 v192, v191
	v_cvt_pk_bf16_f32 v177, v177, v174
	v_lshl_add_u64 v[194:195], v[194:195], 0, v[142:143]
	v_pk_mul_f32 v[136:137], v[134:135], v[180:181]
	v_mov_b32_e32 v184, v183
	v_pk_mul_f32 v[180:181], v[144:145], v[192:193]
	global_store_dwordx4 v[194:195], v[176:179], off
	v_mov_b32_e32 v188, v187
	s_nop 0
	v_pk_mul_f32 v[176:177], v[132:133], v[184:185]
	v_pk_mul_f32 v[178:179], v[130:131], v[188:189]
	v_mov_b32_e32 v174, v181
	v_cvt_pk_bf16_f32 v176, v136, v176
	v_add_u32_e32 v136, s44, v146
	v_cvt_pk_bf16_f32 v178, v178, v180
	v_cvt_pk_bf16_f32 v177, v137, v177
	v_ashrrev_i32_e32 v180, 31, v136
	v_mad_u64_u32 v[136:137], s[40:41], v136, s45, 0
	v_cvt_pk_bf16_f32 v179, v179, v174
	v_mov_b32_e32 v174, v137
	v_mad_u64_u32 v[180:181], s[40:41], v180, s45, v[174:175]
	v_mov_b32_e32 v137, v180
	v_lshl_add_u64 v[136:137], v[136:137], 1, s[0:1]
	v_lshl_add_u64 v[136:137], v[136:137], 0, s[60:61]
	v_lshl_add_u64 v[136:137], v[136:137], 0, v[142:143]
	ds_read2_b32 v[180:181], v153 offset0:16 offset1:24
	ds_read2_b32 v[182:183], v153 offset0:82 offset1:90
	global_store_dwordx4 v[136:137], v[176:179], off
	ds_read2_b32 v[136:137], v153 offset0:49 offset1:57
	ds_read2_b32 v[184:185], v153 offset0:115 offset1:123
	ds_read2_b32 v[186:187], v153 offset0:148 offset1:156
	ds_read2_b32 v[188:189], v153 offset0:214 offset1:222
	ds_read2_b32 v[190:191], v153 offset0:181 offset1:189
	ds_read2_b32 v[192:193], v153 offset0:247 offset1:255
	s_waitcnt lgkmcnt(7)
	v_mov_b32_e32 v176, v180
	s_waitcnt lgkmcnt(5)
	v_mov_b32_e32 v178, v136
	s_waitcnt lgkmcnt(4)
	v_mov_b32_e32 v179, v184
	s_waitcnt lgkmcnt(3)
	v_mov_b32_e32 v194, v186
	s_waitcnt lgkmcnt(2)
	v_mov_b32_e32 v195, v188
	v_mov_b32_e32 v177, v182
	v_pk_mul_f32 v[178:179], v[132:133], v[178:179]
	v_pk_mul_f32 v[194:195], v[130:131], v[194:195]
	s_waitcnt lgkmcnt(1)
	v_mov_b32_e32 v196, v190
	s_waitcnt lgkmcnt(0)
	v_mov_b32_e32 v197, v192
	v_pk_mul_f32 v[176:177], v[134:135], v[176:177]
	v_pk_mul_f32 v[196:197], v[144:145], v[196:197]
	v_bfe_u32 v180, v179, 16, 1
	v_bfe_u32 v186, v195, 16, 1
	v_bfe_u32 v136, v197, 16, 1
	v_add3_u32 v180, v179, v180, s54
	v_bfe_u32 v179, v177, 16, 1
	v_add3_u32 v186, v195, v186, s54
	v_add3_u32 v136, v197, v136, s54
	v_add3_u32 v177, v177, v179, s54
	v_lshrrev_b32_e32 v179, 16, v186
	v_mov_b32_e32 v182, v178
	v_mov_b32_e32 v184, v194
	v_and_or_b32 v179, v136, s55, v179
	v_add_u32_e32 v136, s44, v147
	v_mov_b32_e32 v174, v196
	v_mov_b32_e32 v178, v184
	v_mad_u64_u32 v[194:195], s[40:41], v136, s45, 0
	v_cvt_pk_bf16_f32 v178, v178, v174
	v_ashrrev_i32_e32 v174, 31, v136
	v_mov_b32_e32 v136, v195
	v_mad_u64_u32 v[196:197], s[40:41], v174, s45, v[136:137]
	v_mov_b32_e32 v195, v196
	v_lshl_add_u64 v[194:195], v[194:195], 1, s[0:1]
	v_lshrrev_b32_e32 v177, 16, v177
	v_lshl_add_u64 v[194:195], v[194:195], 0, s[60:61]
	v_mov_b32_e32 v184, v137
	v_mov_b32_e32 v192, v191
	v_and_or_b32 v177, v180, s55, v177
	v_cvt_pk_bf16_f32 v176, v176, v182
	v_lshl_add_u64 v[194:195], v[194:195], 0, v[142:143]
	v_mov_b32_e32 v182, v181
	v_pk_mul_f32 v[132:133], v[132:133], v[184:185]
	v_mov_b32_e32 v188, v187
	v_pk_mul_f32 v[136:137], v[144:145], v[192:193]
	global_store_dwordx4 v[194:195], v[176:179], off
	v_pk_mul_f32 v[134:135], v[134:135], v[182:183]
	v_pk_mul_f32 v[130:131], v[130:131], v[188:189]
	v_bfe_u32 v144, v137, 16, 1
	v_bfe_u32 v145, v136, 16, 1
	v_bfe_u32 v174, v133, 16, 1
	v_bfe_u32 v176, v132, 16, 1
	v_add3_u32 v176, v132, v176, s54
	v_add3_u32 v174, v133, v174, s54
	v_add3_u32 v132, v136, v145, s54
	v_add3_u32 v133, v137, v144, s54
	v_bfe_u32 v136, v134, 16, 1
	v_bfe_u32 v144, v130, 16, 1
	v_bfe_u32 v137, v135, 16, 1
	v_bfe_u32 v145, v131, 16, 1
	v_add3_u32 v130, v130, v144, s54
	v_add3_u32 v134, v134, v136, s54
	v_add3_u32 v131, v131, v145, s54
	v_add3_u32 v135, v135, v137, s54
	v_lshrrev_b32_e32 v134, 16, v134
	v_lshrrev_b32_e32 v130, 16, v130
	v_lshrrev_b32_e32 v135, 16, v135
	v_lshrrev_b32_e32 v131, 16, v131
	v_and_or_b32 v132, v132, s55, v130
	v_and_or_b32 v130, v176, s55, v134
	v_add_u32_e32 v134, s44, v148
	v_and_or_b32 v133, v133, s55, v131
	v_and_or_b32 v131, v174, s55, v135
	v_ashrrev_i32_e32 v137, 31, v134
	v_mad_u64_u32 v[134:135], s[40:41], v134, s45, 0
	v_mov_b32_e32 v136, v135
	v_mad_u64_u32 v[136:137], s[40:41], v137, s45, v[136:137]
	v_mov_b32_e32 v135, v136
	v_lshl_add_u64 v[134:135], v[134:135], 1, s[0:1]
	v_lshl_add_u64 v[134:135], v[134:135], 0, s[60:61]
	v_lshl_add_u64 v[134:135], v[134:135], 0, v[142:143]
	global_store_dwordx4 v[134:135], v[130:133], off
	s_waitcnt lgkmcnt(0)
	s_add_i32 s3, s3, s43
	s_cmp_gt_i32 s3, 0x1f57f
	s_mov_b64 s[60:61], 0
	s_cbranch_scc1 .LBB0_1262
	s_add_i32 s9, s3, s48
	s_cmp_lt_i32 s9, 0x1f580
	s_cselect_b32 s9, s9, s3
	s_cmp_lt_i32 s9, 0x8080
	s_cbranch_scc1 .LBB0_1323
	s_cmpk_lt_u32 s9, 0xa080
	s_cbranch_scc1 .LBB0_1324
	s_cmp_lt_u32 s9, 0x14c80
	s_cselect_b64 s[14:15], -1, 0
	s_add_i32 s16, s9, 0xfffe1580
	s_cmpk_lt_u32 s16, 0xac00
	s_cselect_b64 s[16:17], -1, 0
	s_or_b64 s[14:15], s[14:15], s[16:17]
	s_mov_b64 s[40:41], -1
	s_and_b64 vcc, exec, s[14:15]
	s_cbranch_vccnz .LBB0_1320
	s_add_i32 s14, s9, 0xfffd6980
	s_cmp_lt_u32 s14, 0xffff0c00
	s_mov_b64 s[72:73], -1
	s_cbranch_scc1 .LBB0_1317
	s_cmp_lt_u32 s9, 0x1ca80
	s_mov_b64 s[16:17], -1
	s_cbranch_scc1 .LBB0_1315
	s_add_i32 s14, s9, 0xfffe3580
	v_readlane_b32 s60, v250, 18
	s_lshl_b32 s15, s9, 5
	s_lshr_b32 s14, s14, 1
	v_readlane_b32 s61, v250, 19
	v_readlane_b32 s68, v250, 26
	v_readlane_b32 s69, v250, 27
	s_and_b32 s44, s15, 0xfe0
	s_and_b32 s14, s14, 0x7fffffc0
	s_mov_b64 s[16:17], 0
	s_mov_b64 s[60:61], s[68:69]
	v_readlane_b32 s62, v250, 20
	v_readlane_b32 s63, v250, 21
	v_readlane_b32 s64, v250, 22
	v_readlane_b32 s65, v250, 23
	v_readlane_b32 s66, v250, 24
	v_readlane_b32 s67, v250, 25
	v_readlane_b32 s70, v250, 28
	v_readlane_b32 s71, v250, 29
	v_readlane_b32 s72, v250, 30
	v_readlane_b32 s73, v250, 31
	v_readlane_b32 s74, v250, 32
	v_readlane_b32 s75, v250, 33

.LBB0_1331:
	ds_read2_b32 v[136:137], v153 offset1:8
	ds_read2_b32 v[180:181], v153 offset0:66 offset1:74
	ds_read2_b32 v[182:183], v153 offset0:33 offset1:41
	ds_read2_b32 v[184:185], v153 offset0:99 offset1:107
	ds_read2_b32 v[186:187], v153 offset0:132 offset1:140
	ds_read2_b32 v[188:189], v153 offset0:198 offset1:206
	ds_read2_b32 v[190:191], v153 offset0:165 offset1:173
	ds_read2_b32 v[192:193], v153 offset0:231 offset1:239
	s_waitcnt lgkmcnt(7)
	v_mov_b32_e32 v176, v136
	s_waitcnt lgkmcnt(5)
	v_mov_b32_e32 v178, v182
	s_waitcnt lgkmcnt(4)
	v_mov_b32_e32 v179, v184
	s_waitcnt lgkmcnt(3)
	v_mov_b32_e32 v194, v186
	s_waitcnt lgkmcnt(2)
	v_mov_b32_e32 v195, v188
	v_mov_b32_e32 v177, v180
	v_pk_mul_f32 v[178:179], v[132:133], v[178:179]
	v_pk_mul_f32 v[194:195], v[130:131], v[194:195]
	s_waitcnt lgkmcnt(1)
	v_mov_b32_e32 v196, v190
	s_waitcnt lgkmcnt(0)
	v_mov_b32_e32 v197, v192
	v_pk_mul_f32 v[176:177], v[134:135], v[176:177]
	v_pk_mul_f32 v[196:197], v[144:145], v[196:197]
	v_mov_b32_e32 v174, v179
	v_mov_b32_e32 v184, v195
	v_mov_b32_e32 v136, v197
	v_mov_b32_e32 v179, v184
	v_mov_b32_e32 v180, v178
	v_mov_b32_e32 v182, v194
	v_cvt_pk_bf16_f32 v179, v179, v136
	v_add_u32_e32 v136, s46, v141
	v_mov_b32_e32 v143, v196
	v_mov_b32_e32 v178, v182
	v_mad_u64_u32 v[194:195], s[40:41], v136, s47, 0
	v_cvt_pk_bf16_f32 v178, v178, v143
	v_ashrrev_i32_e32 v143, 31, v136
	v_mov_b32_e32 v136, v195
	v_mad_u64_u32 v[196:197], s[40:41], v143, s47, v[136:137]
	v_mov_b32_e32 v195, v196
	v_lshl_add_u64 v[194:195], v[194:195], 1, s[58:59]
	s_lshl_b64 s[60:61], s[4:5], 1
	v_cvt_pk_bf16_f32 v176, v176, v180
	v_lshl_add_u64 v[194:195], v[194:195], 0, s[60:61]
	v_mov_b32_e32 v143, v139
	v_mov_b32_e32 v180, v137
	v_mov_b32_e32 v192, v191
	v_cvt_pk_bf16_f32 v177, v177, v174
	v_lshl_add_u64 v[194:195], v[194:195], 0, v[142:143]
	v_pk_mul_f32 v[136:137], v[134:135], v[180:181]
	v_mov_b32_e32 v184, v183
	v_pk_mul_f32 v[180:181], v[144:145], v[192:193]
	global_store_dwordx4 v[194:195], v[176:179], off
	v_mov_b32_e32 v188, v187
	s_nop 0
	v_pk_mul_f32 v[176:177], v[132:133], v[184:185]
	v_pk_mul_f32 v[178:179], v[130:131], v[188:189]
	v_mov_b32_e32 v174, v181
	v_cvt_pk_bf16_f32 v176, v136, v176
	v_add_u32_e32 v136, s46, v146
	v_cvt_pk_bf16_f32 v178, v178, v180
	v_cvt_pk_bf16_f32 v177, v137, v177
	v_ashrrev_i32_e32 v180, 31, v136
	v_mad_u64_u32 v[136:137], s[40:41], v136, s47, 0
	v_cvt_pk_bf16_f32 v179, v179, v174
	v_mov_b32_e32 v174, v137
	v_mad_u64_u32 v[180:181], s[40:41], v180, s47, v[174:175]
	v_mov_b32_e32 v137, v180
	v_lshl_add_u64 v[136:137], v[136:137], 1, s[58:59]
	v_lshl_add_u64 v[136:137], v[136:137], 0, s[60:61]
	v_lshl_add_u64 v[136:137], v[136:137], 0, v[142:143]
	ds_read2_b32 v[180:181], v153 offset0:16 offset1:24
	ds_read2_b32 v[182:183], v153 offset0:82 offset1:90
	global_store_dwordx4 v[136:137], v[176:179], off
	ds_read2_b32 v[136:137], v153 offset0:49 offset1:57
	ds_read2_b32 v[184:185], v153 offset0:115 offset1:123
	ds_read2_b32 v[186:187], v153 offset0:148 offset1:156
	ds_read2_b32 v[188:189], v153 offset0:214 offset1:222
	ds_read2_b32 v[190:191], v153 offset0:181 offset1:189
	ds_read2_b32 v[192:193], v153 offset0:247 offset1:255
	s_waitcnt lgkmcnt(7)
	v_mov_b32_e32 v176, v180
	s_waitcnt lgkmcnt(5)
	v_mov_b32_e32 v178, v136
	s_waitcnt lgkmcnt(4)
	v_mov_b32_e32 v179, v184
	s_waitcnt lgkmcnt(3)
	v_mov_b32_e32 v194, v186
	s_waitcnt lgkmcnt(2)
	v_mov_b32_e32 v195, v188
	v_mov_b32_e32 v177, v182
	v_pk_mul_f32 v[178:179], v[132:133], v[178:179]
	v_pk_mul_f32 v[194:195], v[130:131], v[194:195]
	s_waitcnt lgkmcnt(1)
	v_mov_b32_e32 v196, v190
	s_waitcnt lgkmcnt(0)
	v_mov_b32_e32 v197, v192
	v_pk_mul_f32 v[176:177], v[134:135], v[176:177]
	v_pk_mul_f32 v[196:197], v[144:145], v[196:197]
	v_bfe_u32 v180, v179, 16, 1
	v_bfe_u32 v186, v195, 16, 1
	v_bfe_u32 v136, v197, 16, 1
	v_add3_u32 v180, v179, v180, s54
	v_bfe_u32 v179, v177, 16, 1
	v_add3_u32 v186, v195, v186, s54
	v_add3_u32 v136, v197, v136, s54
	v_add3_u32 v177, v177, v179, s54
	v_lshrrev_b32_e32 v179, 16, v186
	v_mov_b32_e32 v182, v178
	v_mov_b32_e32 v184, v194
	v_and_or_b32 v179, v136, s55, v179
	v_add_u32_e32 v136, s46, v147
	v_mov_b32_e32 v174, v196
	v_mov_b32_e32 v178, v184
	v_mad_u64_u32 v[194:195], s[40:41], v136, s47, 0
	v_cvt_pk_bf16_f32 v178, v178, v174
	v_ashrrev_i32_e32 v174, 31, v136
	v_mov_b32_e32 v136, v195
	v_mad_u64_u32 v[196:197], s[40:41], v174, s47, v[136:137]
	v_mov_b32_e32 v195, v196
	v_lshl_add_u64 v[194:195], v[194:195], 1, s[58:59]
	v_lshrrev_b32_e32 v177, 16, v177
	v_lshl_add_u64 v[194:195], v[194:195], 0, s[60:61]
	v_mov_b32_e32 v184, v137
	v_mov_b32_e32 v192, v191
	v_and_or_b32 v177, v180, s55, v177
	v_cvt_pk_bf16_f32 v176, v176, v182
	v_lshl_add_u64 v[194:195], v[194:195], 0, v[142:143]
	v_mov_b32_e32 v182, v181
	v_pk_mul_f32 v[132:133], v[132:133], v[184:185]
	v_mov_b32_e32 v188, v187
	v_pk_mul_f32 v[136:137], v[144:145], v[192:193]
	global_store_dwordx4 v[194:195], v[176:179], off
	v_pk_mul_f32 v[134:135], v[134:135], v[182:183]
	v_pk_mul_f32 v[130:131], v[130:131], v[188:189]
	v_bfe_u32 v144, v137, 16, 1
	v_bfe_u32 v145, v136, 16, 1
	v_bfe_u32 v174, v133, 16, 1
	v_bfe_u32 v176, v132, 16, 1
	v_add3_u32 v176, v132, v176, s54
	v_add3_u32 v174, v133, v174, s54
	v_add3_u32 v132, v136, v145, s54
	v_add3_u32 v133, v137, v144, s54
	v_bfe_u32 v136, v134, 16, 1
	v_bfe_u32 v144, v130, 16, 1
	v_bfe_u32 v137, v135, 16, 1
	v_bfe_u32 v145, v131, 16, 1
	v_add3_u32 v130, v130, v144, s54
	v_add3_u32 v134, v134, v136, s54
	v_add3_u32 v131, v131, v145, s54
	v_add3_u32 v135, v135, v137, s54
	v_lshrrev_b32_e32 v134, 16, v134
	v_lshrrev_b32_e32 v130, 16, v130
	v_lshrrev_b32_e32 v135, 16, v135
	v_lshrrev_b32_e32 v131, 16, v131
	v_and_or_b32 v132, v132, s55, v130
	v_and_or_b32 v130, v176, s55, v134
	v_add_u32_e32 v134, s46, v148
	v_and_or_b32 v133, v133, s55, v131
	v_and_or_b32 v131, v174, s55, v135
	v_ashrrev_i32_e32 v137, 31, v134
	v_mad_u64_u32 v[134:135], s[40:41], v134, s47, 0
	v_mov_b32_e32 v136, v135
	v_mad_u64_u32 v[136:137], s[40:41], v137, s47, v[136:137]
	v_mov_b32_e32 v135, v136
	v_lshl_add_u64 v[134:135], v[134:135], 1, s[58:59]
	v_lshl_add_u64 v[134:135], v[134:135], 0, s[60:61]
	v_lshl_add_u64 v[134:135], v[134:135], 0, v[142:143]
	global_store_dwordx4 v[134:135], v[130:133], off
	s_waitcnt lgkmcnt(0)
	s_add_i32 s3, s3, s43
	s_cmp_gt_i32 s3, 0x1f57f
	s_mov_b64 s[60:61], 0
	s_cbranch_scc1 .LBB0_1262
	s_add_i32 s9, s3, s48
	s_cmp_lt_i32 s9, 0x1f580
	s_cselect_b32 s9, s9, s3
	s_cmp_lt_i32 s9, 0x8080
	s_cbranch_scc1 .LBB0_1346
	s_cmpk_lt_u32 s9, 0xa080
	s_cbranch_scc1 .LBB0_1347
	s_cmp_lt_u32 s9, 0x14c80
	s_cselect_b64 s[20:21], -1, 0
	s_add_i32 s15, s9, 0xfffe1580
	s_cmpk_lt_u32 s15, 0xac00
	s_cselect_b64 s[22:23], -1, 0
	s_or_b64 s[20:21], s[20:21], s[22:23]
	s_mov_b64 s[40:41], -1
	s_and_b64 vcc, exec, s[20:21]
	s_cbranch_vccnz .LBB0_1343
	s_add_i32 s15, s9, 0xfffd6980
	s_cmp_lt_u32 s15, 0xffff0c00
	s_mov_b64 s[72:73], -1
	s_cbranch_scc1 .LBB0_1340
	s_cmp_lt_u32 s9, 0x1ca80
	s_mov_b64 s[22:23], -1
	s_cbranch_scc1 .LBB0_1338
	s_add_i32 s15, s9, 0xfffe3580
	v_readlane_b32 s68, v250, 18
	s_lshl_b32 s20, s9, 5
	s_lshr_b32 s15, s15, 1
	v_readlane_b32 s76, v250, 26
	v_readlane_b32 s77, v250, 27
	s_and_b32 s46, s20, 0xfe0
	s_and_b32 s4, s15, 0x7fffffc0
	s_mov_b64 s[22:23], 0
	s_mov_b64 s[60:61], s[76:77]
	v_readlane_b32 s69, v250, 19
	v_readlane_b32 s70, v250, 20
	v_readlane_b32 s71, v250, 21
	v_readlane_b32 s72, v250, 22
	v_readlane_b32 s73, v250, 23
	v_readlane_b32 s74, v250, 24
	v_readlane_b32 s75, v250, 25
	v_readlane_b32 s78, v250, 28
	v_readlane_b32 s79, v250, 29
	v_readlane_b32 s80, v250, 30
	v_readlane_b32 s81, v250, 31
	v_readlane_b32 s82, v250, 32
	v_readlane_b32 s83, v250, 33

.LBB0_1493:
	global_load_dwordx4 v[14:17], v[18:19], off offset:-3072
	global_load_dwordx4 v[10:13], v[18:19], off offset:-2048
	global_load_dwordx4 v[6:9], v[18:19], off offset:-1024
	global_load_dwordx4 v[2:5], v[18:19], off
	v_add_co_u32_e32 v24, vcc, 0xfffff000, v18
	v_add_co_u32_e64 v20, s[4:5], s12, v18
	s_nop 0
	v_addc_co_u32_e32 v25, vcc, -1, v19, vcc
	global_load_dwordx4 v[34:37], v[24:25], off offset:-3072
	global_load_dwordx4 v[38:41], v[24:25], off offset:-2048
	global_load_dwordx4 v[42:45], v[24:25], off offset:-1024
	global_load_dwordx4 v[46:49], v[18:19], off offset:-4096
	v_addc_co_u32_e64 v21, s[4:5], -1, v19, s[4:5]
	v_add_co_u32_e64 v22, s[4:5], s13, v18
	s_add_i32 s14, s14, s92
	s_nop 0
	v_addc_co_u32_e64 v23, s[4:5], -1, v19, s[4:5]
	s_cmpk_gt_i32 s14, 0x1fff
	v_lshl_add_u64 v[18:19], v[18:19], 0, s[6:7]
	s_waitcnt vmcnt(0)
	v_lshlrev_b32_e32 v25, 16, v16
	v_lshlrev_b32_e32 v24, 16, v14
	v_and_b32_e32 v51, 0xffff0000, v16
	v_and_b32_e32 v50, 0xffff0000, v14
	v_lshlrev_b32_e32 v53, 16, v17
	v_lshlrev_b32_e32 v52, 16, v15
	v_and_b32_e32 v17, 0xffff0000, v17
	v_and_b32_e32 v16, 0xffff0000, v15
	v_lshlrev_b32_e32 v15, 16, v11
	v_lshlrev_b32_e32 v14, 16, v10
	v_and_b32_e32 v11, 0xffff0000, v11
	v_and_b32_e32 v10, 0xffff0000, v10
	v_lshlrev_b32_e32 v55, 16, v13
	v_lshlrev_b32_e32 v54, 16, v12
	v_and_b32_e32 v13, 0xffff0000, v13
	v_and_b32_e32 v12, 0xffff0000, v12
	v_lshlrev_b32_e32 v56, 16, v6
	v_and_b32_e32 v57, 0xffff0000, v6
	v_lshlrev_b32_e32 v6, 16, v7
	v_and_b32_e32 v7, 0xffff0000, v7
	v_lshlrev_b32_e32 v58, 16, v8
	v_and_b32_e32 v59, 0xffff0000, v8
	v_lshlrev_b32_e32 v8, 16, v9
	v_and_b32_e32 v9, 0xffff0000, v9
	s_waitcnt lgkmcnt(0)
	v_pk_mul_f32 v[64:65], v[50:51], v[50:51]
	v_pk_mul_f32 v[66:67], v[16:17], v[16:17]
	v_pk_mul_f32 v[68:69], v[10:11], v[10:11]
	v_pk_mul_f32 v[70:71], v[12:13], v[12:13]
	v_mul_f32_e32 v72, v57, v57
	v_mul_f32_e32 v74, v7, v7
	v_mul_f32_e32 v76, v59, v59
	v_mul_f32_e32 v78, v9, v9
	v_lshlrev_b32_e32 v89, 16, v35
	v_lshlrev_b32_e32 v88, 16, v34
	v_and_b32_e32 v35, 0xffff0000, v35
	v_and_b32_e32 v34, 0xffff0000, v34
	v_lshlrev_b32_e32 v91, 16, v37
	v_lshlrev_b32_e32 v90, 16, v36
	v_and_b32_e32 v37, 0xffff0000, v37
	v_and_b32_e32 v36, 0xffff0000, v36
	v_lshlrev_b32_e32 v93, 16, v39
	v_lshlrev_b32_e32 v92, 16, v38
	v_and_b32_e32 v39, 0xffff0000, v39
	v_and_b32_e32 v38, 0xffff0000, v38
	v_lshlrev_b32_e32 v95, 16, v41
	v_lshlrev_b32_e32 v94, 16, v40
	v_and_b32_e32 v41, 0xffff0000, v41
	v_and_b32_e32 v40, 0xffff0000, v40
	v_lshlrev_b32_e32 v62, 16, v4
	v_and_b32_e32 v63, 0xffff0000, v4
	v_lshlrev_b32_e32 v4, 16, v5
	v_and_b32_e32 v5, 0xffff0000, v5
	v_mov_b32_e32 v80, v52
	v_mov_b32_e32 v81, v16
	v_mov_b32_e32 v82, v24
	v_mov_b32_e32 v83, v50
	v_mov_b32_e32 v16, v53
	v_mov_b32_e32 v50, v25
	v_mov_b32_e32 v84, v15
	v_mov_b32_e32 v85, v11
	v_mov_b32_e32 v86, v55
	v_mov_b32_e32 v87, v13
	v_lshlrev_b32_e32 v96, 16, v42
	v_and_b32_e32 v97, 0xffff0000, v42
	v_lshlrev_b32_e32 v42, 16, v43
	v_and_b32_e32 v43, 0xffff0000, v43
	v_lshlrev_b32_e32 v98, 16, v44
	v_and_b32_e32 v99, 0xffff0000, v44
	v_lshlrev_b32_e32 v44, 16, v45
	v_and_b32_e32 v45, 0xffff0000, v45
	v_pk_fma_f32 v[24:25], v[24:25], v[24:25], v[64:65]
	v_pk_fma_f32 v[52:53], v[52:53], v[52:53], v[66:67]
	v_pk_fma_f32 v[64:65], v[14:15], v[14:15], v[68:69]
	v_pk_fma_f32 v[66:67], v[54:55], v[54:55], v[70:71]
	v_pk_fma_f32 v[68:69], v[56:57], v[56:57], v[72:73] op_sel_hi:[1,1,0]
	v_pk_fma_f32 v[70:71], v[6:7], v[6:7], v[74:75] op_sel_hi:[1,1,0]
	v_pk_fma_f32 v[72:73], v[58:59], v[58:59], v[76:77] op_sel_hi:[1,1,0]
	v_pk_fma_f32 v[74:75], v[8:9], v[8:9], v[78:79] op_sel_hi:[1,1,0]
	v_mov_b32_e32 v15, v10
	v_mov_b32_e32 v55, v12
	v_pk_mul_f32 v[10:11], v[34:35], v[34:35]
	v_pk_mul_f32 v[12:13], v[36:37], v[36:37]
	v_pk_mul_f32 v[76:77], v[38:39], v[38:39]
	v_pk_mul_f32 v[78:79], v[40:41], v[40:41]
	v_lshlrev_b32_e32 v60, 16, v2
	v_and_b32_e32 v61, 0xffff0000, v2
	v_lshlrev_b32_e32 v2, 16, v3
	v_and_b32_e32 v3, 0xffff0000, v3
	v_mul_f32_e32 v105, v62, v62
	v_mul_f32_e32 v107, v63, v63
	v_mul_f32_e32 v109, v4, v4
	v_mul_f32_e32 v111, v5, v5
	v_lshlrev_b32_e32 v100, 16, v46
	v_and_b32_e32 v101, 0xffff0000, v46
	v_lshlrev_b32_e32 v46, 16, v47
	v_and_b32_e32 v47, 0xffff0000, v47
	v_lshlrev_b32_e32 v102, 16, v48
	v_and_b32_e32 v103, 0xffff0000, v48
	v_lshlrev_b32_e32 v48, 16, v49
	v_and_b32_e32 v49, 0xffff0000, v49
	v_mul_f32_e32 v104, v97, v97
	v_mul_f32_e32 v106, v43, v43
	v_mul_f32_e32 v108, v99, v99
	v_mul_f32_e32 v110, v45, v45
	v_pk_fma_f32 v[10:11], v[88:89], v[88:89], v[10:11]
	v_pk_fma_f32 v[12:13], v[90:91], v[90:91], v[12:13]
	v_pk_fma_f32 v[76:77], v[92:93], v[92:93], v[76:77]
	v_pk_fma_f32 v[78:79], v[94:95], v[94:95], v[78:79]
	v_mul_f32_e32 v120, v2, v2
	v_mul_f32_e32 v121, v3, v3
	v_mul_f32_e32 v122, v100, v100
	v_mul_f32_e32 v123, v101, v101
	v_mul_f32_e32 v124, v46, v46
	v_mul_f32_e32 v125, v47, v47
	v_mul_f32_e32 v126, v102, v102
	v_mul_f32_e32 v127, v103, v103
	v_mul_f32_e32 v128, v48, v48
	v_mul_f32_e32 v129, v49, v49
	v_pk_add_f32 v[24:25], v[24:25], v[52:53]
	v_pk_add_f32 v[52:53], v[64:65], v[64:65] op_sel:[0,1] op_sel_hi:[1,0]
	v_pk_add_f32 v[64:65], v[66:67], v[66:67] op_sel:[0,1] op_sel_hi:[1,0]
	v_mov_b32_e32 v69, v105
	v_mov_b32_e32 v71, v107
	v_mov_b32_e32 v73, v109
	v_mov_b32_e32 v75, v111
	v_mov_b32_e32 v66, v89
	v_mov_b32_e32 v67, v35
	v_mov_b32_e32 v112, v91
	v_mov_b32_e32 v113, v37
	v_pk_fma_f32 v[104:105], v[96:97], v[96:97], v[104:105] op_sel_hi:[1,1,0]
	v_pk_fma_f32 v[106:107], v[42:43], v[42:43], v[106:107] op_sel_hi:[1,1,0]
	v_pk_fma_f32 v[108:109], v[98:99], v[98:99], v[108:109] op_sel_hi:[1,1,0]
	v_pk_fma_f32 v[110:111], v[44:45], v[44:45], v[110:111] op_sel_hi:[1,1,0]
	v_mov_b32_e32 v89, v34
	v_mov_b32_e32 v91, v36
	v_pk_add_f32 v[10:11], v[10:11], v[10:11] op_sel:[0,1] op_sel_hi:[1,0]
	v_pk_add_f32 v[12:13], v[12:13], v[12:13] op_sel:[0,1] op_sel_hi:[1,0]
	v_pk_add_f32 v[34:35], v[76:77], v[76:77] op_sel:[0,1] op_sel_hi:[1,0]
	v_pk_add_f32 v[36:37], v[78:79], v[78:79] op_sel:[0,1] op_sel_hi:[1,0]
	v_mov_b32_e32 v53, v120
	v_mov_b32_e32 v65, v121
	v_mov_b32_e32 v105, v126
	v_mov_b32_e32 v107, v127
	v_mov_b32_e32 v109, v128
	v_mov_b32_e32 v111, v129
	v_mov_b32_e32 v11, v122
	v_mov_b32_e32 v13, v123
	v_mov_b32_e32 v35, v124
	v_mov_b32_e32 v37, v125
	v_mov_b32_e32 v114, v93
	v_mov_b32_e32 v115, v39
	v_mov_b32_e32 v93, v38
	v_pk_add_f32 v[38:39], v[52:53], v[64:65]
	v_pk_add_f32 v[52:53], v[104:105], v[106:107]
	v_pk_add_f32 v[64:65], v[108:109], v[110:111]
	v_pk_add_f32 v[10:11], v[10:11], v[12:13]
	v_pk_add_f32 v[12:13], v[34:35], v[36:37]
	v_pk_add_f32 v[34:35], v[52:53], v[64:65]
	v_pk_add_f32 v[10:11], v[10:11], v[12:13]
	v_mul_f32_e32 v118, v60, v60
	v_pk_add_f32 v[10:11], v[10:11], v[34:35]
	v_mul_f32_e32 v119, v61, v61
	v_pk_add_f32 v[24:25], v[24:25], v[24:25] op_sel:[0,1] op_sel_hi:[1,0]
	v_pk_add_f32 v[10:11], v[10:11], v[10:11] op_sel:[0,1] op_sel_hi:[1,0]
	v_mov_b32_e32 v25, v119
	v_mov_b32_e32 v11, v118
	v_pk_add_f32 v[68:69], v[68:69], v[70:71]
	v_pk_add_f32 v[70:71], v[72:73], v[74:75]
	v_pk_add_f32 v[10:11], v[10:11], v[24:25]
	v_mov_b32_e32 v116, v95
	v_mov_b32_e32 v117, v41
	v_mov_b32_e32 v95, v40
	v_pk_add_f32 v[40:41], v[68:69], v[70:71]
	v_pk_add_f32 v[10:11], v[10:11], v[38:39]
	s_nop 0
	v_pk_add_f32 v[10:11], v[10:11], v[40:41]
	s_nop 0
	v_add_f32_e32 v10, v10, v11
	ds_bpermute_b32 v11, v26, v10
	s_waitcnt lgkmcnt(0)
	v_add_f32_e32 v10, v10, v11
	ds_bpermute_b32 v11, v27, v10
	s_waitcnt lgkmcnt(0)
	v_add_f32_e32 v10, v10, v11
	ds_bpermute_b32 v11, v28, v10
	s_waitcnt lgkmcnt(0)
	v_add_f32_e32 v10, v10, v11
	ds_bpermute_b32 v11, v29, v10
	s_waitcnt lgkmcnt(0)
	v_add_f32_e32 v10, v10, v11
	ds_bpermute_b32 v11, v30, v10
	s_waitcnt lgkmcnt(0)
	v_add_f32_e32 v10, v10, v11
	ds_bpermute_b32 v11, v31, v10
	s_waitcnt lgkmcnt(0)
	v_add_f32_e32 v10, v10, v11
	v_fmamk_f32 v10, v10, 0x39800000, v32
	v_mul_f32_e32 v11, 0x4f800000, v10
	v_cmp_gt_f32_e32 vcc, s10, v10
	s_nop 1
	v_cndmask_b32_e32 v10, v10, v11, vcc
	v_sqrt_f32_e32 v11, v10
	s_nop 0
	v_add_u32_e32 v12, -1, v11
	v_add_u32_e32 v13, 1, v11
	v_fma_f32 v24, -v12, v11, v10
	v_fma_f32 v25, -v13, v11, v10
	v_cmp_ge_f32_e64 s[4:5], 0, v24
	s_nop 1
	v_cndmask_b32_e64 v11, v11, v12, s[4:5]
	v_cmp_lt_f32_e64 s[4:5], 0, v25
	s_nop 1
	v_cndmask_b32_e64 v11, v11, v13, s[4:5]
	v_mul_f32_e32 v12, 0x37800000, v11
	v_cndmask_b32_e32 v11, v11, v12, vcc
	v_cmp_class_f32_e32 vcc, v10, v33
	s_nop 1
	v_cndmask_b32_e32 v10, v11, v10, vcc
	v_div_scale_f32 v11, s[4:5], v10, v10, 1.0
	v_rcp_f32_e32 v13, v11
	v_div_scale_f32 v12, vcc, 1.0, v10, 1.0
	v_fma_f32 v24, -v11, v13, 1.0
	v_fmac_f32_e32 v13, v24, v13
	v_mul_f32_e32 v24, v12, v13
	v_fma_f32 v25, -v11, v24, v12
	v_fmac_f32_e32 v24, v25, v13
	v_fma_f32 v11, -v11, v24, v12
	v_div_fmas_f32 v11, v11, v13, v24
	v_div_fixup_f32 v10, v11, v10, 1.0
	v_pk_mul_f32 v[12:13], v[10:11], v[66:67] op_sel_hi:[0,1]
	v_pk_mul_f32 v[24:25], v[10:11], v[88:89] op_sel_hi:[0,1]
	v_pk_mul_f32 v[34:35], v[10:11], v[112:113] op_sel_hi:[0,1]
	v_pk_mul_f32 v[36:37], v[10:11], v[90:91] op_sel_hi:[0,1]
	v_pk_mul_f32 v[38:39], v[10:11], v[114:115] op_sel_hi:[0,1]
	v_pk_mul_f32 v[40:41], v[10:11], v[92:93] op_sel_hi:[0,1]
	v_pk_mul_f32 v[52:53], v[10:11], v[116:117] op_sel_hi:[0,1]
	v_pk_mul_f32 v[64:65], v[10:11], v[94:95] op_sel_hi:[0,1]
	v_pk_mul_f32 v[42:43], v[10:11], v[42:43] op_sel_hi:[0,1]
	v_pk_mul_f32 v[66:67], v[10:11], v[96:97] op_sel_hi:[0,1]
	v_pk_mul_f32 v[44:45], v[10:11], v[44:45] op_sel_hi:[0,1]
	v_pk_mul_f32 v[68:69], v[10:11], v[98:99] op_sel_hi:[0,1]
	v_pk_mul_f32 v[46:47], v[10:11], v[46:47] op_sel_hi:[0,1]
	v_pk_mul_f32 v[70:71], v[10:11], v[100:101] op_sel_hi:[0,1]
	v_pk_mul_f32 v[48:49], v[10:11], v[48:49] op_sel_hi:[0,1]
	v_pk_mul_f32 v[72:73], v[10:11], v[102:103] op_sel_hi:[0,1]
	v_pk_mul_f32 v[74:75], v[10:11], v[80:81] op_sel_hi:[0,1]
	v_pk_mul_f32 v[76:77], v[10:11], v[82:83] op_sel_hi:[0,1]
	v_pk_mul_f32 v[16:17], v[10:11], v[16:17] op_sel_hi:[0,1]
	v_pk_mul_f32 v[50:51], v[10:11], v[50:51] op_sel_hi:[0,1]
	v_pk_mul_f32 v[78:79], v[10:11], v[84:85] op_sel_hi:[0,1]
	v_pk_mul_f32 v[14:15], v[10:11], v[14:15] op_sel_hi:[0,1]
	v_pk_mul_f32 v[80:81], v[10:11], v[86:87] op_sel_hi:[0,1]
	v_pk_mul_f32 v[54:55], v[10:11], v[54:55] op_sel_hi:[0,1]
	v_pk_mul_f32 v[6:7], v[10:11], v[6:7] op_sel_hi:[0,1]
	v_pk_mul_f32 v[56:57], v[10:11], v[56:57] op_sel_hi:[0,1]
	v_pk_mul_f32 v[8:9], v[10:11], v[8:9] op_sel_hi:[0,1]
	v_pk_mul_f32 v[58:59], v[10:11], v[58:59] op_sel_hi:[0,1]
	v_pk_mul_f32 v[2:3], v[10:11], v[2:3] op_sel_hi:[0,1]
	v_pk_mul_f32 v[60:61], v[10:11], v[60:61] op_sel_hi:[0,1]
	v_pk_mul_f32 v[4:5], v[10:11], v[4:5] op_sel_hi:[0,1]
	v_pk_mul_f32 v[10:11], v[10:11], v[62:63] op_sel_hi:[0,1]
	v_bfe_u32 v62, v24, 16, 1
	v_bfe_u32 v63, v25, 16, 1
	v_bfe_u32 v88, v40, 16, 1
	v_bfe_u32 v90, v38, 16, 1
	v_bfe_u32 v92, v64, 16, 1
	v_bfe_u32 v93, v65, 16, 1
	v_bfe_u32 v94, v52, 16, 1
	v_bfe_u32 v96, v66, 16, 1
	v_bfe_u32 v97, v67, 16, 1
	v_bfe_u32 v98, v42, 16, 1
	v_bfe_u32 v100, v68, 16, 1
	v_bfe_u32 v101, v69, 16, 1
	v_bfe_u32 v102, v44, 16, 1
	v_bfe_u32 v104, v70, 16, 1
	v_bfe_u32 v105, v71, 16, 1
	v_bfe_u32 v106, v46, 16, 1
	v_bfe_u32 v108, v72, 16, 1
	v_bfe_u32 v109, v73, 16, 1
	v_bfe_u32 v110, v48, 16, 1
	v_bfe_u32 v112, v76, 16, 1
	v_bfe_u32 v113, v77, 16, 1
	v_bfe_u32 v114, v74, 16, 1
	v_bfe_u32 v116, v50, 16, 1
	v_bfe_u32 v118, v16, 16, 1
	v_bfe_u32 v119, v17, 16, 1
	v_bfe_u32 v120, v14, 16, 1
	v_bfe_u32 v121, v15, 16, 1
	v_bfe_u32 v122, v78, 16, 1
	v_bfe_u32 v123, v79, 16, 1
	v_bfe_u32 v124, v54, 16, 1
	v_bfe_u32 v125, v55, 16, 1
	v_bfe_u32 v126, v80, 16, 1
	v_bfe_u32 v127, v81, 16, 1
	v_bfe_u32 v128, v56, 16, 1
	v_bfe_u32 v130, v6, 16, 1
	v_bfe_u32 v131, v7, 16, 1
	v_bfe_u32 v132, v58, 16, 1
	v_bfe_u32 v133, v59, 16, 1
	v_bfe_u32 v134, v8, 16, 1
	v_bfe_u32 v135, v9, 16, 1
	v_bfe_u32 v136, v60, 16, 1
	v_bfe_u32 v137, v61, 16, 1
	v_bfe_u32 v138, v2, 16, 1
	v_bfe_u32 v139, v3, 16, 1
	v_bfe_u32 v140, v10, 16, 1
	v_bfe_u32 v141, v11, 16, 1
	v_bfe_u32 v142, v4, 16, 1
	v_bfe_u32 v143, v5, 16, 1
	v_add3_u32 v24, v24, v62, s11
	v_bfe_u32 v89, v41, 16, 1
	v_bfe_u32 v91, v39, 16, 1
	v_bfe_u32 v95, v53, 16, 1
	v_bfe_u32 v99, v43, 16, 1
	v_bfe_u32 v103, v45, 16, 1
	v_bfe_u32 v107, v47, 16, 1
	v_bfe_u32 v111, v49, 16, 1
	v_bfe_u32 v115, v75, 16, 1
	v_bfe_u32 v117, v51, 16, 1
	v_bfe_u32 v129, v57, 16, 1
	v_add3_u32 v25, v25, v63, s11
	v_add3_u32 v40, v40, v88, s11
	v_add3_u32 v38, v38, v90, s11
	v_add3_u32 v62, v64, v92, s11
	v_add3_u32 v63, v65, v93, s11
	v_add3_u32 v52, v52, v94, s11
	v_add3_u32 v64, v66, v96, s11
	v_add3_u32 v65, v67, v97, s11
	v_add3_u32 v42, v42, v98, s11
	v_add3_u32 v66, v68, v100, s11
	v_add3_u32 v67, v69, v101, s11
	v_add3_u32 v44, v44, v102, s11
	v_add3_u32 v68, v70, v104, s11
	v_add3_u32 v69, v71, v105, s11
	v_add3_u32 v46, v46, v106, s11
	v_add3_u32 v70, v72, v108, s11
	v_add3_u32 v71, v73, v109, s11
	v_add3_u32 v48, v48, v110, s11
	v_add3_u32 v72, v76, v112, s11
	v_add3_u32 v73, v77, v113, s11
	v_add3_u32 v74, v74, v114, s11
	v_add3_u32 v50, v50, v116, s11
	v_add3_u32 v16, v16, v118, s11
	v_add3_u32 v76, v17, v119, s11
	v_add3_u32 v14, v14, v120, s11
	v_add3_u32 v77, v15, v121, s11
	v_add3_u32 v15, v78, v122, s11
	v_add3_u32 v78, v79, v123, s11
	v_add3_u32 v17, v54, v124, s11
	v_add3_u32 v54, v55, v125, s11
	v_add3_u32 v55, v80, v126, s11
	v_add3_u32 v79, v81, v127, s11
	v_add3_u32 v56, v56, v128, s11
	v_add3_u32 v6, v6, v130, s11
	v_add3_u32 v80, v7, v131, s11
	v_add3_u32 v7, v58, v132, s11
	v_add3_u32 v58, v59, v133, s11
	v_add3_u32 v8, v8, v134, s11
	v_add3_u32 v59, v9, v135, s11
	v_add3_u32 v9, v60, v136, s11
	v_add3_u32 v60, v61, v137, s11
	v_add3_u32 v2, v2, v138, s11
	v_add3_u32 v61, v3, v139, s11
	v_add3_u32 v3, v10, v140, s11
	v_add3_u32 v81, v11, v141, s11
	v_add3_u32 v4, v4, v142, s11
	v_add3_u32 v82, v5, v143, s11
	v_lshrrev_b32_e32 v5, 16, v24
	v_mov_b32_e32 v10, v12
	v_mov_b32_e32 v11, v36
	v_mov_b32_e32 v12, v34
	v_add3_u32 v41, v41, v89, s11
	v_add3_u32 v39, v39, v91, s11
	v_add3_u32 v53, v53, v95, s11
	v_add3_u32 v43, v43, v99, s11
	v_add3_u32 v45, v45, v103, s11
	v_add3_u32 v47, v47, v107, s11
	v_add3_u32 v49, v49, v111, s11
	v_add3_u32 v75, v75, v115, s11
	v_add3_u32 v51, v51, v117, s11
	v_add3_u32 v57, v57, v129, s11
	v_lshrrev_b32_e32 v24, 16, v40
	v_lshrrev_b32_e32 v34, 16, v38
	v_lshrrev_b32_e32 v36, 16, v62
	v_lshrrev_b32_e32 v38, 16, v52
	v_lshrrev_b32_e32 v40, 16, v64
	v_lshrrev_b32_e32 v42, 16, v42
	v_lshrrev_b32_e32 v52, 16, v66
	v_lshrrev_b32_e32 v44, 16, v44
	v_lshrrev_b32_e32 v62, 16, v68
	v_lshrrev_b32_e32 v46, 16, v46
	v_lshrrev_b32_e32 v64, 16, v70
	v_lshrrev_b32_e32 v48, 16, v48
	v_lshrrev_b32_e32 v66, 16, v72
	v_lshrrev_b32_e32 v68, 16, v74
	v_lshrrev_b32_e32 v50, 16, v50
	v_lshrrev_b32_e32 v70, 16, v16
	v_lshrrev_b32_e32 v72, 16, v14
	v_lshrrev_b32_e32 v74, 16, v15
	v_lshrrev_b32_e32 v83, 16, v17
	v_lshrrev_b32_e32 v55, 16, v55
	v_lshrrev_b32_e32 v56, 16, v56
	v_lshrrev_b32_e32 v84, 16, v6
	v_lshrrev_b32_e32 v85, 16, v7
	v_lshrrev_b32_e32 v86, 16, v8
	v_lshrrev_b32_e32 v87, 16, v9
	v_lshrrev_b32_e32 v88, 16, v2
	v_lshrrev_b32_e32 v89, 16, v3
	v_lshrrev_b32_e32 v90, 16, v4
	v_and_or_b32 v2, v25, s3, v5
	v_cvt_pk_bf16_f32 v3, v10, v13
	v_cvt_pk_bf16_f32 v4, v11, v37
	v_cvt_pk_bf16_f32 v5, v12, v35
	v_and_or_b32 v6, v41, s3, v24
	v_and_or_b32 v7, v39, s3, v34
	v_and_or_b32 v8, v63, s3, v36
	v_and_or_b32 v9, v53, s3, v38
	v_and_or_b32 v10, v65, s3, v40
	v_and_or_b32 v11, v43, s3, v42
	v_and_or_b32 v12, v67, s3, v52
	v_and_or_b32 v13, v45, s3, v44
	v_and_or_b32 v14, v69, s3, v62
	v_and_or_b32 v15, v47, s3, v46
	v_and_or_b32 v16, v71, s3, v64
	v_and_or_b32 v17, v49, s3, v48
	v_and_or_b32 v34, v73, s3, v66
	v_and_or_b32 v35, v75, s3, v68
	v_and_or_b32 v36, v51, s3, v50
	v_and_or_b32 v37, v76, s3, v70
	v_and_or_b32 v38, v77, s3, v72
	v_and_or_b32 v39, v78, s3, v74
	v_and_or_b32 v40, v54, s3, v83
	v_and_or_b32 v41, v79, s3, v55
	v_and_or_b32 v42, v57, s3, v56
	v_and_or_b32 v43, v80, s3, v84
	v_and_or_b32 v44, v58, s3, v85
	v_and_or_b32 v45, v59, s3, v86
	v_and_or_b32 v46, v60, s3, v87
	v_and_or_b32 v47, v61, s3, v88
	v_and_or_b32 v48, v81, s3, v89
	v_and_or_b32 v49, v82, s3, v90
	global_store_dwordx4 v[20:21], v[2:5], off offset:-3072
	global_store_dwordx4 v[20:21], v[6:9], off offset:-2048
	global_store_dwordx4 v[20:21], v[10:13], off offset:-1024
	global_store_dwordx4 v[22:23], v[14:17], off offset:-4096
	global_store_dwordx4 v[22:23], v[34:37], off offset:-3072
	global_store_dwordx4 v[22:23], v[38:41], off offset:-2048
	global_store_dwordx4 v[22:23], v[42:45], off offset:-1024
	global_store_dwordx4 v[22:23], v[46:49], off
	s_cbranch_scc0 .LBB0_1493

.LBB0_1496:
	s_or_b64 exec, exec, s[6:7]
	s_waitcnt lgkmcnt(0)
	s_barrier
	ds_read_b128 v[16:19], v62
	ds_read_b128 v[20:23], v62 offset:16
	s_add_i32 s35, s35, s86
	v_lshl_add_u64 v[10:11], v[10:11], 0, s[10:11]
	s_cmpk_lt_i32 s35, 0x100
	s_waitcnt lgkmcnt(1)
	v_mov_b32_e32 v24, v16
	s_waitcnt lgkmcnt(0)
	v_mov_b32_e32 v25, v20
	v_mov_b32_e32 v20, v17
	v_pk_add_f32 v[16:17], v[24:25], v[20:21]
	v_mov_b32_e32 v20, v18
	v_mov_b32_e32 v21, v22
	v_mov_b32_e32 v22, v19
	v_pk_add_f32 v[18:19], v[20:21], v[22:23]
	v_lshl_add_u64 v[14:15], v[14:15], 0, s[12:13]
	v_pk_add_f32 v[16:17], v[16:17], v[18:19]
	s_nop 0
	v_add_f32_e32 v16, v16, v17
	v_fmamk_f32 v16, v16, 0x39800000, v60
	v_mul_f32_e32 v17, 0x4f800000, v16
	v_cmp_gt_f32_e32 vcc, s33, v16
	s_nop 1
	v_cndmask_b32_e32 v16, v16, v17, vcc
	v_sqrt_f32_e32 v17, v16
	s_nop 0
	v_add_u32_e32 v18, -1, v17
	v_fma_f32 v19, -v18, v17, v16
	v_cmp_ge_f32_e64 s[6:7], 0, v19
	v_add_u32_e32 v19, 1, v17
	s_nop 0
	v_cndmask_b32_e64 v18, v17, v18, s[6:7]
	v_fma_f32 v17, -v19, v17, v16
	v_cmp_lt_f32_e64 s[6:7], 0, v17
	s_nop 1
	v_cndmask_b32_e64 v17, v18, v19, s[6:7]
	v_mul_f32_e32 v18, 0x37800000, v17
	v_cndmask_b32_e32 v17, v17, v18, vcc
	v_cmp_class_f32_e32 vcc, v16, v61
	s_nop 1
	v_cndmask_b32_e32 v16, v17, v16, vcc
	v_div_scale_f32 v17, s[6:7], v16, v16, 1.0
	v_rcp_f32_e32 v18, v17
	s_nop 0
	v_fma_f32 v19, -v17, v18, 1.0
	v_fmac_f32_e32 v18, v19, v18
	v_div_scale_f32 v19, vcc, 1.0, v16, 1.0
	v_mul_f32_e32 v20, v19, v18
	v_fma_f32 v21, -v17, v20, v19
	v_fmac_f32_e32 v20, v21, v18
	v_fma_f32 v17, -v17, v20, v19
	v_div_fmas_f32 v17, v17, v18, v20
	v_div_fixup_f32 v16, v17, v16, 1.0
	v_pk_mul_f32 v[2:3], v[2:3], v[16:17] op_sel_hi:[1,0]
	v_pk_mul_f32 v[4:5], v[4:5], v[16:17] op_sel_hi:[1,0]
	v_pk_mul_f32 v[8:9], v[8:9], v[16:17] op_sel_hi:[1,0]
	v_pk_mul_f32 v[6:7], v[6:7], v[16:17] op_sel_hi:[1,0]
	v_bfe_u32 v16, v2, 16, 1
	v_add3_u32 v2, v2, v16, s34
	v_bfe_u32 v16, v3, 16, 1
	v_lshrrev_b32_e32 v2, 16, v2
	v_add3_u32 v3, v3, v16, s34
	v_and_or_b32 v2, v3, s3, v2
	v_mov_b32_e32 v3, v4
	v_mov_b32_e32 v4, v5
	v_cvt_pk_bf16_f32 v3, v3, v4
	v_mov_b32_e32 v4, v6
	v_mov_b32_e32 v5, v7
	v_cvt_pk_bf16_f32 v4, v4, v5
	v_mov_b32_e32 v5, v8
	v_mov_b32_e32 v6, v9
	v_cvt_pk_bf16_f32 v5, v5, v6
	v_lshl_add_u64 v[6:7], s[80:81], 0, v[12:13]
	v_add_co_u32_e32 v6, vcc, 0x2ef00000, v6
	v_lshl_add_u64 v[12:13], v[12:13], 0, s[10:11]
	s_nop 0
	v_addc_co_u32_e32 v7, vcc, 0, v7, vcc
	global_store_dwordx2 v[6:7], v[2:3], off
	global_store_dwordx2 v[6:7], v[4:5], off offset:512
	s_cbranch_scc0 .LBB0_1499

.LBB0_1818:
	ds_read2_b32 v[104:105], v153 offset1:8
	ds_read2_b32 v[112:113], v153 offset0:66 offset1:74
	ds_read2_b32 v[114:115], v153 offset0:33 offset1:41
	ds_read2_b32 v[116:117], v153 offset0:99 offset1:107
	ds_read2_b32 v[118:119], v153 offset0:132 offset1:140
	ds_read2_b32 v[120:121], v153 offset0:198 offset1:206
	ds_read2_b32 v[122:123], v153 offset0:165 offset1:173
	ds_read2_b32 v[124:125], v153 offset0:231 offset1:239
	s_waitcnt lgkmcnt(7)
	v_mov_b32_e32 v108, v104
	s_waitcnt lgkmcnt(5)
	v_mov_b32_e32 v110, v114
	s_waitcnt lgkmcnt(4)
	v_mov_b32_e32 v111, v116
	s_waitcnt lgkmcnt(3)
	v_mov_b32_e32 v126, v118
	s_waitcnt lgkmcnt(2)
	v_mov_b32_e32 v127, v120
	v_mov_b32_e32 v109, v112
	v_pk_mul_f32 v[110:111], v[100:101], v[110:111]
	v_pk_mul_f32 v[126:127], v[98:99], v[126:127]
	s_waitcnt lgkmcnt(1)
	v_mov_b32_e32 v128, v122
	s_waitcnt lgkmcnt(0)
	v_mov_b32_e32 v129, v124
	v_pk_mul_f32 v[108:109], v[102:103], v[108:109]
	v_pk_mul_f32 v[128:129], v[106:107], v[128:129]
	v_mov_b32_e32 v114, v111
	v_mov_b32_e32 v120, v127
	v_mov_b32_e32 v116, v110
	v_mov_b32_e32 v110, v128
	v_mov_b32_e32 v104, v129
	v_mov_b32_e32 v118, v126
	v_mov_b32_e32 v111, v120
	v_mov_b32_e32 v112, v118
	v_cvt_pk_bf16_f32 v111, v111, v104
	v_or_b32_e32 v104, s78, v141
	s_ashr_i32 s7, s78, 31
	v_cvt_pk_bf16_f32 v110, v112, v110
	v_mul_lo_u32 v112, s35, v104
	s_mul_i32 s7, s34, s7
	v_mad_u64_u32 v[126:127], s[38:39], s34, v104, 0
	v_add3_u32 v127, v127, s7, v112
	v_lshl_add_u64 v[126:127], v[126:127], 1, s[48:49]
	s_lshl_b64 s[36:37], s[36:37], 1
	v_lshl_add_u64 v[126:127], v[126:127], 0, s[36:37]
	v_mov_b32_e32 v143, v139
	v_mov_b32_e32 v112, v105
	v_mov_b32_e32 v124, v123
	v_cvt_pk_bf16_f32 v109, v109, v114
	v_cvt_pk_bf16_f32 v108, v108, v116
	v_lshl_add_u64 v[126:127], v[126:127], 0, v[142:143]
	v_pk_mul_f32 v[104:105], v[102:103], v[112:113]
	v_mov_b32_e32 v116, v115
	v_pk_mul_f32 v[112:113], v[106:107], v[124:125]
	global_store_dwordx4 v[126:127], v[108:111], off
	v_mov_b32_e32 v120, v119
	s_nop 0
	v_pk_mul_f32 v[108:109], v[100:101], v[116:117]
	v_pk_mul_f32 v[110:111], v[98:99], v[120:121]
	v_cvt_pk_bf16_f32 v108, v104, v108
	v_or_b32_e32 v104, s78, v146
	v_cvt_pk_bf16_f32 v110, v110, v112
	v_cvt_pk_bf16_f32 v109, v105, v109
	v_mul_lo_u32 v112, s35, v104
	v_mad_u64_u32 v[104:105], s[38:39], s34, v104, 0
	v_add3_u32 v105, v105, s7, v112
	v_lshl_add_u64 v[104:105], v[104:105], 1, s[48:49]
	v_lshl_add_u64 v[104:105], v[104:105], 0, s[36:37]
	v_cvt_pk_bf16_f32 v111, v111, v113
	v_lshl_add_u64 v[104:105], v[104:105], 0, v[142:143]
	ds_read2_b32 v[112:113], v153 offset0:16 offset1:24
	ds_read2_b32 v[114:115], v153 offset0:82 offset1:90
	global_store_dwordx4 v[104:105], v[108:111], off
	ds_read2_b32 v[104:105], v153 offset0:49 offset1:57
	ds_read2_b32 v[116:117], v153 offset0:115 offset1:123
	ds_read2_b32 v[118:119], v153 offset0:148 offset1:156
	ds_read2_b32 v[120:121], v153 offset0:214 offset1:222
	ds_read2_b32 v[122:123], v153 offset0:181 offset1:189
	ds_read2_b32 v[124:125], v153 offset0:247 offset1:255
	s_waitcnt lgkmcnt(7)
	v_mov_b32_e32 v108, v112
	s_waitcnt lgkmcnt(5)
	v_mov_b32_e32 v110, v104
	s_waitcnt lgkmcnt(4)
	v_mov_b32_e32 v111, v116
	s_waitcnt lgkmcnt(3)
	v_mov_b32_e32 v126, v118
	s_waitcnt lgkmcnt(2)
	v_mov_b32_e32 v127, v120
	v_mov_b32_e32 v109, v114
	v_pk_mul_f32 v[110:111], v[100:101], v[110:111]
	v_pk_mul_f32 v[126:127], v[98:99], v[126:127]
	s_waitcnt lgkmcnt(1)
	v_mov_b32_e32 v128, v122
	s_waitcnt lgkmcnt(0)
	v_mov_b32_e32 v129, v124
	v_pk_mul_f32 v[108:109], v[102:103], v[108:109]
	v_pk_mul_f32 v[128:129], v[106:107], v[128:129]
	v_bfe_u32 v112, v128, 16, 1
	v_mov_b32_e32 v114, v111
	v_bfe_u32 v118, v126, 16, 1
	v_mov_b32_e32 v120, v127
	v_mov_b32_e32 v116, v110
	v_add3_u32 v110, v128, v112, s76
	v_mov_b32_e32 v104, v129
	v_add3_u32 v118, v126, v118, s76
	v_mov_b32_e32 v111, v120
	v_lshrrev_b32_e32 v112, 16, v118
	v_cvt_pk_bf16_f32 v111, v111, v104
	v_or_b32_e32 v104, s78, v147
	v_and_or_b32 v110, v110, s77, v112
	v_mul_lo_u32 v112, s35, v104
	v_mad_u64_u32 v[126:127], s[38:39], s34, v104, 0
	v_add3_u32 v127, v127, s7, v112
	v_lshl_add_u64 v[126:127], v[126:127], 1, s[48:49]
	v_cvt_pk_bf16_f32 v108, v108, v116
	v_lshl_add_u64 v[126:127], v[126:127], 0, s[36:37]
	v_mov_b32_e32 v116, v105
	v_mov_b32_e32 v124, v123
	v_cvt_pk_bf16_f32 v109, v109, v114
	v_lshl_add_u64 v[126:127], v[126:127], 0, v[142:143]
	v_mov_b32_e32 v114, v113
	v_pk_mul_f32 v[100:101], v[100:101], v[116:117]
	v_mov_b32_e32 v120, v119
	v_pk_mul_f32 v[104:105], v[106:107], v[124:125]
	global_store_dwordx4 v[126:127], v[108:111], off
	v_pk_mul_f32 v[102:103], v[102:103], v[114:115]
	v_pk_mul_f32 v[98:99], v[98:99], v[120:121]
	v_bfe_u32 v106, v105, 16, 1
	v_bfe_u32 v107, v104, 16, 1
	v_bfe_u32 v108, v101, 16, 1
	v_bfe_u32 v109, v100, 16, 1
	v_add3_u32 v109, v100, v109, s76
	v_add3_u32 v108, v101, v108, s76
	v_add3_u32 v100, v104, v107, s76
	v_add3_u32 v101, v105, v106, s76
	v_bfe_u32 v104, v102, 16, 1
	v_bfe_u32 v106, v98, 16, 1
	v_bfe_u32 v105, v103, 16, 1
	v_bfe_u32 v107, v99, 16, 1
	v_add3_u32 v98, v98, v106, s76
	v_add3_u32 v102, v102, v104, s76
	v_add3_u32 v99, v99, v107, s76
	v_add3_u32 v103, v103, v105, s76
	v_lshrrev_b32_e32 v102, 16, v102
	v_lshrrev_b32_e32 v98, 16, v98
	v_lshrrev_b32_e32 v103, 16, v103
	v_lshrrev_b32_e32 v99, 16, v99
	v_and_or_b32 v100, v100, s77, v98
	v_and_or_b32 v98, v109, s77, v102
	v_or_b32_e32 v102, s78, v148
	v_and_or_b32 v101, v101, s77, v99
	v_and_or_b32 v99, v108, s77, v103
	v_mul_lo_u32 v104, s35, v102
	v_mad_u64_u32 v[102:103], s[34:35], s34, v102, 0
	v_add3_u32 v103, v103, s7, v104
	v_lshl_add_u64 v[102:103], v[102:103], 1, s[48:49]
	v_lshl_add_u64 v[102:103], v[102:103], 0, s[36:37]
	v_lshl_add_u64 v[102:103], v[102:103], 0, v[142:143]
	global_store_dwordx4 v[102:103], v[98:101], off
	s_waitcnt lgkmcnt(0)
	s_add_i32 s3, s3, s47
	s_cmp_lt_i32 s3, 0x24680
	s_cselect_b64 s[40:41], -1, 0

.LBB0_1842:
	ds_read2_b32 v[136:137], v153 offset1:8
	ds_read2_b32 v[180:181], v153 offset0:66 offset1:74
	ds_read2_b32 v[182:183], v153 offset0:33 offset1:41
	ds_read2_b32 v[184:185], v153 offset0:99 offset1:107
	ds_read2_b32 v[186:187], v153 offset0:132 offset1:140
	ds_read2_b32 v[188:189], v153 offset0:198 offset1:206
	ds_read2_b32 v[190:191], v153 offset0:165 offset1:173
	ds_read2_b32 v[192:193], v153 offset0:231 offset1:239
	s_waitcnt lgkmcnt(7)
	v_mov_b32_e32 v176, v136
	s_waitcnt lgkmcnt(5)
	v_mov_b32_e32 v178, v182
	s_waitcnt lgkmcnt(4)
	v_mov_b32_e32 v179, v184
	s_waitcnt lgkmcnt(3)
	v_mov_b32_e32 v194, v186
	s_waitcnt lgkmcnt(2)
	v_mov_b32_e32 v195, v188
	v_mov_b32_e32 v177, v180
	v_pk_mul_f32 v[178:179], v[132:133], v[178:179]
	v_pk_mul_f32 v[194:195], v[130:131], v[194:195]
	s_waitcnt lgkmcnt(1)
	v_mov_b32_e32 v196, v190
	s_waitcnt lgkmcnt(0)
	v_mov_b32_e32 v197, v192
	v_pk_mul_f32 v[176:177], v[134:135], v[176:177]
	v_pk_mul_f32 v[196:197], v[144:145], v[196:197]
	v_mov_b32_e32 v180, v179
	v_mov_b32_e32 v186, v195
	v_mov_b32_e32 v136, v197
	v_mov_b32_e32 v179, v186
	v_mov_b32_e32 v182, v178
	v_mov_b32_e32 v184, v194
	v_cvt_pk_bf16_f32 v179, v179, v136
	v_add_u32_e32 v136, s33, v141
	v_mov_b32_e32 v143, v196
	v_mov_b32_e32 v178, v184
	v_mad_u64_u32 v[194:195], s[40:41], v136, s46, 0
	v_cvt_pk_bf16_f32 v178, v178, v143
	v_ashrrev_i32_e32 v143, 31, v136
	v_mov_b32_e32 v136, v195
	v_mad_u64_u32 v[196:197], s[40:41], v143, s46, v[136:137]
	v_mov_b32_e32 v195, v196
	v_lshl_add_u64 v[194:195], v[194:195], 1, s[92:93]
	s_lshl_b64 s[40:41], s[6:7], 1
	v_cvt_pk_bf16_f32 v177, v177, v180
	v_lshl_add_u64 v[194:195], v[194:195], 0, s[40:41]
	v_mov_b32_e32 v143, v139
	v_mov_b32_e32 v180, v137
	v_mov_b32_e32 v192, v191
	v_cvt_pk_bf16_f32 v176, v176, v182
	v_lshl_add_u64 v[194:195], v[194:195], 0, v[142:143]
	v_pk_mul_f32 v[136:137], v[134:135], v[180:181]
	v_mov_b32_e32 v184, v183
	v_pk_mul_f32 v[180:181], v[144:145], v[192:193]
	global_store_dwordx4 v[194:195], v[176:179], off
	v_mov_b32_e32 v188, v187
	s_nop 0
	v_pk_mul_f32 v[176:177], v[132:133], v[184:185]
	v_pk_mul_f32 v[178:179], v[130:131], v[188:189]
	v_cvt_pk_bf16_f32 v176, v136, v176
	v_add_u32_e32 v136, s33, v146
	v_cvt_pk_bf16_f32 v179, v179, v181
	v_cvt_pk_bf16_f32 v177, v137, v177
	v_ashrrev_i32_e32 v181, 31, v136
	v_mad_u64_u32 v[136:137], s[42:43], v136, s46, 0
	v_cvt_pk_bf16_f32 v178, v178, v180
	v_mov_b32_e32 v180, v137
	v_mad_u64_u32 v[180:181], s[42:43], v181, s46, v[180:181]
	v_mov_b32_e32 v137, v180
	v_lshl_add_u64 v[136:137], v[136:137], 1, s[92:93]
	v_lshl_add_u64 v[136:137], v[136:137], 0, s[40:41]
	v_lshl_add_u64 v[136:137], v[136:137], 0, v[142:143]
	ds_read2_b32 v[180:181], v153 offset0:16 offset1:24
	ds_read2_b32 v[182:183], v153 offset0:82 offset1:90
	global_store_dwordx4 v[136:137], v[176:179], off
	ds_read2_b32 v[136:137], v153 offset0:49 offset1:57
	ds_read2_b32 v[184:185], v153 offset0:115 offset1:123
	ds_read2_b32 v[186:187], v153 offset0:148 offset1:156
	ds_read2_b32 v[188:189], v153 offset0:214 offset1:222
	ds_read2_b32 v[190:191], v153 offset0:181 offset1:189
	ds_read2_b32 v[192:193], v153 offset0:247 offset1:255
	s_waitcnt lgkmcnt(7)
	v_mov_b32_e32 v176, v180
	s_waitcnt lgkmcnt(5)
	v_mov_b32_e32 v178, v136
	s_waitcnt lgkmcnt(4)
	v_mov_b32_e32 v179, v184
	s_waitcnt lgkmcnt(3)
	v_mov_b32_e32 v194, v186
	s_waitcnt lgkmcnt(2)
	v_mov_b32_e32 v195, v188
	v_mov_b32_e32 v177, v182
	v_pk_mul_f32 v[178:179], v[132:133], v[178:179]
	v_pk_mul_f32 v[194:195], v[130:131], v[194:195]
	s_waitcnt lgkmcnt(1)
	v_mov_b32_e32 v196, v190
	s_waitcnt lgkmcnt(0)
	v_mov_b32_e32 v197, v192
	v_pk_mul_f32 v[176:177], v[134:135], v[176:177]
	v_pk_mul_f32 v[196:197], v[144:145], v[196:197]
	v_mov_b32_e32 v182, v179
	v_mov_b32_e32 v188, v195
	v_bfe_u32 v180, v196, 16, 1
	v_mov_b32_e32 v136, v197
	v_bfe_u32 v186, v194, 16, 1
	v_mov_b32_e32 v179, v188
	v_mov_b32_e32 v184, v178
	v_add3_u32 v178, v196, v180, s76
	v_add3_u32 v186, v194, v186, s76
	v_cvt_pk_bf16_f32 v179, v179, v136
	v_add_u32_e32 v136, s33, v147
	v_lshrrev_b32_e32 v180, 16, v186
	v_mad_u64_u32 v[194:195], s[42:43], v136, s46, 0
	v_and_or_b32 v178, v178, s77, v180
	v_ashrrev_i32_e32 v180, 31, v136
	v_mov_b32_e32 v136, v195
	v_mad_u64_u32 v[196:197], s[42:43], v180, s46, v[136:137]
	v_mov_b32_e32 v195, v196
	v_lshl_add_u64 v[194:195], v[194:195], 1, s[92:93]
	v_cvt_pk_bf16_f32 v176, v176, v184
	v_lshl_add_u64 v[194:195], v[194:195], 0, s[40:41]
	v_mov_b32_e32 v184, v137
	v_mov_b32_e32 v192, v191
	v_cvt_pk_bf16_f32 v177, v177, v182
	v_lshl_add_u64 v[194:195], v[194:195], 0, v[142:143]
	v_mov_b32_e32 v182, v181
	v_pk_mul_f32 v[132:133], v[132:133], v[184:185]
	v_mov_b32_e32 v188, v187
	v_pk_mul_f32 v[136:137], v[144:145], v[192:193]
	global_store_dwordx4 v[194:195], v[176:179], off
	v_pk_mul_f32 v[134:135], v[134:135], v[182:183]
	v_pk_mul_f32 v[130:131], v[130:131], v[188:189]
	v_bfe_u32 v144, v137, 16, 1
	v_bfe_u32 v145, v136, 16, 1
	v_bfe_u32 v176, v133, 16, 1
	v_bfe_u32 v177, v132, 16, 1
	v_add3_u32 v177, v132, v177, s76
	v_add3_u32 v176, v133, v176, s76
	v_add3_u32 v132, v136, v145, s76
	v_add3_u32 v133, v137, v144, s76
	v_bfe_u32 v136, v134, 16, 1
	v_bfe_u32 v144, v130, 16, 1
	v_bfe_u32 v137, v135, 16, 1
	v_bfe_u32 v145, v131, 16, 1
	v_add3_u32 v130, v130, v144, s76
	v_add3_u32 v134, v134, v136, s76
	v_add3_u32 v131, v131, v145, s76
	v_add3_u32 v135, v135, v137, s76
	v_lshrrev_b32_e32 v134, 16, v134
	v_lshrrev_b32_e32 v130, 16, v130
	v_lshrrev_b32_e32 v135, 16, v135
	v_lshrrev_b32_e32 v131, 16, v131
	v_and_or_b32 v132, v132, s77, v130
	v_and_or_b32 v130, v177, s77, v134
	v_add_u32_e32 v134, s33, v148
	v_and_or_b32 v133, v133, s77, v131
	v_and_or_b32 v131, v176, s77, v135
	v_ashrrev_i32_e32 v137, 31, v134
	v_mad_u64_u32 v[134:135], s[42:43], v134, s46, 0
	v_mov_b32_e32 v136, v135
	v_mad_u64_u32 v[136:137], s[42:43], v137, s46, v[136:137]
	v_mov_b32_e32 v135, v136
	v_lshl_add_u64 v[134:135], v[134:135], 1, s[92:93]
	v_lshl_add_u64 v[134:135], v[134:135], 0, s[40:41]
	v_lshl_add_u64 v[134:135], v[134:135], 0, v[142:143]
	global_store_dwordx4 v[134:135], v[130:133], off
	s_waitcnt lgkmcnt(0)
	s_add_i32 s3, s3, s47
	s_cmp_lt_i32 s3, 0x24680
	s_mov_b64 s[40:41], 0
	s_cbranch_scc0 .LBB0_1819
	s_add_i32 s6, s3, s79
	s_cmp_lt_i32 s6, 0x24680
	s_cselect_b32 s7, s6, s3
	s_cmp_lt_i32 s7, 0x8080
	s_cbranch_scc1 .LBB0_1857
	s_cmpk_lt_u32 s7, 0xa080
	s_cbranch_scc1 .LBB0_1858
	s_cmp_lt_u32 s7, 0x14c80
	s_cselect_b64 s[8:9], -1, 0
	s_add_i32 s6, s7, 0xfffe1580
	s_cmpk_lt_u32 s6, 0xac00
	s_cselect_b64 s[12:13], -1, 0
	s_or_b64 s[8:9], s[8:9], s[12:13]
	s_mov_b64 s[42:43], -1
	s_and_b64 vcc, exec, s[8:9]
	s_cbranch_vccnz .LBB0_1854
	s_add_i32 s6, s7, 0xfffd6980
	s_cmp_lt_u32 s6, 0xffff0c00
	s_mov_b64 s[72:73], -1
	s_cbranch_scc1 .LBB0_1851
	s_cmp_lt_u32 s7, 0x1ca80
	s_mov_b64 s[8:9], -1
	s_cbranch_scc1 .LBB0_1849
	s_add_i32 s6, s7, 0xfffe3580
	v_readlane_b32 s16, v250, 18
	s_lshl_b32 s8, s7, 5
	s_lshr_b32 s6, s6, 1
	v_readlane_b32 s24, v250, 26
	v_readlane_b32 s25, v250, 27
	s_and_b32 s33, s8, 0xfe0
	s_and_b32 s6, s6, 0x7fffffc0
	s_mov_b64 s[8:9], 0
	s_mov_b64 s[40:41], s[24:25]
	v_readlane_b32 s17, v250, 19
	v_readlane_b32 s18, v250, 20
	v_readlane_b32 s19, v250, 21
	v_readlane_b32 s20, v250, 22
	v_readlane_b32 s21, v250, 23
	v_readlane_b32 s22, v250, 24
	v_readlane_b32 s23, v250, 25
	v_readlane_b32 s26, v250, 28
	v_readlane_b32 s27, v250, 29
	v_readlane_b32 s28, v250, 30
	v_readlane_b32 s29, v250, 31
	v_readlane_b32 s30, v250, 32
	v_readlane_b32 s31, v250, 33

.LBB0_1865:
	ds_read2_b32 v[136:137], v153 offset1:8
	ds_read2_b32 v[180:181], v153 offset0:66 offset1:74
	ds_read2_b32 v[182:183], v153 offset0:33 offset1:41
	ds_read2_b32 v[184:185], v153 offset0:99 offset1:107
	ds_read2_b32 v[186:187], v153 offset0:132 offset1:140
	ds_read2_b32 v[188:189], v153 offset0:198 offset1:206
	ds_read2_b32 v[190:191], v153 offset0:165 offset1:173
	ds_read2_b32 v[192:193], v153 offset0:231 offset1:239
	s_waitcnt lgkmcnt(7)
	v_mov_b32_e32 v176, v136
	s_waitcnt lgkmcnt(5)
	v_mov_b32_e32 v178, v182
	s_waitcnt lgkmcnt(4)
	v_mov_b32_e32 v179, v184
	s_waitcnt lgkmcnt(3)
	v_mov_b32_e32 v194, v186
	s_waitcnt lgkmcnt(2)
	v_mov_b32_e32 v195, v188
	v_mov_b32_e32 v177, v180
	v_pk_mul_f32 v[178:179], v[132:133], v[178:179]
	v_pk_mul_f32 v[194:195], v[130:131], v[194:195]
	s_waitcnt lgkmcnt(1)
	v_mov_b32_e32 v196, v190
	s_waitcnt lgkmcnt(0)
	v_mov_b32_e32 v197, v192
	v_pk_mul_f32 v[176:177], v[134:135], v[176:177]
	v_pk_mul_f32 v[196:197], v[144:145], v[196:197]
	v_mov_b32_e32 v180, v179
	v_mov_b32_e32 v186, v195
	v_mov_b32_e32 v136, v197
	v_mov_b32_e32 v179, v186
	v_mov_b32_e32 v182, v178
	v_mov_b32_e32 v184, v194
	v_cvt_pk_bf16_f32 v179, v179, v136
	v_add_u32_e32 v136, s82, v141
	v_mov_b32_e32 v143, v196
	v_mov_b32_e32 v178, v184
	v_mad_u64_u32 v[194:195], s[40:41], v136, s83, 0
	v_cvt_pk_bf16_f32 v178, v178, v143
	v_ashrrev_i32_e32 v143, 31, v136
	v_mov_b32_e32 v136, v195
	v_mad_u64_u32 v[196:197], s[40:41], v143, s83, v[136:137]
	v_mov_b32_e32 v195, v196
	v_lshl_add_u64 v[194:195], v[194:195], 1, s[74:75]
	s_lshl_b64 s[40:41], s[94:95], 1
	v_cvt_pk_bf16_f32 v177, v177, v180
	v_lshl_add_u64 v[194:195], v[194:195], 0, s[40:41]
	v_mov_b32_e32 v143, v139
	v_mov_b32_e32 v180, v137
	v_mov_b32_e32 v192, v191
	v_cvt_pk_bf16_f32 v176, v176, v182
	v_lshl_add_u64 v[194:195], v[194:195], 0, v[142:143]
	v_pk_mul_f32 v[136:137], v[134:135], v[180:181]
	v_mov_b32_e32 v184, v183
	v_pk_mul_f32 v[180:181], v[144:145], v[192:193]
	global_store_dwordx4 v[194:195], v[176:179], off
	v_mov_b32_e32 v188, v187
	s_nop 0
	v_pk_mul_f32 v[176:177], v[132:133], v[184:185]
	v_pk_mul_f32 v[178:179], v[130:131], v[188:189]
	v_cvt_pk_bf16_f32 v176, v136, v176
	v_add_u32_e32 v136, s82, v146
	v_cvt_pk_bf16_f32 v179, v179, v181
	v_cvt_pk_bf16_f32 v177, v137, v177
	v_ashrrev_i32_e32 v181, 31, v136
	v_mad_u64_u32 v[136:137], s[42:43], v136, s83, 0
	v_cvt_pk_bf16_f32 v178, v178, v180
	v_mov_b32_e32 v180, v137
	v_mad_u64_u32 v[180:181], s[42:43], v181, s83, v[180:181]
	v_mov_b32_e32 v137, v180
	v_lshl_add_u64 v[136:137], v[136:137], 1, s[74:75]
	v_lshl_add_u64 v[136:137], v[136:137], 0, s[40:41]
	v_lshl_add_u64 v[136:137], v[136:137], 0, v[142:143]
	ds_read2_b32 v[180:181], v153 offset0:16 offset1:24
	ds_read2_b32 v[182:183], v153 offset0:82 offset1:90
	global_store_dwordx4 v[136:137], v[176:179], off
	ds_read2_b32 v[136:137], v153 offset0:49 offset1:57
	ds_read2_b32 v[184:185], v153 offset0:115 offset1:123
	ds_read2_b32 v[186:187], v153 offset0:148 offset1:156
	ds_read2_b32 v[188:189], v153 offset0:214 offset1:222
	ds_read2_b32 v[190:191], v153 offset0:181 offset1:189
	ds_read2_b32 v[192:193], v153 offset0:247 offset1:255
	s_waitcnt lgkmcnt(7)
	v_mov_b32_e32 v176, v180
	s_waitcnt lgkmcnt(5)
	v_mov_b32_e32 v178, v136
	s_waitcnt lgkmcnt(4)
	v_mov_b32_e32 v179, v184
	s_waitcnt lgkmcnt(3)
	v_mov_b32_e32 v194, v186
	s_waitcnt lgkmcnt(2)
	v_mov_b32_e32 v195, v188
	v_mov_b32_e32 v177, v182
	v_pk_mul_f32 v[178:179], v[132:133], v[178:179]
	v_pk_mul_f32 v[194:195], v[130:131], v[194:195]
	s_waitcnt lgkmcnt(1)
	v_mov_b32_e32 v196, v190
	s_waitcnt lgkmcnt(0)
	v_mov_b32_e32 v197, v192
	v_pk_mul_f32 v[176:177], v[134:135], v[176:177]
	v_pk_mul_f32 v[196:197], v[144:145], v[196:197]
	v_mov_b32_e32 v182, v179
	v_mov_b32_e32 v188, v195
	v_bfe_u32 v180, v196, 16, 1
	v_mov_b32_e32 v136, v197
	v_bfe_u32 v186, v194, 16, 1
	v_mov_b32_e32 v179, v188
	v_mov_b32_e32 v184, v178
	v_add3_u32 v178, v196, v180, s76
	v_add3_u32 v186, v194, v186, s76
	v_cvt_pk_bf16_f32 v179, v179, v136
	v_add_u32_e32 v136, s82, v147
	v_lshrrev_b32_e32 v180, 16, v186
	v_mad_u64_u32 v[194:195], s[42:43], v136, s83, 0
	v_and_or_b32 v178, v178, s77, v180
	v_ashrrev_i32_e32 v180, 31, v136
	v_mov_b32_e32 v136, v195
	v_mad_u64_u32 v[196:197], s[42:43], v180, s83, v[136:137]
	v_mov_b32_e32 v195, v196
	v_lshl_add_u64 v[194:195], v[194:195], 1, s[74:75]
	v_cvt_pk_bf16_f32 v176, v176, v184
	v_lshl_add_u64 v[194:195], v[194:195], 0, s[40:41]
	v_mov_b32_e32 v184, v137
	v_mov_b32_e32 v192, v191
	v_cvt_pk_bf16_f32 v177, v177, v182
	v_lshl_add_u64 v[194:195], v[194:195], 0, v[142:143]
	v_mov_b32_e32 v182, v181
	v_pk_mul_f32 v[132:133], v[132:133], v[184:185]
	v_mov_b32_e32 v188, v187
	v_pk_mul_f32 v[136:137], v[144:145], v[192:193]
	global_store_dwordx4 v[194:195], v[176:179], off
	v_pk_mul_f32 v[134:135], v[134:135], v[182:183]
	v_pk_mul_f32 v[130:131], v[130:131], v[188:189]
	v_bfe_u32 v144, v137, 16, 1
	v_bfe_u32 v145, v136, 16, 1
	v_bfe_u32 v176, v133, 16, 1
	v_bfe_u32 v177, v132, 16, 1
	v_add3_u32 v177, v132, v177, s76
	v_add3_u32 v176, v133, v176, s76
	v_add3_u32 v132, v136, v145, s76
	v_add3_u32 v133, v137, v144, s76
	v_bfe_u32 v136, v134, 16, 1
	v_bfe_u32 v144, v130, 16, 1
	v_bfe_u32 v137, v135, 16, 1
	v_bfe_u32 v145, v131, 16, 1
	v_add3_u32 v130, v130, v144, s76
	v_add3_u32 v134, v134, v136, s76
	v_add3_u32 v131, v131, v145, s76
	v_add3_u32 v135, v135, v137, s76
	v_lshrrev_b32_e32 v134, 16, v134
	v_lshrrev_b32_e32 v130, 16, v130
	v_lshrrev_b32_e32 v135, 16, v135
	v_lshrrev_b32_e32 v131, 16, v131
	v_and_or_b32 v132, v132, s77, v130
	v_and_or_b32 v130, v177, s77, v134
	v_add_u32_e32 v134, s82, v148
	v_and_or_b32 v133, v133, s77, v131
	v_and_or_b32 v131, v176, s77, v135
	v_ashrrev_i32_e32 v137, 31, v134
	v_mad_u64_u32 v[134:135], s[42:43], v134, s83, 0
	v_mov_b32_e32 v136, v135
	v_mad_u64_u32 v[136:137], s[42:43], v137, s83, v[136:137]
	v_mov_b32_e32 v135, v136
	v_lshl_add_u64 v[134:135], v[134:135], 1, s[74:75]
	v_lshl_add_u64 v[134:135], v[134:135], 0, s[40:41]
	v_lshl_add_u64 v[134:135], v[134:135], 0, v[142:143]
	global_store_dwordx4 v[134:135], v[130:133], off
	s_waitcnt lgkmcnt(0)
	s_add_i32 s3, s3, s47
	s_cmp_gt_i32 s3, 0x2467f
	s_mov_b64 s[40:41], 0
	s_cbranch_scc1 .LBB0_1819
	s_add_i32 s7, s3, s79
	s_cmp_lt_i32 s7, 0x24680
	s_cselect_b32 s7, s7, s3
	s_cmp_lt_i32 s7, 0x8080
	s_cbranch_scc1 .LBB0_1880
	s_cmpk_lt_u32 s7, 0xa080
	s_cbranch_scc1 .LBB0_1881
	s_cmp_lt_u32 s7, 0x14c80
	s_cselect_b64 s[14:15], -1, 0
	s_add_i32 s16, s7, 0xfffe1580
	s_cmpk_lt_u32 s16, 0xac00
	s_cselect_b64 s[16:17], -1, 0
	s_or_b64 s[14:15], s[14:15], s[16:17]
	s_mov_b64 s[42:43], -1
	s_and_b64 vcc, exec, s[14:15]
	s_cbranch_vccnz .LBB0_1877
	s_add_i32 s14, s7, 0xfffd6980
	s_cmp_lt_u32 s14, 0xffff0c00
	s_mov_b64 s[72:73], -1
	s_cbranch_scc1 .LBB0_1874
	s_cmp_lt_u32 s7, 0x1ca80
	s_mov_b64 s[8:9], -1
	s_cbranch_scc1 .LBB0_1872
	s_add_i32 s14, s7, 0xfffe3580
	v_readlane_b32 s16, v250, 18
	s_lshl_b32 s15, s7, 5
	s_lshr_b32 s14, s14, 1
	v_readlane_b32 s24, v250, 26
	v_readlane_b32 s25, v250, 27
	s_and_b32 s82, s15, 0xfe0
	s_and_b32 s94, s14, 0x7fffffc0
	s_mov_b64 s[8:9], 0
	s_mov_b64 s[40:41], s[24:25]
	v_readlane_b32 s17, v250, 19
	v_readlane_b32 s18, v250, 20
	v_readlane_b32 s19, v250, 21
	v_readlane_b32 s20, v250, 22
	v_readlane_b32 s21, v250, 23
	v_readlane_b32 s22, v250, 24
	v_readlane_b32 s23, v250, 25
	v_readlane_b32 s26, v250, 28
	v_readlane_b32 s27, v250, 29
	v_readlane_b32 s28, v250, 30
	v_readlane_b32 s29, v250, 31
	v_readlane_b32 s30, v250, 32
	v_readlane_b32 s31, v250, 33

.LBB0_1888:
	ds_read2_b32 v[136:137], v153 offset1:8
	ds_read2_b32 v[180:181], v153 offset0:66 offset1:74
	ds_read2_b32 v[182:183], v153 offset0:33 offset1:41
	ds_read2_b32 v[184:185], v153 offset0:99 offset1:107
	ds_read2_b32 v[186:187], v153 offset0:132 offset1:140
	ds_read2_b32 v[188:189], v153 offset0:198 offset1:206
	ds_read2_b32 v[190:191], v153 offset0:165 offset1:173
	ds_read2_b32 v[192:193], v153 offset0:231 offset1:239
	s_waitcnt lgkmcnt(7)
	v_mov_b32_e32 v176, v136
	s_waitcnt lgkmcnt(5)
	v_mov_b32_e32 v178, v182
	s_waitcnt lgkmcnt(4)
	v_mov_b32_e32 v179, v184
	s_waitcnt lgkmcnt(3)
	v_mov_b32_e32 v194, v186
	s_waitcnt lgkmcnt(2)
	v_mov_b32_e32 v195, v188
	v_mov_b32_e32 v177, v180
	v_pk_mul_f32 v[178:179], v[132:133], v[178:179]
	v_pk_mul_f32 v[194:195], v[130:131], v[194:195]
	s_waitcnt lgkmcnt(1)
	v_mov_b32_e32 v196, v190
	s_waitcnt lgkmcnt(0)
	v_mov_b32_e32 v197, v192
	v_pk_mul_f32 v[176:177], v[134:135], v[176:177]
	v_pk_mul_f32 v[196:197], v[144:145], v[196:197]
	v_mov_b32_e32 v180, v179
	v_mov_b32_e32 v186, v195
	v_mov_b32_e32 v136, v197
	v_mov_b32_e32 v179, v186
	v_mov_b32_e32 v182, v178
	v_mov_b32_e32 v184, v194
	v_cvt_pk_bf16_f32 v179, v179, v136
	v_add_u32_e32 v136, s90, v141
	v_mov_b32_e32 v143, v196
	v_mov_b32_e32 v178, v184
	v_mad_u64_u32 v[194:195], s[40:41], v136, s91, 0
	v_cvt_pk_bf16_f32 v178, v178, v143
	v_ashrrev_i32_e32 v143, 31, v136
	v_mov_b32_e32 v136, v195
	v_mad_u64_u32 v[196:197], s[40:41], v143, s91, v[136:137]
	v_mov_b32_e32 v195, v196
	v_lshl_add_u64 v[194:195], v[194:195], 1, s[70:71]
	s_lshl_b64 s[40:41], s[4:5], 1
	v_cvt_pk_bf16_f32 v177, v177, v180
	v_lshl_add_u64 v[194:195], v[194:195], 0, s[40:41]
	v_mov_b32_e32 v143, v139
	v_mov_b32_e32 v180, v137
	v_mov_b32_e32 v192, v191
	v_cvt_pk_bf16_f32 v176, v176, v182
	v_lshl_add_u64 v[194:195], v[194:195], 0, v[142:143]
	v_pk_mul_f32 v[136:137], v[134:135], v[180:181]
	v_mov_b32_e32 v184, v183
	v_pk_mul_f32 v[180:181], v[144:145], v[192:193]
	global_store_dwordx4 v[194:195], v[176:179], off
	v_mov_b32_e32 v188, v187
	s_nop 0
	v_pk_mul_f32 v[176:177], v[132:133], v[184:185]
	v_pk_mul_f32 v[178:179], v[130:131], v[188:189]
	v_cvt_pk_bf16_f32 v176, v136, v176
	v_add_u32_e32 v136, s90, v146
	v_cvt_pk_bf16_f32 v179, v179, v181
	v_cvt_pk_bf16_f32 v177, v137, v177
	v_ashrrev_i32_e32 v181, 31, v136
	v_mad_u64_u32 v[136:137], s[42:43], v136, s91, 0
	v_cvt_pk_bf16_f32 v178, v178, v180
	v_mov_b32_e32 v180, v137
	v_mad_u64_u32 v[180:181], s[42:43], v181, s91, v[180:181]
	v_mov_b32_e32 v137, v180
	v_lshl_add_u64 v[136:137], v[136:137], 1, s[70:71]
	v_lshl_add_u64 v[136:137], v[136:137], 0, s[40:41]
	v_lshl_add_u64 v[136:137], v[136:137], 0, v[142:143]
	ds_read2_b32 v[180:181], v153 offset0:16 offset1:24
	ds_read2_b32 v[182:183], v153 offset0:82 offset1:90
	global_store_dwordx4 v[136:137], v[176:179], off
	ds_read2_b32 v[136:137], v153 offset0:49 offset1:57
	ds_read2_b32 v[184:185], v153 offset0:115 offset1:123
	ds_read2_b32 v[186:187], v153 offset0:148 offset1:156
	ds_read2_b32 v[188:189], v153 offset0:214 offset1:222
	ds_read2_b32 v[190:191], v153 offset0:181 offset1:189
	ds_read2_b32 v[192:193], v153 offset0:247 offset1:255
	s_waitcnt lgkmcnt(7)
	v_mov_b32_e32 v176, v180
	s_waitcnt lgkmcnt(5)
	v_mov_b32_e32 v178, v136
	s_waitcnt lgkmcnt(4)
	v_mov_b32_e32 v179, v184
	s_waitcnt lgkmcnt(3)
	v_mov_b32_e32 v194, v186
	s_waitcnt lgkmcnt(2)
	v_mov_b32_e32 v195, v188
	v_mov_b32_e32 v177, v182
	v_pk_mul_f32 v[178:179], v[132:133], v[178:179]
	v_pk_mul_f32 v[194:195], v[130:131], v[194:195]
	s_waitcnt lgkmcnt(1)
	v_mov_b32_e32 v196, v190
	s_waitcnt lgkmcnt(0)
	v_mov_b32_e32 v197, v192
	v_pk_mul_f32 v[176:177], v[134:135], v[176:177]
	v_pk_mul_f32 v[196:197], v[144:145], v[196:197]
	v_mov_b32_e32 v182, v179
	v_mov_b32_e32 v188, v195
	v_bfe_u32 v180, v196, 16, 1
	v_mov_b32_e32 v136, v197
	v_bfe_u32 v186, v194, 16, 1
	v_mov_b32_e32 v179, v188
	v_mov_b32_e32 v184, v178
	v_add3_u32 v178, v196, v180, s76
	v_add3_u32 v186, v194, v186, s76
	v_cvt_pk_bf16_f32 v179, v179, v136
	v_add_u32_e32 v136, s90, v147
	v_lshrrev_b32_e32 v180, 16, v186
	v_mad_u64_u32 v[194:195], s[42:43], v136, s91, 0
	v_and_or_b32 v178, v178, s77, v180
	v_ashrrev_i32_e32 v180, 31, v136
	v_mov_b32_e32 v136, v195
	v_mad_u64_u32 v[196:197], s[42:43], v180, s91, v[136:137]
	v_mov_b32_e32 v195, v196
	v_lshl_add_u64 v[194:195], v[194:195], 1, s[70:71]
	v_cvt_pk_bf16_f32 v176, v176, v184
	v_lshl_add_u64 v[194:195], v[194:195], 0, s[40:41]
	v_mov_b32_e32 v184, v137
	v_mov_b32_e32 v192, v191
	v_cvt_pk_bf16_f32 v177, v177, v182
	v_lshl_add_u64 v[194:195], v[194:195], 0, v[142:143]
	v_mov_b32_e32 v182, v181
	v_pk_mul_f32 v[132:133], v[132:133], v[184:185]
	v_mov_b32_e32 v188, v187
	v_pk_mul_f32 v[136:137], v[144:145], v[192:193]
	global_store_dwordx4 v[194:195], v[176:179], off
	v_pk_mul_f32 v[134:135], v[134:135], v[182:183]
	v_pk_mul_f32 v[130:131], v[130:131], v[188:189]
	v_bfe_u32 v144, v137, 16, 1
	v_bfe_u32 v145, v136, 16, 1
	v_bfe_u32 v176, v133, 16, 1
	v_bfe_u32 v177, v132, 16, 1
	v_add3_u32 v177, v132, v177, s76
	v_add3_u32 v176, v133, v176, s76
	v_add3_u32 v132, v136, v145, s76
	v_add3_u32 v133, v137, v144, s76
	v_bfe_u32 v136, v134, 16, 1
	v_bfe_u32 v144, v130, 16, 1
	v_bfe_u32 v137, v135, 16, 1
	v_bfe_u32 v145, v131, 16, 1
	v_add3_u32 v130, v130, v144, s76
	v_add3_u32 v134, v134, v136, s76
	v_add3_u32 v131, v131, v145, s76
	v_add3_u32 v135, v135, v137, s76
	v_lshrrev_b32_e32 v134, 16, v134
	v_lshrrev_b32_e32 v130, 16, v130
	v_lshrrev_b32_e32 v135, 16, v135
	v_lshrrev_b32_e32 v131, 16, v131
	v_and_or_b32 v132, v132, s77, v130
	v_and_or_b32 v130, v177, s77, v134
	v_add_u32_e32 v134, s90, v148
	v_and_or_b32 v133, v133, s77, v131
	v_and_or_b32 v131, v176, s77, v135
	v_ashrrev_i32_e32 v137, 31, v134
	v_mad_u64_u32 v[134:135], s[42:43], v134, s91, 0
	v_mov_b32_e32 v136, v135
	v_mad_u64_u32 v[136:137], s[42:43], v137, s91, v[136:137]
	v_mov_b32_e32 v135, v136
	v_lshl_add_u64 v[134:135], v[134:135], 1, s[70:71]
	v_lshl_add_u64 v[134:135], v[134:135], 0, s[40:41]
	v_lshl_add_u64 v[134:135], v[134:135], 0, v[142:143]
	global_store_dwordx4 v[134:135], v[130:133], off
	s_waitcnt lgkmcnt(0)
	s_add_i32 s3, s3, s47
	s_cmp_gt_i32 s3, 0x2467f
	s_mov_b64 s[40:41], 0
	s_cbranch_scc1 .LBB0_1819
	s_add_i32 s7, s3, s79
	s_cmp_lt_i32 s7, 0x24680
	s_cselect_b32 s7, s7, s3
	s_cmp_lt_i32 s7, 0x8080
	s_cbranch_scc1 .LBB0_1903
	s_cmpk_lt_u32 s7, 0xa080
	s_cbranch_scc1 .LBB0_1904
	s_cmp_lt_u32 s7, 0x14c80
	s_cselect_b64 s[20:21], -1, 0
	s_add_i32 s15, s7, 0xfffe1580
	s_cmpk_lt_u32 s15, 0xac00
	s_cselect_b64 s[22:23], -1, 0
	s_or_b64 s[20:21], s[20:21], s[22:23]
	s_mov_b64 s[42:43], -1
	s_and_b64 vcc, exec, s[20:21]
	s_cbranch_vccnz .LBB0_1900
	s_add_i32 s15, s7, 0xfffd6980
	s_cmp_lt_u32 s15, 0xffff0c00
	s_mov_b64 s[72:73], -1
	s_cbranch_scc1 .LBB0_1897
	s_cmp_lt_u32 s7, 0x1ca80
	s_mov_b64 s[8:9], -1
	s_cbranch_scc1 .LBB0_1895
	s_lshl_b32 s20, s7, 5
	s_add_i32 s15, s7, 0xfffe3580
	s_and_b32 s90, s20, 0xfe0
	v_readlane_b32 s16, v250, 18
	s_lshr_b32 s15, s15, 1
	v_readlane_b32 s24, v250, 26
	v_readlane_b32 s25, v250, 27
	s_and_b32 s4, s15, 0x7fffffc0
	s_mov_b64 s[8:9], 0
	s_mov_b64 s[40:41], s[24:25]
	v_readlane_b32 s17, v250, 19
	v_readlane_b32 s18, v250, 20
	v_readlane_b32 s19, v250, 21
	v_readlane_b32 s20, v250, 22
	v_readlane_b32 s21, v250, 23
	v_readlane_b32 s22, v250, 24
	v_readlane_b32 s23, v250, 25
	v_readlane_b32 s26, v250, 28
	v_readlane_b32 s27, v250, 29
	v_readlane_b32 s28, v250, 30
	v_readlane_b32 s29, v250, 31
	v_readlane_b32 s30, v250, 32
	v_readlane_b32 s31, v250, 33

.LBB0_1970:
	ds_read2_b32 v[8:9], v123 offset1:8
	ds_read2_b32 v[16:17], v123 offset0:66 offset1:74
	ds_read2_b32 v[18:19], v123 offset0:33 offset1:41
	ds_read2_b32 v[20:21], v123 offset0:99 offset1:107
	ds_read2_b32 v[22:23], v123 offset0:132 offset1:140
	ds_read2_b32 v[24:25], v123 offset0:198 offset1:206
	ds_read2_b32 v[26:27], v123 offset0:165 offset1:173
	ds_read2_b32 v[28:29], v123 offset0:231 offset1:239
	s_waitcnt lgkmcnt(7)
	v_mov_b32_e32 v12, v8
	s_waitcnt lgkmcnt(5)
	v_mov_b32_e32 v14, v18
	s_waitcnt lgkmcnt(4)
	v_mov_b32_e32 v15, v20
	s_waitcnt lgkmcnt(3)
	v_mov_b32_e32 v30, v22
	s_waitcnt lgkmcnt(2)
	v_mov_b32_e32 v31, v24
	v_mov_b32_e32 v13, v16
	v_pk_mul_f32 v[14:15], v[4:5], v[14:15]
	v_pk_mul_f32 v[30:31], v[2:3], v[30:31]
	s_waitcnt lgkmcnt(1)
	v_mov_b32_e32 v32, v26
	s_waitcnt lgkmcnt(0)
	v_mov_b32_e32 v33, v28
	v_pk_mul_f32 v[12:13], v[6:7], v[12:13]
	v_pk_mul_f32 v[32:33], v[10:11], v[32:33]
	v_mov_b32_e32 v18, v15
	v_mov_b32_e32 v24, v31
	v_mov_b32_e32 v20, v14
	v_mov_b32_e32 v14, v32
	v_mov_b32_e32 v8, v33
	v_mov_b32_e32 v22, v30
	v_mov_b32_e32 v15, v24
	v_mov_b32_e32 v16, v22
	v_cvt_pk_bf16_f32 v15, v15, v8
	v_or_b32_e32 v8, s46, v93
	s_ashr_i32 s26, s46, 31
	v_cvt_pk_bf16_f32 v14, v16, v14
	v_mul_lo_u32 v16, s31, v8
	s_mul_i32 s36, s30, s26
	v_mad_u64_u32 v[30:31], s[26:27], s30, v8, 0
	v_add3_u32 v31, v31, s36, v16
	v_lshl_add_u64 v[30:31], v[30:31], 1, s[28:29]
	s_lshl_b64 s[26:27], s[34:35], 1
	v_lshl_add_u64 v[30:31], v[30:31], 0, s[26:27]
	v_mov_b32_e32 v113, v91
	v_mov_b32_e32 v16, v9
	v_mov_b32_e32 v28, v27
	v_cvt_pk_bf16_f32 v13, v13, v18
	v_cvt_pk_bf16_f32 v12, v12, v20
	v_lshl_add_u64 v[30:31], v[30:31], 0, v[112:113]
	v_pk_mul_f32 v[8:9], v[6:7], v[16:17]
	v_mov_b32_e32 v20, v19
	v_pk_mul_f32 v[16:17], v[10:11], v[28:29]
	global_store_dwordx4 v[30:31], v[12:15], off
	v_mov_b32_e32 v24, v23
	s_nop 0
	v_pk_mul_f32 v[12:13], v[4:5], v[20:21]
	v_pk_mul_f32 v[14:15], v[2:3], v[24:25]
	v_cvt_pk_bf16_f32 v12, v8, v12
	v_or_b32_e32 v8, s46, v116
	v_cvt_pk_bf16_f32 v14, v14, v16
	v_cvt_pk_bf16_f32 v13, v9, v13
	v_mul_lo_u32 v16, s31, v8
	v_mad_u64_u32 v[8:9], s[34:35], s30, v8, 0
	v_add3_u32 v9, v9, s36, v16
	v_lshl_add_u64 v[8:9], v[8:9], 1, s[28:29]
	v_lshl_add_u64 v[8:9], v[8:9], 0, s[26:27]
	v_cvt_pk_bf16_f32 v15, v15, v17
	v_lshl_add_u64 v[8:9], v[8:9], 0, v[112:113]
	ds_read2_b32 v[16:17], v123 offset0:16 offset1:24
	ds_read2_b32 v[18:19], v123 offset0:82 offset1:90
	global_store_dwordx4 v[8:9], v[12:15], off
	ds_read2_b32 v[8:9], v123 offset0:49 offset1:57
	ds_read2_b32 v[20:21], v123 offset0:115 offset1:123
	ds_read2_b32 v[22:23], v123 offset0:148 offset1:156
	ds_read2_b32 v[24:25], v123 offset0:214 offset1:222
	ds_read2_b32 v[26:27], v123 offset0:181 offset1:189
	ds_read2_b32 v[28:29], v123 offset0:247 offset1:255
	s_waitcnt lgkmcnt(7)
	v_mov_b32_e32 v12, v16
	s_waitcnt lgkmcnt(5)
	v_mov_b32_e32 v14, v8
	s_waitcnt lgkmcnt(4)
	v_mov_b32_e32 v15, v20
	s_waitcnt lgkmcnt(3)
	v_mov_b32_e32 v30, v22
	s_waitcnt lgkmcnt(2)
	v_mov_b32_e32 v31, v24
	v_mov_b32_e32 v13, v18
	v_pk_mul_f32 v[14:15], v[4:5], v[14:15]
	v_pk_mul_f32 v[30:31], v[2:3], v[30:31]
	s_waitcnt lgkmcnt(1)
	v_mov_b32_e32 v32, v26
	s_waitcnt lgkmcnt(0)
	v_mov_b32_e32 v33, v28
	v_pk_mul_f32 v[12:13], v[6:7], v[12:13]
	v_pk_mul_f32 v[32:33], v[10:11], v[32:33]
	v_bfe_u32 v16, v32, 16, 1
	v_mov_b32_e32 v18, v15
	v_bfe_u32 v22, v30, 16, 1
	v_mov_b32_e32 v24, v31
	v_mov_b32_e32 v20, v14
	v_add3_u32 v14, v32, v16, s95
	v_mov_b32_e32 v8, v33
	v_add3_u32 v22, v30, v22, s95
	v_mov_b32_e32 v15, v24
	v_lshrrev_b32_e32 v16, 16, v22
	v_cvt_pk_bf16_f32 v15, v15, v8
	v_or_b32_e32 v8, s46, v117
	v_and_or_b32 v14, v14, s91, v16
	v_mul_lo_u32 v16, s31, v8
	v_mad_u64_u32 v[30:31], s[34:35], s30, v8, 0
	v_add3_u32 v31, v31, s36, v16
	v_lshl_add_u64 v[30:31], v[30:31], 1, s[28:29]
	v_cvt_pk_bf16_f32 v12, v12, v20
	v_lshl_add_u64 v[30:31], v[30:31], 0, s[26:27]
	v_mov_b32_e32 v20, v9
	v_mov_b32_e32 v28, v27
	v_cvt_pk_bf16_f32 v13, v13, v18
	v_lshl_add_u64 v[30:31], v[30:31], 0, v[112:113]
	v_mov_b32_e32 v18, v17
	v_pk_mul_f32 v[4:5], v[4:5], v[20:21]
	v_mov_b32_e32 v24, v23
	v_pk_mul_f32 v[8:9], v[10:11], v[28:29]
	global_store_dwordx4 v[30:31], v[12:15], off
	v_pk_mul_f32 v[6:7], v[6:7], v[18:19]
	v_pk_mul_f32 v[2:3], v[2:3], v[24:25]
	v_bfe_u32 v10, v9, 16, 1
	v_bfe_u32 v11, v8, 16, 1
	v_bfe_u32 v12, v5, 16, 1
	v_bfe_u32 v13, v4, 16, 1
	v_add3_u32 v13, v4, v13, s95
	v_add3_u32 v12, v5, v12, s95
	v_add3_u32 v4, v8, v11, s95
	v_add3_u32 v5, v9, v10, s95
	v_bfe_u32 v8, v6, 16, 1
	v_bfe_u32 v10, v2, 16, 1
	v_bfe_u32 v9, v7, 16, 1
	v_bfe_u32 v11, v3, 16, 1
	v_add3_u32 v2, v2, v10, s95
	v_add3_u32 v6, v6, v8, s95
	v_add3_u32 v3, v3, v11, s95
	v_add3_u32 v7, v7, v9, s95
	v_lshrrev_b32_e32 v6, 16, v6
	v_lshrrev_b32_e32 v2, 16, v2
	v_lshrrev_b32_e32 v7, 16, v7
	v_lshrrev_b32_e32 v3, 16, v3
	v_and_or_b32 v4, v4, s91, v2
	v_and_or_b32 v2, v13, s91, v6
	v_or_b32_e32 v6, s46, v118
	v_and_or_b32 v5, v5, s91, v3
	v_and_or_b32 v3, v12, s91, v7
	v_mul_lo_u32 v8, s31, v6
	v_mad_u64_u32 v[6:7], s[30:31], s30, v6, 0
	v_add3_u32 v7, v7, s36, v8
	v_lshl_add_u64 v[6:7], v[6:7], 1, s[28:29]
	v_lshl_add_u64 v[6:7], v[6:7], 0, s[26:27]
	v_lshl_add_u64 v[6:7], v[6:7], 0, v[112:113]
	global_store_dwordx4 v[6:7], v[2:5], off
	s_waitcnt lgkmcnt(0)
	v_readlane_b32 s26, v249, 19
	s_add_i32 s33, s33, 1
	s_add_i32 s3, s3, s26
	s_cmpk_gt_i32 s3, 0x4ff
	v_readlane_b32 s27, v249, 20
	s_cbranch_scc1 .LBB0_2165

.LBB0_2138:
	ds_read2_b32 v[8:9], v123 offset1:8
	ds_read2_b32 v[16:17], v123 offset0:66 offset1:74
	ds_read2_b32 v[18:19], v123 offset0:33 offset1:41
	ds_read2_b32 v[20:21], v123 offset0:99 offset1:107
	ds_read2_b32 v[22:23], v123 offset0:132 offset1:140
	ds_read2_b32 v[24:25], v123 offset0:198 offset1:206
	ds_read2_b32 v[26:27], v123 offset0:165 offset1:173
	ds_read2_b32 v[28:29], v123 offset0:231 offset1:239
	s_waitcnt lgkmcnt(7)
	v_mov_b32_e32 v12, v8
	s_waitcnt lgkmcnt(5)
	v_mov_b32_e32 v14, v18
	s_waitcnt lgkmcnt(4)
	v_mov_b32_e32 v15, v20
	s_waitcnt lgkmcnt(3)
	v_mov_b32_e32 v30, v22
	s_waitcnt lgkmcnt(2)
	v_mov_b32_e32 v31, v24
	v_mov_b32_e32 v13, v16
	v_pk_mul_f32 v[14:15], v[4:5], v[14:15]
	v_pk_mul_f32 v[30:31], v[2:3], v[30:31]
	s_waitcnt lgkmcnt(1)
	v_mov_b32_e32 v32, v26
	s_waitcnt lgkmcnt(0)
	v_mov_b32_e32 v33, v28
	v_pk_mul_f32 v[12:13], v[6:7], v[12:13]
	v_pk_mul_f32 v[32:33], v[10:11], v[32:33]
	v_mov_b32_e32 v18, v15
	v_mov_b32_e32 v24, v31
	v_mov_b32_e32 v20, v14
	v_mov_b32_e32 v14, v32
	v_mov_b32_e32 v8, v33
	v_mov_b32_e32 v22, v30
	v_mov_b32_e32 v15, v24
	v_mov_b32_e32 v16, v22
	v_cvt_pk_bf16_f32 v15, v15, v8
	v_or_b32_e32 v8, s81, v93
	s_ashr_i32 s28, s81, 31
	v_cvt_pk_bf16_f32 v14, v16, v14
	v_mul_lo_u32 v16, s75, v8
	s_mul_i32 s34, s74, s28
	v_mad_u64_u32 v[30:31], s[28:29], s74, v8, 0
	v_add3_u32 v31, v31, s34, v16
	v_lshl_add_u64 v[30:31], v[30:31], 1, s[72:73]
	s_lshl_b64 s[28:29], s[76:77], 1
	v_lshl_add_u64 v[30:31], v[30:31], 0, s[28:29]
	v_mov_b32_e32 v113, v91
	v_mov_b32_e32 v16, v9
	v_mov_b32_e32 v28, v27
	v_cvt_pk_bf16_f32 v13, v13, v18
	v_cvt_pk_bf16_f32 v12, v12, v20
	v_lshl_add_u64 v[30:31], v[30:31], 0, v[112:113]
	v_pk_mul_f32 v[8:9], v[6:7], v[16:17]
	v_mov_b32_e32 v20, v19
	v_pk_mul_f32 v[16:17], v[10:11], v[28:29]
	global_store_dwordx4 v[30:31], v[12:15], off
	v_mov_b32_e32 v24, v23
	s_nop 0
	v_pk_mul_f32 v[12:13], v[4:5], v[20:21]
	v_pk_mul_f32 v[14:15], v[2:3], v[24:25]
	v_cvt_pk_bf16_f32 v12, v8, v12
	v_or_b32_e32 v8, s81, v116
	v_cvt_pk_bf16_f32 v14, v14, v16
	v_cvt_pk_bf16_f32 v13, v9, v13
	v_mul_lo_u32 v16, s75, v8
	v_mad_u64_u32 v[8:9], s[30:31], s74, v8, 0
	v_add3_u32 v9, v9, s34, v16
	v_lshl_add_u64 v[8:9], v[8:9], 1, s[72:73]
	v_lshl_add_u64 v[8:9], v[8:9], 0, s[28:29]
	v_cvt_pk_bf16_f32 v15, v15, v17
	v_lshl_add_u64 v[8:9], v[8:9], 0, v[112:113]
	ds_read2_b32 v[16:17], v123 offset0:16 offset1:24
	ds_read2_b32 v[18:19], v123 offset0:82 offset1:90
	global_store_dwordx4 v[8:9], v[12:15], off
	ds_read2_b32 v[8:9], v123 offset0:49 offset1:57
	ds_read2_b32 v[20:21], v123 offset0:115 offset1:123
	ds_read2_b32 v[22:23], v123 offset0:148 offset1:156
	ds_read2_b32 v[24:25], v123 offset0:214 offset1:222
	ds_read2_b32 v[26:27], v123 offset0:181 offset1:189
	ds_read2_b32 v[28:29], v123 offset0:247 offset1:255
	s_waitcnt lgkmcnt(7)
	v_mov_b32_e32 v12, v16
	s_waitcnt lgkmcnt(5)
	v_mov_b32_e32 v14, v8
	s_waitcnt lgkmcnt(4)
	v_mov_b32_e32 v15, v20
	s_waitcnt lgkmcnt(3)
	v_mov_b32_e32 v30, v22
	s_waitcnt lgkmcnt(2)
	v_mov_b32_e32 v31, v24
	v_mov_b32_e32 v13, v18
	v_pk_mul_f32 v[14:15], v[4:5], v[14:15]
	v_pk_mul_f32 v[30:31], v[2:3], v[30:31]
	s_waitcnt lgkmcnt(1)
	v_mov_b32_e32 v32, v26
	s_waitcnt lgkmcnt(0)
	v_mov_b32_e32 v33, v28
	v_pk_mul_f32 v[12:13], v[6:7], v[12:13]
	v_pk_mul_f32 v[32:33], v[10:11], v[32:33]
	v_bfe_u32 v16, v32, 16, 1
	v_mov_b32_e32 v18, v15
	v_bfe_u32 v22, v30, 16, 1
	v_mov_b32_e32 v24, v31
	v_mov_b32_e32 v20, v14
	v_add3_u32 v14, v32, v16, s95
	v_mov_b32_e32 v8, v33
	v_add3_u32 v22, v30, v22, s95
	v_mov_b32_e32 v15, v24
	v_lshrrev_b32_e32 v16, 16, v22
	v_cvt_pk_bf16_f32 v15, v15, v8
	v_or_b32_e32 v8, s81, v117
	v_and_or_b32 v14, v14, s91, v16
	v_mul_lo_u32 v16, s75, v8
	v_mad_u64_u32 v[30:31], s[30:31], s74, v8, 0
	v_add3_u32 v31, v31, s34, v16
	v_lshl_add_u64 v[30:31], v[30:31], 1, s[72:73]
	v_cvt_pk_bf16_f32 v12, v12, v20
	v_lshl_add_u64 v[30:31], v[30:31], 0, s[28:29]
	v_mov_b32_e32 v20, v9
	v_mov_b32_e32 v28, v27
	v_cvt_pk_bf16_f32 v13, v13, v18
	v_lshl_add_u64 v[30:31], v[30:31], 0, v[112:113]
	v_mov_b32_e32 v18, v17
	v_pk_mul_f32 v[4:5], v[4:5], v[20:21]
	v_mov_b32_e32 v24, v23
	v_pk_mul_f32 v[8:9], v[10:11], v[28:29]
	global_store_dwordx4 v[30:31], v[12:15], off
	v_pk_mul_f32 v[6:7], v[6:7], v[18:19]
	v_pk_mul_f32 v[2:3], v[2:3], v[24:25]
	v_bfe_u32 v10, v9, 16, 1
	v_bfe_u32 v11, v8, 16, 1
	v_bfe_u32 v12, v5, 16, 1
	v_bfe_u32 v13, v4, 16, 1
	v_add3_u32 v13, v4, v13, s95
	v_add3_u32 v12, v5, v12, s95
	v_add3_u32 v4, v8, v11, s95
	v_add3_u32 v5, v9, v10, s95
	v_bfe_u32 v8, v6, 16, 1
	v_bfe_u32 v10, v2, 16, 1
	v_bfe_u32 v9, v7, 16, 1
	v_bfe_u32 v11, v3, 16, 1
	v_add3_u32 v2, v2, v10, s95
	v_add3_u32 v6, v6, v8, s95
	v_add3_u32 v3, v3, v11, s95
	v_add3_u32 v7, v7, v9, s95
	v_lshrrev_b32_e32 v6, 16, v6
	v_lshrrev_b32_e32 v2, 16, v2
	v_lshrrev_b32_e32 v7, 16, v7
	v_lshrrev_b32_e32 v3, 16, v3
	v_and_or_b32 v4, v4, s91, v2
	v_and_or_b32 v2, v13, s91, v6
	v_or_b32_e32 v6, s81, v118
	v_and_or_b32 v5, v5, s91, v3
	v_and_or_b32 v3, v12, s91, v7
	v_mul_lo_u32 v8, s75, v6
	v_mad_u64_u32 v[6:7], s[30:31], s74, v6, 0
	v_add3_u32 v7, v7, s34, v8
	v_lshl_add_u64 v[6:7], v[6:7], 1, s[72:73]
	v_lshl_add_u64 v[6:7], v[6:7], 0, s[28:29]
	v_lshl_add_u64 v[6:7], v[6:7], 0, v[112:113]
	global_store_dwordx4 v[6:7], v[2:5], off
	s_waitcnt lgkmcnt(0)
	s_add_i32 s35, s80, s92
	s_cmp_gt_i32 s35, 0x807f
	s_cbranch_scc0 .LBB0_2152
	s_cmpk_gt_u32 s35, 0xa07f
	s_cbranch_scc0 .LBB0_2153
	s_cmp_lt_u32 s35, 0x14c80
	s_cselect_b64 s[28:29], -1, 0
	s_add_i32 s30, s35, 0xfffe1580
	s_cmpk_lt_u32 s30, 0xac00
	s_cselect_b64 s[30:31], -1, 0
	s_or_b64 s[28:29], s[28:29], s[30:31]
	s_andn2_b64 vcc, exec, s[28:29]
	s_mov_b64 s[42:43], -1
	s_cbranch_vccz .LBB0_2149
	s_add_i32 s28, s35, 0xfffd6980
	s_cmp_gt_u32 s28, 0xffff0bff
	s_mov_b64 s[30:31], -1
	s_cbranch_scc0 .LBB0_2146
	s_cmp_gt_u32 s35, 0x1ca7f
	s_mov_b64 s[28:29], -1
	s_cbranch_scc0 .LBB0_2144
	s_add_i32 s28, s35, 0xfffe3580
	v_readlane_b32 s68, v250, 18
	s_lshl_b32 s29, s35, 5
	s_lshr_b32 s28, s28, 1
	v_readlane_b32 s76, v250, 26
	v_readlane_b32 s77, v250, 27
	s_and_b32 s46, s29, 0xfe0
	s_and_b32 s34, s28, 0x7fffffc0
	s_mov_b64 s[28:29], 0
	v_readlane_b32 s69, v250, 19
	v_readlane_b32 s70, v250, 20
	v_readlane_b32 s71, v250, 21
	v_readlane_b32 s72, v250, 22
	v_readlane_b32 s73, v250, 23
	v_readlane_b32 s74, v250, 24
	v_readlane_b32 s75, v250, 25
	v_readlane_b32 s78, v250, 28
	v_readlane_b32 s79, v250, 29
	v_readlane_b32 s80, v250, 30
	v_readlane_b32 s81, v250, 31
	v_readlane_b32 s82, v250, 32
	v_readlane_b32 s83, v250, 33
	s_mov_b64 s[38:39], s[76:77]

.LBB0_2301:
	global_load_dwordx4 v[78:81], v[84:85], off offset:-3072
	global_load_dwordx4 v[74:77], v[84:85], off offset:-2048
	global_load_dwordx4 v[70:73], v[84:85], off offset:-1024
	global_load_dwordx4 v[66:69], v[84:85], off
	v_add_co_u32_e32 v90, vcc, 0xfffff000, v84
	v_add_co_u32_e64 v86, s[4:5], s14, v84
	s_nop 0
	v_addc_co_u32_e32 v91, vcc, -1, v85, vcc
	global_load_dwordx4 v[100:103], v[90:91], off offset:-3072
	global_load_dwordx4 v[104:107], v[90:91], off offset:-2048
	global_load_dwordx4 v[108:111], v[90:91], off offset:-1024
	global_load_dwordx4 v[112:115], v[84:85], off offset:-4096
	v_addc_co_u32_e64 v87, s[4:5], -1, v85, s[4:5]
	v_add_co_u32_e64 v88, s[4:5], s15, v84
	s_add_i32 s16, s16, s92
	s_nop 0
	v_addc_co_u32_e64 v89, s[4:5], -1, v85, s[4:5]
	s_cmpk_gt_i32 s16, 0x1fff
	v_lshl_add_u64 v[84:85], v[84:85], 0, s[10:11]
	s_waitcnt vmcnt(7)
	v_lshlrev_b32_e32 v91, 16, v80
	v_lshlrev_b32_e32 v90, 16, v78
	v_and_b32_e32 v117, 0xffff0000, v80
	v_and_b32_e32 v116, 0xffff0000, v78
	v_lshlrev_b32_e32 v119, 16, v81
	v_lshlrev_b32_e32 v118, 16, v79
	v_and_b32_e32 v81, 0xffff0000, v81
	v_and_b32_e32 v80, 0xffff0000, v79
	s_waitcnt vmcnt(6)
	v_lshlrev_b32_e32 v79, 16, v75
	v_lshlrev_b32_e32 v78, 16, v74
	v_and_b32_e32 v75, 0xffff0000, v75
	v_and_b32_e32 v74, 0xffff0000, v74
	v_lshlrev_b32_e32 v121, 16, v77
	v_lshlrev_b32_e32 v120, 16, v76
	v_and_b32_e32 v77, 0xffff0000, v77
	v_and_b32_e32 v76, 0xffff0000, v76
	s_waitcnt vmcnt(5)
	v_lshlrev_b32_e32 v122, 16, v70
	v_and_b32_e32 v123, 0xffff0000, v70
	v_lshlrev_b32_e32 v70, 16, v71
	v_and_b32_e32 v71, 0xffff0000, v71
	v_lshlrev_b32_e32 v124, 16, v72
	v_and_b32_e32 v125, 0xffff0000, v72
	v_lshlrev_b32_e32 v72, 16, v73
	v_and_b32_e32 v73, 0xffff0000, v73
	s_waitcnt vmcnt(4)
	v_lshlrev_b32_e32 v128, 16, v68
	v_and_b32_e32 v129, 0xffff0000, v68
	v_lshlrev_b32_e32 v68, 16, v69
	v_and_b32_e32 v69, 0xffff0000, v69
	v_pk_mul_f32 v[130:131], v[116:117], v[116:117]
	v_pk_mul_f32 v[132:133], v[80:81], v[80:81]
	v_pk_mul_f32 v[134:135], v[74:75], v[74:75]
	v_pk_mul_f32 v[136:137], v[76:77], v[76:77]
	v_mul_f32_e32 v138, v123, v123
	v_mul_f32_e32 v140, v71, v71
	v_mul_f32_e32 v142, v125, v125
	v_mul_f32_e32 v144, v73, v73
	s_waitcnt vmcnt(3)
	v_lshlrev_b32_e32 v155, 16, v101
	v_lshlrev_b32_e32 v154, 16, v100
	v_and_b32_e32 v101, 0xffff0000, v101
	v_and_b32_e32 v100, 0xffff0000, v100
	v_lshlrev_b32_e32 v157, 16, v103
	v_lshlrev_b32_e32 v156, 16, v102
	v_and_b32_e32 v103, 0xffff0000, v103
	v_and_b32_e32 v102, 0xffff0000, v102
	s_waitcnt vmcnt(2)
	v_lshlrev_b32_e32 v159, 16, v105
	v_lshlrev_b32_e32 v158, 16, v104
	v_and_b32_e32 v105, 0xffff0000, v105
	v_and_b32_e32 v104, 0xffff0000, v104
	v_lshlrev_b32_e32 v161, 16, v107
	v_lshlrev_b32_e32 v160, 16, v106
	v_and_b32_e32 v107, 0xffff0000, v107
	v_and_b32_e32 v106, 0xffff0000, v106
	v_lshlrev_b32_e32 v126, 16, v66
	v_and_b32_e32 v127, 0xffff0000, v66
	v_lshlrev_b32_e32 v66, 16, v67
	v_mul_f32_e32 v184, v128, v128
	v_mul_f32_e32 v185, v129, v129
	v_mul_f32_e32 v186, v68, v68
	v_mul_f32_e32 v187, v69, v69
	v_mov_b32_e32 v146, v90
	v_mov_b32_e32 v147, v116
	v_mov_b32_e32 v148, v118
	v_mov_b32_e32 v149, v80
	v_mov_b32_e32 v116, v91
	v_mov_b32_e32 v80, v119
	v_mov_b32_e32 v150, v78
	v_mov_b32_e32 v151, v74
	v_mov_b32_e32 v74, v79
	v_mov_b32_e32 v152, v120
	v_mov_b32_e32 v153, v76
	v_mov_b32_e32 v76, v121
	s_waitcnt vmcnt(1)
	v_lshlrev_b32_e32 v168, 16, v108
	v_and_b32_e32 v169, 0xffff0000, v108
	v_lshlrev_b32_e32 v108, 16, v109
	v_and_b32_e32 v109, 0xffff0000, v109
	v_lshlrev_b32_e32 v170, 16, v110
	v_and_b32_e32 v171, 0xffff0000, v110
	v_lshlrev_b32_e32 v110, 16, v111
	v_and_b32_e32 v111, 0xffff0000, v111
	v_pk_fma_f32 v[90:91], v[90:91], v[90:91], v[130:131]
	v_pk_fma_f32 v[118:119], v[118:119], v[118:119], v[132:133]
	v_pk_fma_f32 v[78:79], v[78:79], v[78:79], v[134:135]
	v_pk_fma_f32 v[120:121], v[120:121], v[120:121], v[136:137]
	v_pk_fma_f32 v[130:131], v[122:123], v[122:123], v[138:139] op_sel_hi:[1,1,0]
	v_pk_fma_f32 v[132:133], v[70:71], v[70:71], v[140:141] op_sel_hi:[1,1,0]
	v_pk_fma_f32 v[134:135], v[124:125], v[124:125], v[142:143] op_sel_hi:[1,1,0]
	v_pk_fma_f32 v[136:137], v[72:73], v[72:73], v[144:145] op_sel_hi:[1,1,0]
	v_pk_mul_f32 v[138:139], v[100:101], v[100:101]
	v_pk_mul_f32 v[140:141], v[102:103], v[102:103]
	v_pk_mul_f32 v[142:143], v[104:105], v[104:105]
	v_pk_mul_f32 v[144:145], v[106:107], v[106:107]
	v_and_b32_e32 v67, 0xffff0000, v67
	v_mul_f32_e32 v179, v126, v126
	v_mul_f32_e32 v181, v127, v127
	v_mul_f32_e32 v183, v66, v66
	s_waitcnt vmcnt(0)
	v_lshlrev_b32_e32 v172, 16, v112
	v_and_b32_e32 v173, 0xffff0000, v112
	v_lshlrev_b32_e32 v112, 16, v113
	v_and_b32_e32 v113, 0xffff0000, v113
	v_lshlrev_b32_e32 v176, 16, v114
	v_and_b32_e32 v177, 0xffff0000, v114
	v_lshlrev_b32_e32 v114, 16, v115
	v_and_b32_e32 v115, 0xffff0000, v115
	v_mul_f32_e32 v174, v169, v169
	v_mul_f32_e32 v178, v109, v109
	v_mul_f32_e32 v180, v171, v171
	v_mul_f32_e32 v182, v111, v111
	v_mov_b32_e32 v131, v184
	v_mov_b32_e32 v133, v185
	v_mov_b32_e32 v135, v186
	v_mov_b32_e32 v137, v187
	v_pk_fma_f32 v[138:139], v[154:155], v[154:155], v[138:139]
	v_pk_fma_f32 v[140:141], v[156:157], v[156:157], v[140:141]
	v_pk_fma_f32 v[142:143], v[158:159], v[158:159], v[142:143]
	v_pk_fma_f32 v[144:145], v[160:161], v[160:161], v[144:145]
	v_mul_f32_e32 v190, v67, v67
	v_mul_f32_e32 v191, v172, v172
	v_mul_f32_e32 v192, v173, v173
	v_mul_f32_e32 v193, v112, v112
	v_mul_f32_e32 v194, v113, v113
	v_mul_f32_e32 v195, v176, v176
	v_mul_f32_e32 v196, v177, v177
	v_mul_f32_e32 v197, v114, v114
	v_mul_f32_e32 v203, v115, v115
	v_pk_add_f32 v[90:91], v[90:91], v[118:119]
	v_pk_add_f32 v[78:79], v[78:79], v[78:79] op_sel:[0,1] op_sel_hi:[1,0]
	v_pk_add_f32 v[118:119], v[120:121], v[120:121] op_sel:[0,1] op_sel_hi:[1,0]
	v_mov_b32_e32 v120, v154
	v_mov_b32_e32 v121, v100
	v_mov_b32_e32 v100, v155
	v_mov_b32_e32 v184, v156
	v_mov_b32_e32 v185, v102
	v_mov_b32_e32 v102, v157
	v_mov_b32_e32 v186, v158
	v_mov_b32_e32 v187, v104
	v_mov_b32_e32 v104, v159
	v_mov_b32_e32 v188, v160
	v_mov_b32_e32 v189, v106
	v_mov_b32_e32 v106, v161
	v_pk_fma_f32 v[154:155], v[168:169], v[168:169], v[174:175] op_sel_hi:[1,1,0]
	v_pk_fma_f32 v[156:157], v[108:109], v[108:109], v[178:179] op_sel_hi:[1,1,0]
	v_pk_fma_f32 v[158:159], v[170:171], v[170:171], v[180:181] op_sel_hi:[1,1,0]
	v_pk_fma_f32 v[160:161], v[110:111], v[110:111], v[182:183] op_sel_hi:[1,1,0]
	v_pk_add_f32 v[130:131], v[130:131], v[132:133]
	v_pk_add_f32 v[132:133], v[134:135], v[136:137]
	v_pk_add_f32 v[134:135], v[138:139], v[138:139] op_sel:[0,1] op_sel_hi:[1,0]
	v_pk_add_f32 v[136:137], v[140:141], v[140:141] op_sel:[0,1] op_sel_hi:[1,0]
	v_pk_add_f32 v[138:139], v[142:143], v[142:143] op_sel:[0,1] op_sel_hi:[1,0]
	v_pk_add_f32 v[140:141], v[144:145], v[144:145] op_sel:[0,1] op_sel_hi:[1,0]
	v_mov_b32_e32 v79, v183
	v_mov_b32_e32 v119, v190
	v_mov_b32_e32 v155, v195
	v_mov_b32_e32 v157, v196
	v_mov_b32_e32 v159, v197
	v_mov_b32_e32 v161, v203
	v_mov_b32_e32 v135, v191
	v_mov_b32_e32 v137, v192
	v_mov_b32_e32 v139, v193
	v_mov_b32_e32 v141, v194
	v_pk_add_f32 v[78:79], v[78:79], v[118:119]
	v_pk_add_f32 v[118:119], v[130:131], v[132:133]
	v_pk_add_f32 v[130:131], v[154:155], v[156:157]
	v_pk_add_f32 v[132:133], v[158:159], v[160:161]
	v_pk_add_f32 v[134:135], v[134:135], v[136:137]
	v_pk_add_f32 v[136:137], v[138:139], v[140:141]
	v_pk_add_f32 v[130:131], v[130:131], v[132:133]
	v_pk_add_f32 v[132:133], v[134:135], v[136:137]
	v_pk_add_f32 v[90:91], v[90:91], v[90:91] op_sel:[0,1] op_sel_hi:[1,0]
	v_pk_add_f32 v[130:131], v[132:133], v[130:131]
	v_mov_b32_e32 v91, v181
	v_pk_add_f32 v[130:131], v[130:131], v[130:131] op_sel:[0,1] op_sel_hi:[1,0]
	s_nop 0
	v_mov_b32_e32 v131, v179
	v_pk_add_f32 v[90:91], v[130:131], v[90:91]
	s_nop 0
	v_pk_add_f32 v[78:79], v[90:91], v[78:79]
	s_nop 0
	v_pk_add_f32 v[78:79], v[78:79], v[118:119]
	s_nop 0
	v_add_f32_e32 v78, v78, v79
	ds_bpermute_b32 v79, v93, v78
	s_waitcnt lgkmcnt(0)
	v_add_f32_e32 v78, v78, v79
	ds_bpermute_b32 v79, v94, v78
	s_waitcnt lgkmcnt(0)
	v_add_f32_e32 v78, v78, v79
	ds_bpermute_b32 v79, v95, v78
	s_waitcnt lgkmcnt(0)
	v_add_f32_e32 v78, v78, v79
	ds_bpermute_b32 v79, v96, v78
	s_waitcnt lgkmcnt(0)
	v_add_f32_e32 v78, v78, v79
	ds_bpermute_b32 v79, v97, v78
	s_waitcnt lgkmcnt(0)
	v_add_f32_e32 v78, v78, v79
	ds_bpermute_b32 v79, v98, v78
	s_waitcnt lgkmcnt(0)
	v_add_f32_e32 v78, v78, v79
	v_fmamk_f32 v78, v78, 0x39800000, v83
	v_mul_f32_e32 v79, 0x4f800000, v78
	v_cmp_gt_f32_e32 vcc, s12, v78
	s_nop 1
	v_cndmask_b32_e32 v78, v78, v79, vcc
	v_sqrt_f32_e32 v79, v78
	s_nop 0
	v_add_u32_e32 v90, -1, v79
	v_add_u32_e32 v91, 1, v79
	v_fma_f32 v118, -v90, v79, v78
	v_fma_f32 v119, -v91, v79, v78
	v_cmp_ge_f32_e64 s[4:5], 0, v118
	s_nop 1
	v_cndmask_b32_e64 v79, v79, v90, s[4:5]
	v_cmp_lt_f32_e64 s[4:5], 0, v119
	s_nop 1
	v_cndmask_b32_e64 v79, v79, v91, s[4:5]
	v_mul_f32_e32 v90, 0x37800000, v79
	v_cndmask_b32_e32 v79, v79, v90, vcc
	v_cmp_class_f32_e32 vcc, v78, v99
	s_nop 1
	v_cndmask_b32_e32 v78, v79, v78, vcc
	v_div_scale_f32 v79, s[4:5], v78, v78, 1.0
	v_rcp_f32_e32 v91, v79
	v_div_scale_f32 v90, vcc, 1.0, v78, 1.0
	v_fma_f32 v118, -v79, v91, 1.0
	v_fmac_f32_e32 v91, v118, v91
	v_mul_f32_e32 v118, v90, v91
	v_fma_f32 v119, -v79, v118, v90
	v_fmac_f32_e32 v118, v119, v91
	v_fma_f32 v79, -v79, v118, v90
	v_div_fmas_f32 v79, v79, v91, v118
	v_div_fixup_f32 v78, v79, v78, 1.0
	v_pk_mul_f32 v[90:91], v[78:79], v[120:121] op_sel_hi:[0,1]
	v_pk_mul_f32 v[100:101], v[78:79], v[100:101] op_sel_hi:[0,1]
	v_pk_mul_f32 v[118:119], v[78:79], v[184:185] op_sel_hi:[0,1]
	v_pk_mul_f32 v[102:103], v[78:79], v[102:103] op_sel_hi:[0,1]
	v_pk_mul_f32 v[120:121], v[78:79], v[186:187] op_sel_hi:[0,1]
	v_pk_mul_f32 v[104:105], v[78:79], v[104:105] op_sel_hi:[0,1]
	v_pk_mul_f32 v[130:131], v[78:79], v[188:189] op_sel_hi:[0,1]
	v_pk_mul_f32 v[106:107], v[78:79], v[106:107] op_sel_hi:[0,1]
	v_pk_mul_f32 v[132:133], v[78:79], v[168:169] op_sel_hi:[0,1]
	v_pk_mul_f32 v[108:109], v[78:79], v[108:109] op_sel_hi:[0,1]
	v_pk_mul_f32 v[134:135], v[78:79], v[170:171] op_sel_hi:[0,1]
	v_pk_mul_f32 v[110:111], v[78:79], v[110:111] op_sel_hi:[0,1]
	v_pk_mul_f32 v[136:137], v[78:79], v[172:173] op_sel_hi:[0,1]
	v_pk_mul_f32 v[112:113], v[78:79], v[112:113] op_sel_hi:[0,1]
	v_pk_mul_f32 v[138:139], v[78:79], v[176:177] op_sel_hi:[0,1]
	v_pk_mul_f32 v[114:115], v[78:79], v[114:115] op_sel_hi:[0,1]
	v_pk_mul_f32 v[140:141], v[78:79], v[146:147] op_sel_hi:[0,1]
	v_pk_mul_f32 v[142:143], v[78:79], v[148:149] op_sel_hi:[0,1]
	v_pk_mul_f32 v[116:117], v[78:79], v[116:117] op_sel_hi:[0,1]
	v_pk_mul_f32 v[80:81], v[78:79], v[80:81] op_sel_hi:[0,1]
	v_pk_mul_f32 v[144:145], v[78:79], v[150:151] op_sel_hi:[0,1]
	v_pk_mul_f32 v[74:75], v[78:79], v[74:75] op_sel_hi:[0,1]
	v_pk_mul_f32 v[146:147], v[78:79], v[152:153] op_sel_hi:[0,1]
	v_pk_mul_f32 v[76:77], v[78:79], v[76:77] op_sel_hi:[0,1]
	v_pk_mul_f32 v[122:123], v[78:79], v[122:123] op_sel_hi:[0,1]
	v_pk_mul_f32 v[70:71], v[78:79], v[70:71] op_sel_hi:[0,1]
	v_pk_mul_f32 v[124:125], v[78:79], v[124:125] op_sel_hi:[0,1]
	v_pk_mul_f32 v[72:73], v[78:79], v[72:73] op_sel_hi:[0,1]
	v_pk_mul_f32 v[126:127], v[78:79], v[126:127] op_sel_hi:[0,1]
	v_pk_mul_f32 v[66:67], v[78:79], v[66:67] op_sel_hi:[0,1]
	v_pk_mul_f32 v[128:129], v[78:79], v[128:129] op_sel_hi:[0,1]
	v_pk_mul_f32 v[68:69], v[78:79], v[68:69] op_sel_hi:[0,1]
	v_pk_mul_f32 v[78:79], v[60:61], v[100:101]
	v_pk_mul_f32 v[90:91], v[58:59], v[90:91]
	v_pk_mul_f32 v[100:101], v[4:5], v[102:103]
	v_pk_mul_f32 v[102:103], v[2:3], v[118:119]
	v_pk_mul_f32 v[104:105], v[8:9], v[104:105]
	v_pk_mul_f32 v[118:119], v[6:7], v[120:121]
	v_pk_mul_f32 v[106:107], v[28:29], v[106:107]
	v_pk_mul_f32 v[120:121], v[26:27], v[130:131]
	v_pk_mul_f32 v[108:109], v[12:13], v[108:109]
	v_pk_mul_f32 v[130:131], v[10:11], v[132:133]
	v_pk_mul_f32 v[110:111], v[16:17], v[110:111]
	v_pk_mul_f32 v[132:133], v[14:15], v[134:135]
	v_pk_mul_f32 v[112:113], v[20:21], v[112:113]
	v_pk_mul_f32 v[134:135], v[18:19], v[136:137]
	v_pk_mul_f32 v[114:115], v[24:25], v[114:115]
	v_pk_mul_f32 v[136:137], v[22:23], v[138:139]
	v_pk_mul_f32 v[138:139], v[32:33], v[142:143]
	v_pk_mul_f32 v[140:141], v[30:31], v[140:141]
	v_pk_mul_f32 v[80:81], v[36:37], v[80:81]
	v_pk_mul_f32 v[116:117], v[34:35], v[116:117]
	v_pk_mul_f32 v[74:75], v[40:41], v[74:75]
	v_pk_mul_f32 v[142:143], v[38:39], v[144:145]
	v_pk_mul_f32 v[76:77], v[44:45], v[76:77]
	v_pk_mul_f32 v[144:145], v[42:43], v[146:147]
	v_pk_mul_f32 v[70:71], v[52:53], v[70:71]
	v_pk_mul_f32 v[122:123], v[50:51], v[122:123]
	v_pk_mul_f32 v[72:73], v[48:49], v[72:73]
	v_pk_mul_f32 v[124:125], v[46:47], v[124:125]
	v_pk_mul_f32 v[66:67], v[56:57], v[66:67]
	v_pk_mul_f32 v[126:127], v[54:55], v[126:127]
	v_pk_mul_f32 v[68:69], v[64:65], v[68:69]
	v_pk_mul_f32 v[128:129], v[62:63], v[128:129]
	v_bfe_u32 v146, v90, 16, 1
	v_bfe_u32 v150, v102, 16, 1
	v_bfe_u32 v147, v91, 16, 1
	v_bfe_u32 v151, v103, 16, 1
	v_bfe_u32 v154, v118, 16, 1
	v_bfe_u32 v158, v120, 16, 1
	v_bfe_u32 v160, v106, 16, 1
	v_bfe_u32 v168, v130, 16, 1
	v_bfe_u32 v170, v108, 16, 1
	v_bfe_u32 v172, v132, 16, 1
	v_bfe_u32 v174, v110, 16, 1
	v_bfe_u32 v177, v134, 16, 1
	v_bfe_u32 v179, v112, 16, 1
	v_bfe_u32 v181, v136, 16, 1
	v_bfe_u32 v183, v114, 16, 1
	v_bfe_u32 v185, v140, 16, 1
	v_bfe_u32 v187, v138, 16, 1
	v_bfe_u32 v189, v116, 16, 1
	v_bfe_u32 v191, v80, 16, 1
	v_bfe_u32 v192, v81, 16, 1
	v_bfe_u32 v193, v142, 16, 1
	v_bfe_u32 v194, v143, 16, 1
	v_bfe_u32 v195, v74, 16, 1
	v_bfe_u32 v196, v75, 16, 1
	v_bfe_u32 v197, v144, 16, 1
	v_bfe_u32 v203, v145, 16, 1
	v_bfe_u32 v204, v76, 16, 1
	v_bfe_u32 v205, v77, 16, 1
	v_bfe_u32 v206, v122, 16, 1
	v_bfe_u32 v207, v123, 16, 1
	v_bfe_u32 v208, v70, 16, 1
	v_bfe_u32 v209, v71, 16, 1
	v_bfe_u32 v210, v124, 16, 1
	v_bfe_u32 v211, v125, 16, 1
	v_bfe_u32 v212, v72, 16, 1
	v_bfe_u32 v213, v73, 16, 1
	v_bfe_u32 v214, v126, 16, 1
	v_bfe_u32 v215, v127, 16, 1
	v_bfe_u32 v216, v66, 16, 1
	v_bfe_u32 v217, v67, 16, 1
	v_bfe_u32 v218, v128, 16, 1
	v_bfe_u32 v219, v129, 16, 1
	v_bfe_u32 v220, v68, 16, 1
	v_bfe_u32 v221, v69, 16, 1
	v_add3_u32 v90, v90, v146, s13
	v_add3_u32 v102, v102, v150, s13
	v_bfe_u32 v155, v119, 16, 1
	v_bfe_u32 v159, v121, 16, 1
	v_bfe_u32 v161, v107, 16, 1
	v_bfe_u32 v169, v131, 16, 1
	v_bfe_u32 v171, v109, 16, 1
	v_bfe_u32 v173, v133, 16, 1
	v_bfe_u32 v176, v111, 16, 1
	v_bfe_u32 v178, v135, 16, 1
	v_bfe_u32 v180, v113, 16, 1
	v_bfe_u32 v182, v137, 16, 1
	v_bfe_u32 v184, v115, 16, 1
	v_bfe_u32 v186, v141, 16, 1
	v_bfe_u32 v188, v139, 16, 1
	v_bfe_u32 v190, v117, 16, 1
	v_add3_u32 v91, v91, v147, s13
	v_add3_u32 v103, v103, v151, s13
	v_add3_u32 v118, v118, v154, s13
	v_add3_u32 v120, v120, v158, s13
	v_add3_u32 v106, v106, v160, s13
	v_add3_u32 v130, v130, v168, s13
	v_add3_u32 v108, v108, v170, s13
	v_add3_u32 v132, v132, v172, s13
	v_add3_u32 v110, v110, v174, s13
	v_add3_u32 v134, v134, v177, s13
	v_add3_u32 v112, v112, v179, s13
	v_add3_u32 v136, v136, v181, s13
	v_add3_u32 v114, v114, v183, s13
	v_add3_u32 v140, v140, v185, s13
	v_add3_u32 v138, v138, v187, s13
	v_add3_u32 v116, v116, v189, s13
	v_add3_u32 v80, v80, v191, s13
	v_add3_u32 v146, v81, v192, s13
	v_add3_u32 v81, v142, v193, s13
	v_add3_u32 v142, v143, v194, s13
	v_add3_u32 v74, v74, v195, s13
	v_add3_u32 v143, v75, v196, s13
	v_add3_u32 v75, v144, v197, s13
	v_add3_u32 v144, v145, v203, s13
	v_add3_u32 v76, v76, v204, s13
	v_add3_u32 v145, v77, v205, s13
	v_add3_u32 v77, v122, v206, s13
	v_add3_u32 v122, v123, v207, s13
	v_add3_u32 v70, v70, v208, s13
	v_add3_u32 v123, v71, v209, s13
	v_add3_u32 v71, v124, v210, s13
	v_add3_u32 v124, v125, v211, s13
	v_add3_u32 v72, v72, v212, s13
	v_add3_u32 v125, v73, v213, s13
	v_add3_u32 v73, v126, v214, s13
	v_add3_u32 v126, v127, v215, s13
	v_add3_u32 v66, v66, v216, s13
	v_add3_u32 v127, v67, v217, s13
	v_add3_u32 v67, v128, v218, s13
	v_add3_u32 v128, v129, v219, s13
	v_add3_u32 v68, v68, v220, s13
	v_add3_u32 v129, v69, v221, s13
	v_lshrrev_b32_e32 v69, 16, v90
	v_lshrrev_b32_e32 v90, 16, v102
	v_add3_u32 v119, v119, v155, s13
	v_add3_u32 v121, v121, v159, s13
	v_add3_u32 v107, v107, v161, s13
	v_add3_u32 v131, v131, v169, s13
	v_add3_u32 v109, v109, v171, s13
	v_add3_u32 v133, v133, v173, s13
	v_add3_u32 v111, v111, v176, s13
	v_add3_u32 v135, v135, v178, s13
	v_add3_u32 v113, v113, v180, s13
	v_add3_u32 v137, v137, v182, s13
	v_add3_u32 v115, v115, v184, s13
	v_add3_u32 v141, v141, v186, s13
	v_add3_u32 v139, v139, v188, s13
	v_add3_u32 v117, v117, v190, s13
	v_lshrrev_b32_e32 v102, 16, v118
	v_lshrrev_b32_e32 v118, 16, v120
	v_lshrrev_b32_e32 v106, 16, v106
	v_lshrrev_b32_e32 v120, 16, v130
	v_lshrrev_b32_e32 v108, 16, v108
	v_lshrrev_b32_e32 v130, 16, v132
	v_lshrrev_b32_e32 v110, 16, v110
	v_lshrrev_b32_e32 v132, 16, v134
	v_lshrrev_b32_e32 v112, 16, v112
	v_lshrrev_b32_e32 v134, 16, v136
	v_lshrrev_b32_e32 v114, 16, v114
	v_lshrrev_b32_e32 v136, 16, v140
	v_lshrrev_b32_e32 v138, 16, v138
	v_lshrrev_b32_e32 v116, 16, v116
	v_lshrrev_b32_e32 v140, 16, v80
	v_lshrrev_b32_e32 v147, 16, v81
	v_lshrrev_b32_e32 v148, 16, v74
	v_lshrrev_b32_e32 v149, 16, v75
	v_lshrrev_b32_e32 v150, 16, v76
	v_lshrrev_b32_e32 v151, 16, v77
	v_lshrrev_b32_e32 v152, 16, v70
	v_lshrrev_b32_e32 v153, 16, v71
	v_lshrrev_b32_e32 v154, 16, v72
	v_lshrrev_b32_e32 v155, 16, v73
	v_lshrrev_b32_e32 v156, 16, v66
	v_lshrrev_b32_e32 v157, 16, v67
	v_lshrrev_b32_e32 v158, 16, v68
	v_and_or_b32 v66, v91, s3, v69
	v_cvt_pk_bf16_f32 v67, v78, v79
	v_and_or_b32 v68, v103, s3, v90
	v_cvt_pk_bf16_f32 v69, v100, v101
	v_and_or_b32 v70, v119, s3, v102
	v_cvt_pk_bf16_f32 v71, v104, v105
	v_and_or_b32 v72, v121, s3, v118
	v_and_or_b32 v73, v107, s3, v106
	v_and_or_b32 v74, v131, s3, v120
	v_and_or_b32 v75, v109, s3, v108
	v_and_or_b32 v76, v133, s3, v130
	v_and_or_b32 v77, v111, s3, v110
	v_and_or_b32 v78, v135, s3, v132
	v_and_or_b32 v79, v113, s3, v112
	v_and_or_b32 v80, v137, s3, v134
	v_and_or_b32 v81, v115, s3, v114
	v_and_or_b32 v100, v141, s3, v136
	v_and_or_b32 v101, v139, s3, v138
	v_and_or_b32 v102, v117, s3, v116
	v_and_or_b32 v103, v146, s3, v140
	v_and_or_b32 v104, v142, s3, v147
	v_and_or_b32 v105, v143, s3, v148
	v_and_or_b32 v106, v144, s3, v149
	v_and_or_b32 v107, v145, s3, v150
	v_and_or_b32 v108, v122, s3, v151
	v_and_or_b32 v109, v123, s3, v152
	v_and_or_b32 v110, v124, s3, v153
	v_and_or_b32 v111, v125, s3, v154
	v_and_or_b32 v112, v126, s3, v155
	v_and_or_b32 v113, v127, s3, v156
	v_and_or_b32 v114, v128, s3, v157
	v_and_or_b32 v115, v129, s3, v158
	global_store_dwordx4 v[86:87], v[66:69], off offset:-3072
	global_store_dwordx4 v[86:87], v[70:73], off offset:-2048
	global_store_dwordx4 v[86:87], v[74:77], off offset:-1024
	global_store_dwordx4 v[88:89], v[78:81], off offset:-4096
	global_store_dwordx4 v[88:89], v[100:103], off offset:-3072
	global_store_dwordx4 v[88:89], v[104:107], off offset:-2048
	global_store_dwordx4 v[88:89], v[108:111], off offset:-1024
	global_store_dwordx4 v[88:89], v[112:115], off
	s_cbranch_scc0 .LBB0_2301

.LBB0_2462:
	ds_read2_b32 v[104:105], v153 offset1:8
	ds_read2_b32 v[112:113], v153 offset0:66 offset1:74
	ds_read2_b32 v[114:115], v153 offset0:33 offset1:41
	ds_read2_b32 v[116:117], v153 offset0:99 offset1:107
	ds_read2_b32 v[118:119], v153 offset0:132 offset1:140
	ds_read2_b32 v[120:121], v153 offset0:198 offset1:206
	ds_read2_b32 v[122:123], v153 offset0:165 offset1:173
	ds_read2_b32 v[124:125], v153 offset0:231 offset1:239
	s_waitcnt lgkmcnt(7)
	v_mov_b32_e32 v108, v104
	s_waitcnt lgkmcnt(5)
	v_mov_b32_e32 v110, v114
	s_waitcnt lgkmcnt(4)
	v_mov_b32_e32 v111, v116
	s_waitcnt lgkmcnt(3)
	v_mov_b32_e32 v126, v118
	s_waitcnt lgkmcnt(2)
	v_mov_b32_e32 v127, v120
	v_mov_b32_e32 v109, v112
	v_pk_mul_f32 v[110:111], v[100:101], v[110:111]
	v_pk_mul_f32 v[126:127], v[98:99], v[126:127]
	s_waitcnt lgkmcnt(1)
	v_mov_b32_e32 v128, v122
	s_waitcnt lgkmcnt(0)
	v_mov_b32_e32 v129, v124
	v_pk_mul_f32 v[108:109], v[102:103], v[108:109]
	v_pk_mul_f32 v[128:129], v[106:107], v[128:129]
	v_mov_b32_e32 v114, v111
	v_mov_b32_e32 v120, v127
	v_mov_b32_e32 v116, v110
	v_mov_b32_e32 v110, v128
	v_mov_b32_e32 v104, v129
	v_mov_b32_e32 v118, v126
	v_mov_b32_e32 v111, v120
	v_mov_b32_e32 v112, v118
	v_cvt_pk_bf16_f32 v111, v111, v104
	v_or_b32_e32 v104, s64, v141
	s_ashr_i32 s7, s64, 31
	v_cvt_pk_bf16_f32 v110, v112, v110
	v_mul_lo_u32 v112, s29, v104
	s_mul_i32 s7, s28, s7
	v_mad_u64_u32 v[126:127], s[34:35], s28, v104, 0
	v_add3_u32 v127, v127, s7, v112
	v_lshl_add_u64 v[126:127], v[126:127], 1, s[26:27]
	s_lshl_b64 s[30:31], s[30:31], 1
	v_lshl_add_u64 v[126:127], v[126:127], 0, s[30:31]
	v_mov_b32_e32 v143, v139
	v_mov_b32_e32 v112, v105
	v_mov_b32_e32 v124, v123
	v_cvt_pk_bf16_f32 v109, v109, v114
	v_cvt_pk_bf16_f32 v108, v108, v116
	v_lshl_add_u64 v[126:127], v[126:127], 0, v[142:143]
	v_pk_mul_f32 v[104:105], v[102:103], v[112:113]
	v_mov_b32_e32 v116, v115
	v_pk_mul_f32 v[112:113], v[106:107], v[124:125]
	global_store_dwordx4 v[126:127], v[108:111], off
	v_mov_b32_e32 v120, v119
	s_nop 0
	v_pk_mul_f32 v[108:109], v[100:101], v[116:117]
	v_pk_mul_f32 v[110:111], v[98:99], v[120:121]
	v_cvt_pk_bf16_f32 v108, v104, v108
	v_or_b32_e32 v104, s64, v146
	v_cvt_pk_bf16_f32 v110, v110, v112
	v_cvt_pk_bf16_f32 v109, v105, v109
	v_mul_lo_u32 v112, s29, v104
	v_mad_u64_u32 v[104:105], s[34:35], s28, v104, 0
	v_add3_u32 v105, v105, s7, v112
	v_lshl_add_u64 v[104:105], v[104:105], 1, s[26:27]
	v_lshl_add_u64 v[104:105], v[104:105], 0, s[30:31]
	v_cvt_pk_bf16_f32 v111, v111, v113
	v_lshl_add_u64 v[104:105], v[104:105], 0, v[142:143]
	ds_read2_b32 v[112:113], v153 offset0:16 offset1:24
	ds_read2_b32 v[114:115], v153 offset0:82 offset1:90
	global_store_dwordx4 v[104:105], v[108:111], off
	ds_read2_b32 v[104:105], v153 offset0:49 offset1:57
	ds_read2_b32 v[116:117], v153 offset0:115 offset1:123
	ds_read2_b32 v[118:119], v153 offset0:148 offset1:156
	ds_read2_b32 v[120:121], v153 offset0:214 offset1:222
	ds_read2_b32 v[122:123], v153 offset0:181 offset1:189
	ds_read2_b32 v[124:125], v153 offset0:247 offset1:255
	s_waitcnt lgkmcnt(7)
	v_mov_b32_e32 v108, v112
	s_waitcnt lgkmcnt(5)
	v_mov_b32_e32 v110, v104
	s_waitcnt lgkmcnt(4)
	v_mov_b32_e32 v111, v116
	s_waitcnt lgkmcnt(3)
	v_mov_b32_e32 v126, v118
	s_waitcnt lgkmcnt(2)
	v_mov_b32_e32 v127, v120
	v_mov_b32_e32 v109, v114
	v_pk_mul_f32 v[110:111], v[100:101], v[110:111]
	v_pk_mul_f32 v[126:127], v[98:99], v[126:127]
	s_waitcnt lgkmcnt(1)
	v_mov_b32_e32 v128, v122
	s_waitcnt lgkmcnt(0)
	v_mov_b32_e32 v129, v124
	v_pk_mul_f32 v[108:109], v[102:103], v[108:109]
	v_pk_mul_f32 v[128:129], v[106:107], v[128:129]
	v_bfe_u32 v112, v128, 16, 1
	v_mov_b32_e32 v114, v111
	v_bfe_u32 v118, v126, 16, 1
	v_mov_b32_e32 v120, v127
	v_mov_b32_e32 v116, v110
	v_add3_u32 v110, v128, v112, s62
	v_mov_b32_e32 v104, v129
	v_add3_u32 v118, v126, v118, s62
	v_mov_b32_e32 v111, v120
	v_lshrrev_b32_e32 v112, 16, v118
	v_cvt_pk_bf16_f32 v111, v111, v104
	v_or_b32_e32 v104, s64, v147
	v_and_or_b32 v110, v110, s63, v112
	v_mul_lo_u32 v112, s29, v104
	v_mad_u64_u32 v[126:127], s[34:35], s28, v104, 0
	v_add3_u32 v127, v127, s7, v112
	v_lshl_add_u64 v[126:127], v[126:127], 1, s[26:27]
	v_cvt_pk_bf16_f32 v108, v108, v116
	v_lshl_add_u64 v[126:127], v[126:127], 0, s[30:31]
	v_mov_b32_e32 v116, v105
	v_mov_b32_e32 v124, v123
	v_cvt_pk_bf16_f32 v109, v109, v114
	v_lshl_add_u64 v[126:127], v[126:127], 0, v[142:143]
	v_mov_b32_e32 v114, v113
	v_pk_mul_f32 v[100:101], v[100:101], v[116:117]
	v_mov_b32_e32 v120, v119
	v_pk_mul_f32 v[104:105], v[106:107], v[124:125]
	global_store_dwordx4 v[126:127], v[108:111], off
	v_pk_mul_f32 v[102:103], v[102:103], v[114:115]
	v_pk_mul_f32 v[98:99], v[98:99], v[120:121]
	v_bfe_u32 v106, v105, 16, 1
	v_bfe_u32 v107, v104, 16, 1
	v_bfe_u32 v108, v101, 16, 1
	v_bfe_u32 v109, v100, 16, 1
	v_add3_u32 v109, v100, v109, s62
	v_add3_u32 v108, v101, v108, s62
	v_add3_u32 v100, v104, v107, s62
	v_add3_u32 v101, v105, v106, s62
	v_bfe_u32 v104, v102, 16, 1
	v_bfe_u32 v106, v98, 16, 1
	v_bfe_u32 v105, v103, 16, 1
	v_bfe_u32 v107, v99, 16, 1
	v_add3_u32 v98, v98, v106, s62
	v_add3_u32 v102, v102, v104, s62
	v_add3_u32 v99, v99, v107, s62
	v_add3_u32 v103, v103, v105, s62
	v_lshrrev_b32_e32 v102, 16, v102
	v_lshrrev_b32_e32 v98, 16, v98
	v_lshrrev_b32_e32 v103, 16, v103
	v_lshrrev_b32_e32 v99, 16, v99
	v_and_or_b32 v100, v100, s63, v98
	v_and_or_b32 v98, v109, s63, v102
	v_or_b32_e32 v102, s64, v148
	v_and_or_b32 v101, v101, s63, v99
	v_and_or_b32 v99, v108, s63, v103
	v_mul_lo_u32 v104, s29, v102
	v_mad_u64_u32 v[102:103], s[28:29], s28, v102, 0
	v_add3_u32 v103, v103, s7, v104
	v_lshl_add_u64 v[102:103], v[102:103], 1, s[26:27]
	v_lshl_add_u64 v[102:103], v[102:103], 0, s[30:31]
	v_lshl_add_u64 v[102:103], v[102:103], 0, v[142:143]
	global_store_dwordx4 v[102:103], v[98:101], off
	s_waitcnt lgkmcnt(0)
	s_add_i32 s3, s3, s47
	s_cmp_lt_i32 s3, 0x2ec80
	s_cselect_b64 s[36:37], -1, 0

.LBB0_2486:
	ds_read2_b32 v[136:137], v153 offset1:8
	ds_read2_b32 v[180:181], v153 offset0:66 offset1:74
	ds_read2_b32 v[182:183], v153 offset0:33 offset1:41
	ds_read2_b32 v[184:185], v153 offset0:99 offset1:107
	ds_read2_b32 v[186:187], v153 offset0:132 offset1:140
	ds_read2_b32 v[188:189], v153 offset0:198 offset1:206
	ds_read2_b32 v[190:191], v153 offset0:165 offset1:173
	ds_read2_b32 v[192:193], v153 offset0:231 offset1:239
	s_waitcnt lgkmcnt(7)
	v_mov_b32_e32 v176, v136
	s_waitcnt lgkmcnt(5)
	v_mov_b32_e32 v178, v182
	s_waitcnt lgkmcnt(4)
	v_mov_b32_e32 v179, v184
	s_waitcnt lgkmcnt(3)
	v_mov_b32_e32 v194, v186
	s_waitcnt lgkmcnt(2)
	v_mov_b32_e32 v195, v188
	v_mov_b32_e32 v177, v180
	v_pk_mul_f32 v[178:179], v[132:133], v[178:179]
	v_pk_mul_f32 v[194:195], v[130:131], v[194:195]
	s_waitcnt lgkmcnt(1)
	v_mov_b32_e32 v196, v190
	s_waitcnt lgkmcnt(0)
	v_mov_b32_e32 v197, v192
	v_pk_mul_f32 v[176:177], v[134:135], v[176:177]
	v_pk_mul_f32 v[196:197], v[144:145], v[196:197]
	v_mov_b32_e32 v174, v179
	v_mov_b32_e32 v184, v195
	v_mov_b32_e32 v136, v197
	v_mov_b32_e32 v179, v184
	v_mov_b32_e32 v180, v178
	v_mov_b32_e32 v182, v194
	v_cvt_pk_bf16_f32 v179, v179, v136
	v_add_u32_e32 v136, s33, v141
	v_mov_b32_e32 v143, v196
	v_mov_b32_e32 v178, v182
	v_mad_u64_u32 v[194:195], s[36:37], v136, s46, 0
	v_cvt_pk_bf16_f32 v178, v178, v143
	v_ashrrev_i32_e32 v143, 31, v136
	v_mov_b32_e32 v136, v195
	v_mad_u64_u32 v[196:197], s[36:37], v143, s46, v[136:137]
	v_mov_b32_e32 v195, v196
	v_lshl_add_u64 v[194:195], v[194:195], 1, s[10:11]
	s_lshl_b64 s[36:37], s[6:7], 1
	v_cvt_pk_bf16_f32 v176, v176, v180
	v_lshl_add_u64 v[194:195], v[194:195], 0, s[36:37]
	v_mov_b32_e32 v143, v139
	v_mov_b32_e32 v180, v137
	v_mov_b32_e32 v192, v191
	v_cvt_pk_bf16_f32 v177, v177, v174
	v_lshl_add_u64 v[194:195], v[194:195], 0, v[142:143]
	v_pk_mul_f32 v[136:137], v[134:135], v[180:181]
	v_mov_b32_e32 v184, v183
	v_pk_mul_f32 v[180:181], v[144:145], v[192:193]
	global_store_dwordx4 v[194:195], v[176:179], off
	v_mov_b32_e32 v188, v187
	s_nop 0
	v_pk_mul_f32 v[176:177], v[132:133], v[184:185]
	v_pk_mul_f32 v[178:179], v[130:131], v[188:189]
	v_mov_b32_e32 v174, v181
	v_cvt_pk_bf16_f32 v176, v136, v176
	v_add_u32_e32 v136, s33, v146
	v_cvt_pk_bf16_f32 v178, v178, v180
	v_cvt_pk_bf16_f32 v177, v137, v177
	v_ashrrev_i32_e32 v180, 31, v136
	v_mad_u64_u32 v[136:137], s[38:39], v136, s46, 0
	v_cvt_pk_bf16_f32 v179, v179, v174
	v_mov_b32_e32 v174, v137
	v_mad_u64_u32 v[180:181], s[38:39], v180, s46, v[174:175]
	v_mov_b32_e32 v137, v180
	v_lshl_add_u64 v[136:137], v[136:137], 1, s[10:11]
	v_lshl_add_u64 v[136:137], v[136:137], 0, s[36:37]
	v_lshl_add_u64 v[136:137], v[136:137], 0, v[142:143]
	ds_read2_b32 v[180:181], v153 offset0:16 offset1:24
	ds_read2_b32 v[182:183], v153 offset0:82 offset1:90
	global_store_dwordx4 v[136:137], v[176:179], off
	ds_read2_b32 v[136:137], v153 offset0:49 offset1:57
	ds_read2_b32 v[184:185], v153 offset0:115 offset1:123
	ds_read2_b32 v[186:187], v153 offset0:148 offset1:156
	ds_read2_b32 v[188:189], v153 offset0:214 offset1:222
	ds_read2_b32 v[190:191], v153 offset0:181 offset1:189
	ds_read2_b32 v[192:193], v153 offset0:247 offset1:255
	s_waitcnt lgkmcnt(7)
	v_mov_b32_e32 v176, v180
	s_waitcnt lgkmcnt(5)
	v_mov_b32_e32 v178, v136
	s_waitcnt lgkmcnt(4)
	v_mov_b32_e32 v179, v184
	s_waitcnt lgkmcnt(3)
	v_mov_b32_e32 v194, v186
	s_waitcnt lgkmcnt(2)
	v_mov_b32_e32 v195, v188
	v_mov_b32_e32 v177, v182
	v_pk_mul_f32 v[178:179], v[132:133], v[178:179]
	v_pk_mul_f32 v[194:195], v[130:131], v[194:195]
	s_waitcnt lgkmcnt(1)
	v_mov_b32_e32 v196, v190
	s_waitcnt lgkmcnt(0)
	v_mov_b32_e32 v197, v192
	v_pk_mul_f32 v[176:177], v[134:135], v[176:177]
	v_pk_mul_f32 v[196:197], v[144:145], v[196:197]
	v_bfe_u32 v180, v179, 16, 1
	v_bfe_u32 v186, v195, 16, 1
	v_bfe_u32 v136, v197, 16, 1
	v_add3_u32 v180, v179, v180, s62
	v_bfe_u32 v179, v177, 16, 1
	v_add3_u32 v186, v195, v186, s62
	v_add3_u32 v136, v197, v136, s62
	v_add3_u32 v177, v177, v179, s62
	v_lshrrev_b32_e32 v179, 16, v186
	v_mov_b32_e32 v182, v178
	v_mov_b32_e32 v184, v194
	v_and_or_b32 v179, v136, s63, v179
	v_add_u32_e32 v136, s33, v147
	v_mov_b32_e32 v174, v196
	v_mov_b32_e32 v178, v184
	v_mad_u64_u32 v[194:195], s[38:39], v136, s46, 0
	v_cvt_pk_bf16_f32 v178, v178, v174
	v_ashrrev_i32_e32 v174, 31, v136
	v_mov_b32_e32 v136, v195
	v_mad_u64_u32 v[196:197], s[38:39], v174, s46, v[136:137]
	v_mov_b32_e32 v195, v196
	v_lshl_add_u64 v[194:195], v[194:195], 1, s[10:11]
	v_lshrrev_b32_e32 v177, 16, v177
	v_lshl_add_u64 v[194:195], v[194:195], 0, s[36:37]
	v_mov_b32_e32 v184, v137
	v_mov_b32_e32 v192, v191
	v_and_or_b32 v177, v180, s63, v177
	v_cvt_pk_bf16_f32 v176, v176, v182
	v_lshl_add_u64 v[194:195], v[194:195], 0, v[142:143]
	v_mov_b32_e32 v182, v181
	v_pk_mul_f32 v[132:133], v[132:133], v[184:185]
	v_mov_b32_e32 v188, v187
	v_pk_mul_f32 v[136:137], v[144:145], v[192:193]
	global_store_dwordx4 v[194:195], v[176:179], off
	v_pk_mul_f32 v[134:135], v[134:135], v[182:183]
	v_pk_mul_f32 v[130:131], v[130:131], v[188:189]
	v_bfe_u32 v144, v137, 16, 1
	v_bfe_u32 v145, v136, 16, 1
	v_bfe_u32 v174, v133, 16, 1
	v_bfe_u32 v176, v132, 16, 1
	v_add3_u32 v176, v132, v176, s62
	v_add3_u32 v174, v133, v174, s62
	v_add3_u32 v132, v136, v145, s62
	v_add3_u32 v133, v137, v144, s62
	v_bfe_u32 v136, v134, 16, 1
	v_bfe_u32 v144, v130, 16, 1
	v_bfe_u32 v137, v135, 16, 1
	v_bfe_u32 v145, v131, 16, 1
	v_add3_u32 v130, v130, v144, s62
	v_add3_u32 v134, v134, v136, s62
	v_add3_u32 v131, v131, v145, s62
	v_add3_u32 v135, v135, v137, s62
	v_lshrrev_b32_e32 v134, 16, v134
	v_lshrrev_b32_e32 v130, 16, v130
	v_lshrrev_b32_e32 v135, 16, v135
	v_lshrrev_b32_e32 v131, 16, v131
	v_and_or_b32 v132, v132, s63, v130
	v_and_or_b32 v130, v176, s63, v134
	v_add_u32_e32 v134, s33, v148
	v_and_or_b32 v133, v133, s63, v131
	v_and_or_b32 v131, v174, s63, v135
	v_ashrrev_i32_e32 v137, 31, v134
	v_mad_u64_u32 v[134:135], s[38:39], v134, s46, 0
	v_mov_b32_e32 v136, v135
	v_mad_u64_u32 v[136:137], s[38:39], v137, s46, v[136:137]
	v_mov_b32_e32 v135, v136
	v_lshl_add_u64 v[134:135], v[134:135], 1, s[10:11]
	v_lshl_add_u64 v[134:135], v[134:135], 0, s[36:37]
	v_lshl_add_u64 v[134:135], v[134:135], 0, v[142:143]
	global_store_dwordx4 v[134:135], v[130:133], off
	s_waitcnt lgkmcnt(0)
	s_add_i32 s3, s3, s47
	s_cmp_lt_i32 s3, 0x2ec80
	s_mov_b64 s[36:37], 0
	s_cbranch_scc0 .LBB0_2463
	s_add_i32 s6, s3, s52
	s_cmp_lt_i32 s6, 0x2ec80
	s_cselect_b32 s7, s6, s3
	s_cmp_lt_i32 s7, 0x8080
	s_cbranch_scc1 .LBB0_2501
	s_cmpk_lt_u32 s7, 0xa080
	s_cbranch_scc1 .LBB0_2502
	s_cmp_lt_u32 s7, 0x14c80
	s_cselect_b64 s[8:9], -1, 0
	s_add_i32 s6, s7, 0xfffe1580
	s_cmpk_lt_u32 s6, 0xac00
	s_cselect_b64 s[10:11], -1, 0
	s_or_b64 s[8:9], s[8:9], s[10:11]
	s_mov_b64 s[42:43], -1
	s_and_b64 vcc, exec, s[8:9]
	s_cbranch_vccnz .LBB0_2498
	s_add_i32 s6, s7, 0xfffd6980
	s_cmp_lt_u32 s6, 0xffff0c00
	s_mov_b64 s[44:45], -1
	s_cbranch_scc1 .LBB0_2495
	s_cmp_lt_u32 s7, 0x1ca80
	s_mov_b64 s[8:9], -1
	s_cbranch_scc1 .LBB0_2493
	s_add_i32 s6, s7, 0xfffe3580
	v_readlane_b32 s68, v250, 18
	s_lshl_b32 s8, s7, 5
	s_lshr_b32 s6, s6, 1
	v_readlane_b32 s76, v250, 26
	v_readlane_b32 s77, v250, 27
	s_and_b32 s33, s8, 0xfe0
	s_and_b32 s6, s6, 0x7fffffc0
	s_mov_b64 s[8:9], 0
	s_mov_b64 s[36:37], s[76:77]
	v_readlane_b32 s69, v250, 19
	v_readlane_b32 s70, v250, 20
	v_readlane_b32 s71, v250, 21
	v_readlane_b32 s72, v250, 22
	v_readlane_b32 s73, v250, 23
	v_readlane_b32 s74, v250, 24
	v_readlane_b32 s75, v250, 25
	v_readlane_b32 s78, v250, 28
	v_readlane_b32 s79, v250, 29
	v_readlane_b32 s80, v250, 30
	v_readlane_b32 s81, v250, 31
	v_readlane_b32 s82, v250, 32
	v_readlane_b32 s83, v250, 33

.LBB0_2509:
	ds_read2_b32 v[136:137], v153 offset1:8
	ds_read2_b32 v[180:181], v153 offset0:66 offset1:74
	ds_read2_b32 v[182:183], v153 offset0:33 offset1:41
	ds_read2_b32 v[184:185], v153 offset0:99 offset1:107
	ds_read2_b32 v[186:187], v153 offset0:132 offset1:140
	ds_read2_b32 v[188:189], v153 offset0:198 offset1:206
	ds_read2_b32 v[190:191], v153 offset0:165 offset1:173
	ds_read2_b32 v[192:193], v153 offset0:231 offset1:239
	s_waitcnt lgkmcnt(7)
	v_mov_b32_e32 v176, v136
	s_waitcnt lgkmcnt(5)
	v_mov_b32_e32 v178, v182
	s_waitcnt lgkmcnt(4)
	v_mov_b32_e32 v179, v184
	s_waitcnt lgkmcnt(3)
	v_mov_b32_e32 v194, v186
	s_waitcnt lgkmcnt(2)
	v_mov_b32_e32 v195, v188
	v_mov_b32_e32 v177, v180
	v_pk_mul_f32 v[178:179], v[132:133], v[178:179]
	v_pk_mul_f32 v[194:195], v[130:131], v[194:195]
	s_waitcnt lgkmcnt(1)
	v_mov_b32_e32 v196, v190
	s_waitcnt lgkmcnt(0)
	v_mov_b32_e32 v197, v192
	v_pk_mul_f32 v[176:177], v[134:135], v[176:177]
	v_pk_mul_f32 v[196:197], v[144:145], v[196:197]
	v_mov_b32_e32 v174, v179
	v_mov_b32_e32 v184, v195
	v_mov_b32_e32 v136, v197
	v_mov_b32_e32 v179, v184
	v_mov_b32_e32 v180, v178
	v_mov_b32_e32 v182, v194
	v_cvt_pk_bf16_f32 v179, v179, v136
	v_add_u32_e32 v136, s48, v141
	v_mov_b32_e32 v143, v196
	v_mov_b32_e32 v178, v182
	v_mad_u64_u32 v[194:195], s[36:37], v136, s49, 0
	v_cvt_pk_bf16_f32 v178, v178, v143
	v_ashrrev_i32_e32 v143, 31, v136
	v_mov_b32_e32 v136, v195
	v_mad_u64_u32 v[196:197], s[36:37], v143, s49, v[136:137]
	v_mov_b32_e32 v195, v196
	v_lshl_add_u64 v[194:195], v[194:195], 1, s[16:17]
	s_lshl_b64 s[36:37], s[12:13], 1
	v_cvt_pk_bf16_f32 v176, v176, v180
	v_lshl_add_u64 v[194:195], v[194:195], 0, s[36:37]
	v_mov_b32_e32 v143, v139
	v_mov_b32_e32 v180, v137
	v_mov_b32_e32 v192, v191
	v_cvt_pk_bf16_f32 v177, v177, v174
	v_lshl_add_u64 v[194:195], v[194:195], 0, v[142:143]
	v_pk_mul_f32 v[136:137], v[134:135], v[180:181]
	v_mov_b32_e32 v184, v183
	v_pk_mul_f32 v[180:181], v[144:145], v[192:193]
	global_store_dwordx4 v[194:195], v[176:179], off
	v_mov_b32_e32 v188, v187
	s_nop 0
	v_pk_mul_f32 v[176:177], v[132:133], v[184:185]
	v_pk_mul_f32 v[178:179], v[130:131], v[188:189]
	v_mov_b32_e32 v174, v181
	v_cvt_pk_bf16_f32 v176, v136, v176
	v_add_u32_e32 v136, s48, v146
	v_cvt_pk_bf16_f32 v178, v178, v180
	v_cvt_pk_bf16_f32 v177, v137, v177
	v_ashrrev_i32_e32 v180, 31, v136
	v_mad_u64_u32 v[136:137], s[38:39], v136, s49, 0
	v_cvt_pk_bf16_f32 v179, v179, v174
	v_mov_b32_e32 v174, v137
	v_mad_u64_u32 v[180:181], s[38:39], v180, s49, v[174:175]
	v_mov_b32_e32 v137, v180
	v_lshl_add_u64 v[136:137], v[136:137], 1, s[16:17]
	v_lshl_add_u64 v[136:137], v[136:137], 0, s[36:37]
	v_lshl_add_u64 v[136:137], v[136:137], 0, v[142:143]
	ds_read2_b32 v[180:181], v153 offset0:16 offset1:24
	ds_read2_b32 v[182:183], v153 offset0:82 offset1:90
	global_store_dwordx4 v[136:137], v[176:179], off
	ds_read2_b32 v[136:137], v153 offset0:49 offset1:57
	ds_read2_b32 v[184:185], v153 offset0:115 offset1:123
	ds_read2_b32 v[186:187], v153 offset0:148 offset1:156
	ds_read2_b32 v[188:189], v153 offset0:214 offset1:222
	ds_read2_b32 v[190:191], v153 offset0:181 offset1:189
	ds_read2_b32 v[192:193], v153 offset0:247 offset1:255
	s_waitcnt lgkmcnt(7)
	v_mov_b32_e32 v176, v180
	s_waitcnt lgkmcnt(5)
	v_mov_b32_e32 v178, v136
	s_waitcnt lgkmcnt(4)
	v_mov_b32_e32 v179, v184
	s_waitcnt lgkmcnt(3)
	v_mov_b32_e32 v194, v186
	s_waitcnt lgkmcnt(2)
	v_mov_b32_e32 v195, v188
	v_mov_b32_e32 v177, v182
	v_pk_mul_f32 v[178:179], v[132:133], v[178:179]
	v_pk_mul_f32 v[194:195], v[130:131], v[194:195]
	s_waitcnt lgkmcnt(1)
	v_mov_b32_e32 v196, v190
	s_waitcnt lgkmcnt(0)
	v_mov_b32_e32 v197, v192
	v_pk_mul_f32 v[176:177], v[134:135], v[176:177]
	v_pk_mul_f32 v[196:197], v[144:145], v[196:197]
	v_bfe_u32 v180, v179, 16, 1
	v_bfe_u32 v186, v195, 16, 1
	v_bfe_u32 v136, v197, 16, 1
	v_add3_u32 v180, v179, v180, s62
	v_bfe_u32 v179, v177, 16, 1
	v_add3_u32 v186, v195, v186, s62
	v_add3_u32 v136, v197, v136, s62
	v_add3_u32 v177, v177, v179, s62
	v_lshrrev_b32_e32 v179, 16, v186
	v_mov_b32_e32 v182, v178
	v_mov_b32_e32 v184, v194
	v_and_or_b32 v179, v136, s63, v179
	v_add_u32_e32 v136, s48, v147
	v_mov_b32_e32 v174, v196
	v_mov_b32_e32 v178, v184
	v_mad_u64_u32 v[194:195], s[38:39], v136, s49, 0
	v_cvt_pk_bf16_f32 v178, v178, v174
	v_ashrrev_i32_e32 v174, 31, v136
	v_mov_b32_e32 v136, v195
	v_mad_u64_u32 v[196:197], s[38:39], v174, s49, v[136:137]
	v_mov_b32_e32 v195, v196
	v_lshl_add_u64 v[194:195], v[194:195], 1, s[16:17]
	v_lshrrev_b32_e32 v177, 16, v177
	v_lshl_add_u64 v[194:195], v[194:195], 0, s[36:37]
	v_mov_b32_e32 v184, v137
	v_mov_b32_e32 v192, v191
	v_and_or_b32 v177, v180, s63, v177
	v_cvt_pk_bf16_f32 v176, v176, v182
	v_lshl_add_u64 v[194:195], v[194:195], 0, v[142:143]
	v_mov_b32_e32 v182, v181
	v_pk_mul_f32 v[132:133], v[132:133], v[184:185]
	v_mov_b32_e32 v188, v187
	v_pk_mul_f32 v[136:137], v[144:145], v[192:193]
	global_store_dwordx4 v[194:195], v[176:179], off
	v_pk_mul_f32 v[134:135], v[134:135], v[182:183]
	v_pk_mul_f32 v[130:131], v[130:131], v[188:189]
	v_bfe_u32 v144, v137, 16, 1
	v_bfe_u32 v145, v136, 16, 1
	v_bfe_u32 v174, v133, 16, 1
	v_bfe_u32 v176, v132, 16, 1
	v_add3_u32 v176, v132, v176, s62
	v_add3_u32 v174, v133, v174, s62
	v_add3_u32 v132, v136, v145, s62
	v_add3_u32 v133, v137, v144, s62
	v_bfe_u32 v136, v134, 16, 1
	v_bfe_u32 v144, v130, 16, 1
	v_bfe_u32 v137, v135, 16, 1
	v_bfe_u32 v145, v131, 16, 1
	v_add3_u32 v130, v130, v144, s62
	v_add3_u32 v134, v134, v136, s62
	v_add3_u32 v131, v131, v145, s62
	v_add3_u32 v135, v135, v137, s62
	v_lshrrev_b32_e32 v134, 16, v134
	v_lshrrev_b32_e32 v130, 16, v130
	v_lshrrev_b32_e32 v135, 16, v135
	v_lshrrev_b32_e32 v131, 16, v131
	v_and_or_b32 v132, v132, s63, v130
	v_and_or_b32 v130, v176, s63, v134
	v_add_u32_e32 v134, s48, v148
	v_and_or_b32 v133, v133, s63, v131
	v_and_or_b32 v131, v174, s63, v135
	v_ashrrev_i32_e32 v137, 31, v134
	v_mad_u64_u32 v[134:135], s[38:39], v134, s49, 0
	v_mov_b32_e32 v136, v135
	v_mad_u64_u32 v[136:137], s[38:39], v137, s49, v[136:137]
	v_mov_b32_e32 v135, v136
	v_lshl_add_u64 v[134:135], v[134:135], 1, s[16:17]
	v_lshl_add_u64 v[134:135], v[134:135], 0, s[36:37]
	v_lshl_add_u64 v[134:135], v[134:135], 0, v[142:143]
	global_store_dwordx4 v[134:135], v[130:133], off
	s_waitcnt lgkmcnt(0)
	s_add_i32 s3, s3, s47
	s_cmp_gt_i32 s3, 0x2ec7f
	s_mov_b64 s[36:37], 0
	s_cbranch_scc1 .LBB0_2463
	s_add_i32 s7, s3, s52
	s_cmp_lt_i32 s7, 0x2ec80
	s_cselect_b32 s7, s7, s3
	s_cmp_lt_i32 s7, 0x8080
	s_cbranch_scc1 .LBB0_2524
	s_cmpk_lt_u32 s7, 0xa080
	s_cbranch_scc1 .LBB0_2525
	s_cmp_lt_u32 s7, 0x14c80
	s_cselect_b64 s[12:13], -1, 0
	s_add_i32 s14, s7, 0xfffe1580
	s_cmpk_lt_u32 s14, 0xac00
	s_cselect_b64 s[14:15], -1, 0
	s_or_b64 s[12:13], s[12:13], s[14:15]
	s_mov_b64 s[42:43], -1
	s_and_b64 vcc, exec, s[12:13]
	s_cbranch_vccnz .LBB0_2521
	s_add_i32 s12, s7, 0xfffd6980
	s_cmp_lt_u32 s12, 0xffff0c00
	s_mov_b64 s[44:45], -1
	s_cbranch_scc1 .LBB0_2518
	s_cmp_lt_u32 s7, 0x1ca80
	s_mov_b64 s[14:15], -1
	s_cbranch_scc1 .LBB0_2516
	s_add_i32 s12, s7, 0xfffe3580
	v_readlane_b32 s68, v250, 18
	s_lshl_b32 s13, s7, 5
	s_lshr_b32 s12, s12, 1
	v_readlane_b32 s76, v250, 26
	v_readlane_b32 s77, v250, 27
	s_and_b32 s48, s13, 0xfe0
	s_and_b32 s12, s12, 0x7fffffc0
	s_mov_b64 s[14:15], 0
	s_mov_b64 s[36:37], s[76:77]
	v_readlane_b32 s69, v250, 19
	v_readlane_b32 s70, v250, 20
	v_readlane_b32 s71, v250, 21
	v_readlane_b32 s72, v250, 22
	v_readlane_b32 s73, v250, 23
	v_readlane_b32 s74, v250, 24
	v_readlane_b32 s75, v250, 25
	v_readlane_b32 s78, v250, 28
	v_readlane_b32 s79, v250, 29
	v_readlane_b32 s80, v250, 30
	v_readlane_b32 s81, v250, 31
	v_readlane_b32 s82, v250, 32
	v_readlane_b32 s83, v250, 33

.LBB0_2532:
	ds_read2_b32 v[136:137], v153 offset1:8
	ds_read2_b32 v[180:181], v153 offset0:66 offset1:74
	ds_read2_b32 v[182:183], v153 offset0:33 offset1:41
	ds_read2_b32 v[184:185], v153 offset0:99 offset1:107
	ds_read2_b32 v[186:187], v153 offset0:132 offset1:140
	ds_read2_b32 v[188:189], v153 offset0:198 offset1:206
	ds_read2_b32 v[190:191], v153 offset0:165 offset1:173
	ds_read2_b32 v[192:193], v153 offset0:231 offset1:239
	s_waitcnt lgkmcnt(7)
	v_mov_b32_e32 v176, v136
	s_waitcnt lgkmcnt(5)
	v_mov_b32_e32 v178, v182
	s_waitcnt lgkmcnt(4)
	v_mov_b32_e32 v179, v184
	s_waitcnt lgkmcnt(3)
	v_mov_b32_e32 v194, v186
	s_waitcnt lgkmcnt(2)
	v_mov_b32_e32 v195, v188
	v_mov_b32_e32 v177, v180
	v_pk_mul_f32 v[178:179], v[132:133], v[178:179]
	v_pk_mul_f32 v[194:195], v[130:131], v[194:195]
	s_waitcnt lgkmcnt(1)
	v_mov_b32_e32 v196, v190
	s_waitcnt lgkmcnt(0)
	v_mov_b32_e32 v197, v192
	v_pk_mul_f32 v[176:177], v[134:135], v[176:177]
	v_pk_mul_f32 v[196:197], v[144:145], v[196:197]
	v_mov_b32_e32 v174, v179
	v_mov_b32_e32 v184, v195
	v_mov_b32_e32 v136, v197
	v_mov_b32_e32 v179, v184
	v_mov_b32_e32 v180, v178
	v_mov_b32_e32 v182, v194
	v_cvt_pk_bf16_f32 v179, v179, v136
	v_add_u32_e32 v136, s50, v141
	v_mov_b32_e32 v143, v196
	v_mov_b32_e32 v178, v182
	v_mad_u64_u32 v[194:195], s[36:37], v136, s51, 0
	v_cvt_pk_bf16_f32 v178, v178, v143
	v_ashrrev_i32_e32 v143, 31, v136
	v_mov_b32_e32 v136, v195
	v_mad_u64_u32 v[196:197], s[36:37], v143, s51, v[136:137]
	v_mov_b32_e32 v195, v196
	v_lshl_add_u64 v[194:195], v[194:195], 1, s[22:23]
	s_lshl_b64 s[36:37], s[18:19], 1
	v_cvt_pk_bf16_f32 v176, v176, v180
	v_lshl_add_u64 v[194:195], v[194:195], 0, s[36:37]
	v_mov_b32_e32 v143, v139
	v_mov_b32_e32 v180, v137
	v_mov_b32_e32 v192, v191
	v_cvt_pk_bf16_f32 v177, v177, v174
	v_lshl_add_u64 v[194:195], v[194:195], 0, v[142:143]
	v_pk_mul_f32 v[136:137], v[134:135], v[180:181]
	v_mov_b32_e32 v184, v183
	v_pk_mul_f32 v[180:181], v[144:145], v[192:193]
	global_store_dwordx4 v[194:195], v[176:179], off
	v_mov_b32_e32 v188, v187
	s_nop 0
	v_pk_mul_f32 v[176:177], v[132:133], v[184:185]
	v_pk_mul_f32 v[178:179], v[130:131], v[188:189]
	v_mov_b32_e32 v174, v181
	v_cvt_pk_bf16_f32 v176, v136, v176
	v_add_u32_e32 v136, s50, v146
	v_cvt_pk_bf16_f32 v178, v178, v180
	v_cvt_pk_bf16_f32 v177, v137, v177
	v_ashrrev_i32_e32 v180, 31, v136
	v_mad_u64_u32 v[136:137], s[38:39], v136, s51, 0
	v_cvt_pk_bf16_f32 v179, v179, v174
	v_mov_b32_e32 v174, v137
	v_mad_u64_u32 v[180:181], s[38:39], v180, s51, v[174:175]
	v_mov_b32_e32 v137, v180
	v_lshl_add_u64 v[136:137], v[136:137], 1, s[22:23]
	v_lshl_add_u64 v[136:137], v[136:137], 0, s[36:37]
	v_lshl_add_u64 v[136:137], v[136:137], 0, v[142:143]
	ds_read2_b32 v[180:181], v153 offset0:16 offset1:24
	ds_read2_b32 v[182:183], v153 offset0:82 offset1:90
	global_store_dwordx4 v[136:137], v[176:179], off
	ds_read2_b32 v[136:137], v153 offset0:49 offset1:57
	ds_read2_b32 v[184:185], v153 offset0:115 offset1:123
	ds_read2_b32 v[186:187], v153 offset0:148 offset1:156
	ds_read2_b32 v[188:189], v153 offset0:214 offset1:222
	ds_read2_b32 v[190:191], v153 offset0:181 offset1:189
	ds_read2_b32 v[192:193], v153 offset0:247 offset1:255
	s_waitcnt lgkmcnt(7)
	v_mov_b32_e32 v176, v180
	s_waitcnt lgkmcnt(5)
	v_mov_b32_e32 v178, v136
	s_waitcnt lgkmcnt(4)
	v_mov_b32_e32 v179, v184
	s_waitcnt lgkmcnt(3)
	v_mov_b32_e32 v194, v186
	s_waitcnt lgkmcnt(2)
	v_mov_b32_e32 v195, v188
	v_mov_b32_e32 v177, v182
	v_pk_mul_f32 v[178:179], v[132:133], v[178:179]
	v_pk_mul_f32 v[194:195], v[130:131], v[194:195]
	s_waitcnt lgkmcnt(1)
	v_mov_b32_e32 v196, v190
	s_waitcnt lgkmcnt(0)
	v_mov_b32_e32 v197, v192
	v_pk_mul_f32 v[176:177], v[134:135], v[176:177]
	v_pk_mul_f32 v[196:197], v[144:145], v[196:197]
	v_bfe_u32 v180, v179, 16, 1
	v_bfe_u32 v186, v195, 16, 1
	v_bfe_u32 v136, v197, 16, 1
	v_add3_u32 v180, v179, v180, s62
	v_bfe_u32 v179, v177, 16, 1
	v_add3_u32 v186, v195, v186, s62
	v_add3_u32 v136, v197, v136, s62
	v_add3_u32 v177, v177, v179, s62
	v_lshrrev_b32_e32 v179, 16, v186
	v_mov_b32_e32 v182, v178
	v_mov_b32_e32 v184, v194
	v_and_or_b32 v179, v136, s63, v179
	v_add_u32_e32 v136, s50, v147
	v_mov_b32_e32 v174, v196
	v_mov_b32_e32 v178, v184
	v_mad_u64_u32 v[194:195], s[38:39], v136, s51, 0
	v_cvt_pk_bf16_f32 v178, v178, v174
	v_ashrrev_i32_e32 v174, 31, v136
	v_mov_b32_e32 v136, v195
	v_mad_u64_u32 v[196:197], s[38:39], v174, s51, v[136:137]
	v_mov_b32_e32 v195, v196
	v_lshl_add_u64 v[194:195], v[194:195], 1, s[22:23]
	v_lshrrev_b32_e32 v177, 16, v177
	v_lshl_add_u64 v[194:195], v[194:195], 0, s[36:37]
	v_mov_b32_e32 v184, v137
	v_mov_b32_e32 v192, v191
	v_and_or_b32 v177, v180, s63, v177
	v_cvt_pk_bf16_f32 v176, v176, v182
	v_lshl_add_u64 v[194:195], v[194:195], 0, v[142:143]
	v_mov_b32_e32 v182, v181
	v_pk_mul_f32 v[132:133], v[132:133], v[184:185]
	v_mov_b32_e32 v188, v187
	v_pk_mul_f32 v[136:137], v[144:145], v[192:193]
	global_store_dwordx4 v[194:195], v[176:179], off
	v_pk_mul_f32 v[134:135], v[134:135], v[182:183]
	v_pk_mul_f32 v[130:131], v[130:131], v[188:189]
	v_bfe_u32 v144, v137, 16, 1
	v_bfe_u32 v145, v136, 16, 1
	v_bfe_u32 v174, v133, 16, 1
	v_bfe_u32 v176, v132, 16, 1
	v_add3_u32 v176, v132, v176, s62
	v_add3_u32 v174, v133, v174, s62
	v_add3_u32 v132, v136, v145, s62
	v_add3_u32 v133, v137, v144, s62
	v_bfe_u32 v136, v134, 16, 1
	v_bfe_u32 v144, v130, 16, 1
	v_bfe_u32 v137, v135, 16, 1
	v_bfe_u32 v145, v131, 16, 1
	v_add3_u32 v130, v130, v144, s62
	v_add3_u32 v134, v134, v136, s62
	v_add3_u32 v131, v131, v145, s62
	v_add3_u32 v135, v135, v137, s62
	v_lshrrev_b32_e32 v134, 16, v134
	v_lshrrev_b32_e32 v130, 16, v130
	v_lshrrev_b32_e32 v135, 16, v135
	v_lshrrev_b32_e32 v131, 16, v131
	v_and_or_b32 v132, v132, s63, v130
	v_and_or_b32 v130, v176, s63, v134
	v_add_u32_e32 v134, s50, v148
	v_and_or_b32 v133, v133, s63, v131
	v_and_or_b32 v131, v174, s63, v135
	v_ashrrev_i32_e32 v137, 31, v134
	v_mad_u64_u32 v[134:135], s[38:39], v134, s51, 0
	v_mov_b32_e32 v136, v135
	v_mad_u64_u32 v[136:137], s[38:39], v137, s51, v[136:137]
	v_mov_b32_e32 v135, v136
	v_lshl_add_u64 v[134:135], v[134:135], 1, s[22:23]
	v_lshl_add_u64 v[134:135], v[134:135], 0, s[36:37]
	v_lshl_add_u64 v[134:135], v[134:135], 0, v[142:143]
	global_store_dwordx4 v[134:135], v[130:133], off
	s_waitcnt lgkmcnt(0)
	s_add_i32 s3, s3, s47
	s_cmp_gt_i32 s3, 0x2ec7f
	s_mov_b64 s[36:37], 0
	s_cbranch_scc1 .LBB0_2463
	s_add_i32 s7, s3, s52
	s_cmp_lt_i32 s7, 0x2ec80
	s_cselect_b32 s7, s7, s3
	s_cmp_lt_i32 s7, 0x8080
	s_cbranch_scc1 .LBB0_2547
	s_cmpk_lt_u32 s7, 0xa080
	s_cbranch_scc1 .LBB0_2548
	s_cmp_lt_u32 s7, 0x14c80
	s_cselect_b64 s[18:19], -1, 0
	s_add_i32 s13, s7, 0xfffe1580
	s_cmpk_lt_u32 s13, 0xac00
	s_cselect_b64 s[20:21], -1, 0
	s_or_b64 s[18:19], s[18:19], s[20:21]
	s_mov_b64 s[42:43], -1
	s_and_b64 vcc, exec, s[18:19]
	s_cbranch_vccnz .LBB0_2544
	s_add_i32 s13, s7, 0xfffd6980
	s_cmp_lt_u32 s13, 0xffff0c00
	s_mov_b64 s[44:45], -1
	s_cbranch_scc1 .LBB0_2541
	s_cmp_lt_u32 s7, 0x1ca80
	s_mov_b64 s[20:21], -1
	s_cbranch_scc1 .LBB0_2539
	s_add_i32 s13, s7, 0xfffe3580
	v_readlane_b32 s68, v250, 18
	s_lshl_b32 s18, s7, 5
	s_lshr_b32 s13, s13, 1
	v_readlane_b32 s76, v250, 26
	v_readlane_b32 s77, v250, 27
	s_and_b32 s50, s18, 0xfe0
	s_and_b32 s18, s13, 0x7fffffc0
	s_mov_b64 s[20:21], 0
	s_mov_b64 s[36:37], s[76:77]
	v_readlane_b32 s69, v250, 19
	v_readlane_b32 s70, v250, 20
	v_readlane_b32 s71, v250, 21
	v_readlane_b32 s72, v250, 22
	v_readlane_b32 s73, v250, 23
	v_readlane_b32 s74, v250, 24
	v_readlane_b32 s75, v250, 25
	v_readlane_b32 s78, v250, 28
	v_readlane_b32 s79, v250, 29
	v_readlane_b32 s80, v250, 30
	v_readlane_b32 s81, v250, 31
	v_readlane_b32 s82, v250, 32
	v_readlane_b32 s83, v250, 33
